# back-edge rotation: loop counter / pointer bump / compare moved from after the last MFMA barrier to the end of the last load segment; only the branch remains at the loop bottom
# speedup vs baseline: 1.0024x; 1.0024x over previous
.LBB0_141:
	s_lshl_b32 s34, s11, 8
	s_ashr_i32 s35, s34, 31
	s_lshl_b64 s[34:35], s[34:35], 11
	s_add_u32 s82, s49, s34
	s_addc_u32 s83, s53, s35
	s_and_b64 s[34:35], s[0:1], exec
	s_cselect_b32 s5, s83, s7
	s_cselect_b32 s22, s82, s6
	s_ashr_i32 s81, s80, 31
	s_lshl_b64 s[34:35], s[80:81], 19
	s_add_u32 s84, s55, s34
	s_addc_u32 s85, s57, s35
	s_and_b64 s[34:35], s[0:1], exec
	s_cselect_b32 s34, s85, s9
	s_cselect_b32 s35, s84, s8
	s_add_u32 s40, s8, 0x100
	s_addc_u32 s41, s9, 0
	s_mov_b32 s50, -2
	s_waitcnt vmcnt(0)
	s_waitcnt lgkmcnt(0)
	ds_read_b128 v[128:131], v175
	ds_read_b128 v[132:135], v175 offset:1024
	ds_read_b128 v[136:139], v175 offset:2048
	ds_read_b128 v[140:143], v175 offset:3072
	ds_read_b128 v[166:169], v176
	ds_read_b128 v[170:173], v176 offset:1024
	ds_read_b128 v[182:185], v176 offset:2048
	ds_read_b128 v[186:189], v176 offset:3072
	s_add_u32 s8, s6, 0x100
	s_addc_u32 s9, s7, 0
	s_cmp_eq_u32 s50, 12
	s_cselect_b32 s89, s5, s9
	s_cselect_b32 s88, s22, s8
	s_cselect_b32 s87, s34, s41
	s_cselect_b32 s86, s35, s40
	v_lshl_add_u64 v[220:221], s[6:7], 0, v[158:159]
	s_add_i32 m0, s61, 0xc000
	ds_read_b128 v[190:193], v177
	ds_read_b128 v[194:197], v177 offset:1024
	ds_read_b128 v[198:201], v177 offset:2048
	ds_read_b128 v[202:205], v177 offset:3072
	ds_read_b128 v[206:209], v177 offset:4096
	ds_read_b128 v[210:213], v177 offset:5120
	ds_read_b128 v[214:217], v177 offset:6144
	ds_read_b128 v[224:227], v177 offset:7168
	global_load_lds_dwordx4 v[220:221], off
	s_add_i32 m0, s61, 0xe000
	v_lshl_add_u64 v[220:221], s[6:7], 0, v[160:161]
	global_load_lds_dwordx4 v[220:221], off
	s_setprio 1
	s_waitcnt vmcnt(8) lgkmcnt(0)
	s_barrier
	v_mfma_f32_16x16x32_bf16 v[124:127], v[128:131], v[190:193], 0
	v_mfma_f32_16x16x32_bf16 v[120:123], v[136:139], v[190:193], 0
	v_mfma_f32_16x16x32_bf16 v[108:111], v[128:131], v[198:201], 0
	v_mfma_f32_16x16x32_bf16 v[104:107], v[136:139], v[198:201], 0
	v_mfma_f32_16x16x32_bf16 v[92:95], v[128:131], v[206:209], 0
	v_mfma_f32_16x16x32_bf16 v[88:91], v[136:139], v[206:209], 0
	v_mfma_f32_16x16x32_bf16 v[76:79], v[128:131], v[214:217], 0
	v_mfma_f32_16x16x32_bf16 v[72:75], v[136:139], v[214:217], 0
	v_mfma_f32_16x16x32_bf16 v[124:127], v[132:135], v[194:197], v[124:127]
	v_mfma_f32_16x16x32_bf16 v[120:123], v[140:143], v[194:197], v[120:123]
	v_mfma_f32_16x16x32_bf16 v[108:111], v[132:135], v[202:205], v[108:111]
	v_mfma_f32_16x16x32_bf16 v[104:107], v[140:143], v[202:205], v[104:107]
	v_mfma_f32_16x16x32_bf16 v[92:95], v[132:135], v[210:213], v[92:95]
	v_mfma_f32_16x16x32_bf16 v[88:91], v[140:143], v[210:213], v[88:91]
	v_mfma_f32_16x16x32_bf16 v[76:79], v[132:135], v[224:227], v[76:79]
	v_mfma_f32_16x16x32_bf16 v[72:75], v[140:143], v[224:227], v[72:75]
	v_mfma_f32_16x16x32_bf16 v[116:119], v[166:169], v[190:193], 0
	v_mfma_f32_16x16x32_bf16 v[112:115], v[182:185], v[190:193], 0
	v_mfma_f32_16x16x32_bf16 v[100:103], v[166:169], v[198:201], 0
	v_mfma_f32_16x16x32_bf16 v[96:99], v[182:185], v[198:201], 0
	v_mfma_f32_16x16x32_bf16 v[84:87], v[166:169], v[206:209], 0
	v_mfma_f32_16x16x32_bf16 v[80:83], v[182:185], v[206:209], 0
	v_mfma_f32_16x16x32_bf16 v[68:71], v[166:169], v[214:217], 0
	v_mfma_f32_16x16x32_bf16 v[64:67], v[182:185], v[214:217], 0
	v_mfma_f32_16x16x32_bf16 v[116:119], v[170:173], v[194:197], v[116:119]
	v_mfma_f32_16x16x32_bf16 v[112:115], v[186:189], v[194:197], v[112:115]
	v_mfma_f32_16x16x32_bf16 v[100:103], v[170:173], v[202:205], v[100:103]
	v_mfma_f32_16x16x32_bf16 v[96:99], v[186:189], v[202:205], v[96:99]
	v_mfma_f32_16x16x32_bf16 v[84:87], v[170:173], v[210:213], v[84:87]
	v_mfma_f32_16x16x32_bf16 v[80:83], v[186:189], v[210:213], v[80:83]
	v_mfma_f32_16x16x32_bf16 v[68:71], v[170:173], v[224:227], v[68:71]
	v_mfma_f32_16x16x32_bf16 v[64:67], v[186:189], v[224:227], v[64:67]
	s_barrier
	s_setprio 0
	s_add_i32 s6, s37, s59
	v_lshl_add_u64 v[220:221], s[86:87], 0, v[148:149]
	s_mov_b32 m0, s6
	ds_read_b128 v[190:193], v177 offset:16384
	ds_read_b128 v[194:197], v177 offset:17408
	ds_read_b128 v[198:201], v177 offset:18432
	ds_read_b128 v[202:205], v177 offset:19456
	ds_read_b128 v[206:209], v177 offset:20480
	ds_read_b128 v[210:213], v177 offset:21504
	ds_read_b128 v[214:217], v177 offset:22528
	ds_read_b128 v[224:227], v177 offset:23552
	global_load_lds_dwordx4 v[220:221], off
	s_add_i32 m0, s6, 0x2000
	s_add_u32 s6, s86, 0x40000
	v_lshl_add_u64 v[228:229], s[86:87], 0, v[152:153]
	s_addc_u32 s7, s87, 0
	s_add_i32 s51, s97, s59
	global_load_lds_dwordx4 v[228:229], off
	v_lshl_add_u64 v[230:231], s[6:7], 0, v[148:149]
	s_mov_b32 m0, s51
	v_lshl_add_u64 v[232:233], s[88:89], 0, v[150:151]
	global_load_lds_dwordx4 v[230:231], off
	v_lshl_add_u64 v[230:231], s[6:7], 0, v[152:153]
	s_add_i32 m0, s51, 0x2000
	v_lshl_add_u64 v[234:235], v[232:233], 0, s[68:69]
	global_load_lds_dwordx4 v[230:231], off
	s_mov_b32 m0, s61
	v_lshl_add_u64 v[230:231], s[88:89], 0, v[146:147]
	global_load_lds_dwordx4 v[230:231], off
	s_mov_b32 m0, s63
	s_nop 0
	global_load_lds_dwordx4 v[234:235], off
	s_setprio 1
	s_waitcnt vmcnt(8) lgkmcnt(0)
	s_barrier
	v_mfma_f32_16x16x32_bf16 v[60:63], v[128:131], v[190:193], 0
	v_mfma_f32_16x16x32_bf16 v[56:59], v[136:139], v[190:193], 0
	v_mfma_f32_16x16x32_bf16 v[44:47], v[128:131], v[198:201], 0
	v_mfma_f32_16x16x32_bf16 v[40:43], v[136:139], v[198:201], 0
	v_mfma_f32_16x16x32_bf16 v[28:31], v[128:131], v[206:209], 0
	v_mfma_f32_16x16x32_bf16 v[24:27], v[136:139], v[206:209], 0
	v_mfma_f32_16x16x32_bf16 v[12:15], v[128:131], v[214:217], 0
	v_mfma_f32_16x16x32_bf16 v[8:11], v[136:139], v[214:217], 0
	v_mfma_f32_16x16x32_bf16 v[60:63], v[132:135], v[194:197], v[60:63]
	v_mfma_f32_16x16x32_bf16 v[56:59], v[140:143], v[194:197], v[56:59]
	v_mfma_f32_16x16x32_bf16 v[44:47], v[132:135], v[202:205], v[44:47]
	v_mfma_f32_16x16x32_bf16 v[40:43], v[140:143], v[202:205], v[40:43]
	v_mfma_f32_16x16x32_bf16 v[28:31], v[132:135], v[210:213], v[28:31]
	v_mfma_f32_16x16x32_bf16 v[24:27], v[140:143], v[210:213], v[24:27]
	v_mfma_f32_16x16x32_bf16 v[12:15], v[132:135], v[224:227], v[12:15]
	v_mfma_f32_16x16x32_bf16 v[8:11], v[140:143], v[224:227], v[8:11]
	v_mfma_f32_16x16x32_bf16 v[52:55], v[166:169], v[190:193], 0
	v_mfma_f32_16x16x32_bf16 v[48:51], v[182:185], v[190:193], 0
	v_mfma_f32_16x16x32_bf16 v[36:39], v[166:169], v[198:201], 0
	v_mfma_f32_16x16x32_bf16 v[32:35], v[182:185], v[198:201], 0
	v_mfma_f32_16x16x32_bf16 v[20:23], v[166:169], v[206:209], 0
	v_mfma_f32_16x16x32_bf16 v[16:19], v[182:185], v[206:209], 0
	v_mfma_f32_16x16x32_bf16 v[4:7], v[166:169], v[214:217], 0
	v_mfma_f32_16x16x32_bf16 v[0:3], v[182:185], v[214:217], 0
	v_mfma_f32_16x16x32_bf16 v[52:55], v[170:173], v[194:197], v[52:55]
	v_mfma_f32_16x16x32_bf16 v[48:51], v[186:189], v[194:197], v[48:51]
	v_mfma_f32_16x16x32_bf16 v[36:39], v[170:173], v[202:205], v[36:39]
	v_mfma_f32_16x16x32_bf16 v[32:35], v[186:189], v[202:205], v[32:35]
	v_mfma_f32_16x16x32_bf16 v[20:23], v[170:173], v[210:213], v[20:23]
	v_mfma_f32_16x16x32_bf16 v[16:19], v[186:189], v[210:213], v[16:19]
	v_mfma_f32_16x16x32_bf16 v[4:7], v[170:173], v[224:227], v[4:7]
	v_mfma_f32_16x16x32_bf16 v[0:3], v[186:189], v[224:227], v[0:3]
	s_barrier
	s_setprio 0
	s_add_i32 s6, 0, 0x18000
	s_add_i32 s51, 0, 0x1c000
	v_add_u32_e32 v140, s6, v174
	v_add_u32_e32 v154, s51, v174
	ds_read_b128 v[128:131], v140
	ds_read_b128 v[132:135], v140 offset:1024
	ds_read_b128 v[136:139], v140 offset:2048
	ds_read_b128 v[140:143], v140 offset:3072
	ds_read_b128 v[166:169], v154
	ds_read_b128 v[170:173], v154 offset:1024
	ds_read_b128 v[182:185], v154 offset:2048
	ds_read_b128 v[186:189], v154 offset:3072
	s_mov_b32 m0, s65
	v_lshl_add_u64 v[234:235], v[230:231], 0, s[66:67]
	ds_read_b128 v[190:193], v177 offset:32768
	ds_read_b128 v[194:197], v177 offset:33792
	ds_read_b128 v[198:201], v177 offset:34816
	ds_read_b128 v[202:205], v177 offset:35840
	ds_read_b128 v[206:209], v177 offset:36864
	ds_read_b128 v[210:213], v177 offset:37888
	ds_read_b128 v[214:217], v177 offset:38912
	ds_read_b128 v[224:227], v177 offset:39936
	global_load_lds_dwordx4 v[234:235], off
	s_mov_b32 m0, s77
	v_lshl_add_u64 v[234:235], v[232:233], 0, s[46:47]
	global_load_lds_dwordx4 v[234:235], off
	s_setprio 1
	s_waitcnt vmcnt(8) lgkmcnt(0)
	s_barrier
	v_mfma_f32_16x16x32_bf16 v[124:127], v[128:131], v[190:193], v[124:127]
	v_mfma_f32_16x16x32_bf16 v[120:123], v[136:139], v[190:193], v[120:123]
	v_mfma_f32_16x16x32_bf16 v[108:111], v[128:131], v[198:201], v[108:111]
	v_mfma_f32_16x16x32_bf16 v[104:107], v[136:139], v[198:201], v[104:107]
	v_mfma_f32_16x16x32_bf16 v[92:95], v[128:131], v[206:209], v[92:95]
	v_mfma_f32_16x16x32_bf16 v[88:91], v[136:139], v[206:209], v[88:91]
	v_mfma_f32_16x16x32_bf16 v[76:79], v[128:131], v[214:217], v[76:79]
	v_mfma_f32_16x16x32_bf16 v[72:75], v[136:139], v[214:217], v[72:75]
	v_mfma_f32_16x16x32_bf16 v[124:127], v[132:135], v[194:197], v[124:127]
	v_mfma_f32_16x16x32_bf16 v[120:123], v[140:143], v[194:197], v[120:123]
	v_mfma_f32_16x16x32_bf16 v[108:111], v[132:135], v[202:205], v[108:111]
	v_mfma_f32_16x16x32_bf16 v[104:107], v[140:143], v[202:205], v[104:107]
	v_mfma_f32_16x16x32_bf16 v[92:95], v[132:135], v[210:213], v[92:95]
	v_mfma_f32_16x16x32_bf16 v[88:91], v[140:143], v[210:213], v[88:91]
	v_mfma_f32_16x16x32_bf16 v[76:79], v[132:135], v[224:227], v[76:79]
	v_mfma_f32_16x16x32_bf16 v[72:75], v[140:143], v[224:227], v[72:75]
	v_mfma_f32_16x16x32_bf16 v[116:119], v[166:169], v[190:193], v[116:119]
	v_mfma_f32_16x16x32_bf16 v[112:115], v[182:185], v[190:193], v[112:115]
	v_mfma_f32_16x16x32_bf16 v[100:103], v[166:169], v[198:201], v[100:103]
	v_mfma_f32_16x16x32_bf16 v[96:99], v[182:185], v[198:201], v[96:99]
	v_mfma_f32_16x16x32_bf16 v[84:87], v[166:169], v[206:209], v[84:87]
	v_mfma_f32_16x16x32_bf16 v[80:83], v[182:185], v[206:209], v[80:83]
	v_mfma_f32_16x16x32_bf16 v[68:71], v[166:169], v[214:217], v[68:71]
	v_mfma_f32_16x16x32_bf16 v[64:67], v[182:185], v[214:217], v[64:67]
	v_mfma_f32_16x16x32_bf16 v[116:119], v[170:173], v[194:197], v[116:119]
	v_mfma_f32_16x16x32_bf16 v[112:115], v[186:189], v[194:197], v[112:115]
	v_mfma_f32_16x16x32_bf16 v[100:103], v[170:173], v[202:205], v[100:103]
	v_mfma_f32_16x16x32_bf16 v[96:99], v[186:189], v[202:205], v[96:99]
	v_mfma_f32_16x16x32_bf16 v[84:87], v[170:173], v[210:213], v[84:87]
	v_mfma_f32_16x16x32_bf16 v[80:83], v[186:189], v[210:213], v[80:83]
	v_mfma_f32_16x16x32_bf16 v[68:71], v[170:173], v[224:227], v[68:71]
	v_mfma_f32_16x16x32_bf16 v[64:67], v[186:189], v[224:227], v[64:67]
	s_barrier
	s_setprio 0
	s_add_i32 s6, s6, s59
	v_lshl_add_u64 v[220:221], v[220:221], 0, s[42:43]
	s_mov_b32 m0, s6
	ds_read_b128 v[190:193], v177 offset:49152
	ds_read_b128 v[194:197], v177 offset:50176
	ds_read_b128 v[198:201], v177 offset:51200
	ds_read_b128 v[202:205], v177 offset:52224
	ds_read_b128 v[206:209], v177 offset:53248
	ds_read_b128 v[210:213], v177 offset:54272
	ds_read_b128 v[214:217], v177 offset:55296
	ds_read_b128 v[224:227], v177 offset:56320
	global_load_lds_dwordx4 v[220:221], off
	s_add_i32 m0, s6, 0x2000
	s_add_u32 s6, s86, 0x40080
	v_lshl_add_u64 v[220:221], v[228:229], 0, s[42:43]
	s_addc_u32 s7, s87, 0
	s_add_i32 s51, s51, s59
	global_load_lds_dwordx4 v[220:221], off
	s_mov_b32 m0, s51
	v_lshl_add_u64 v[220:221], s[6:7], 0, v[148:149]
	global_load_lds_dwordx4 v[220:221], off
	s_add_i32 m0, s51, 0x2000
	v_lshl_add_u64 v[220:221], s[6:7], 0, v[152:153]
	global_load_lds_dwordx4 v[220:221], off
	s_mov_b32 m0, s91
	v_lshl_add_u64 v[220:221], v[230:231], 0, s[42:43]
	global_load_lds_dwordx4 v[220:221], off
	s_mov_b32 m0, s92
	v_lshl_add_u64 v[220:221], v[232:233], 0, s[44:45]
	global_load_lds_dwordx4 v[220:221], off
	s_add_i32 s50, s50, 2
	s_add_u32 s40, s40, 0x100
	s_addc_u32 s41, s41, 0
	s_cmp_gt_u32 s50, 13
	s_mov_b64 s[6:7], s[8:9]
	s_setprio 1
	s_waitcnt vmcnt(8) lgkmcnt(0)
	s_barrier
	v_mfma_f32_16x16x32_bf16 v[60:63], v[128:131], v[190:193], v[60:63]
	v_mfma_f32_16x16x32_bf16 v[56:59], v[136:139], v[190:193], v[56:59]
	v_mfma_f32_16x16x32_bf16 v[44:47], v[128:131], v[198:201], v[44:47]
	v_mfma_f32_16x16x32_bf16 v[40:43], v[136:139], v[198:201], v[40:43]
	v_mfma_f32_16x16x32_bf16 v[28:31], v[128:131], v[206:209], v[28:31]
	v_mfma_f32_16x16x32_bf16 v[24:27], v[136:139], v[206:209], v[24:27]
	v_mfma_f32_16x16x32_bf16 v[12:15], v[128:131], v[214:217], v[12:15]
	v_mfma_f32_16x16x32_bf16 v[8:11], v[136:139], v[214:217], v[8:11]
	v_mfma_f32_16x16x32_bf16 v[60:63], v[132:135], v[194:197], v[60:63]
	v_mfma_f32_16x16x32_bf16 v[56:59], v[140:143], v[194:197], v[56:59]
	v_mfma_f32_16x16x32_bf16 v[44:47], v[132:135], v[202:205], v[44:47]
	v_mfma_f32_16x16x32_bf16 v[40:43], v[140:143], v[202:205], v[40:43]
	v_mfma_f32_16x16x32_bf16 v[28:31], v[132:135], v[210:213], v[28:31]
	v_mfma_f32_16x16x32_bf16 v[24:27], v[140:143], v[210:213], v[24:27]
	v_mfma_f32_16x16x32_bf16 v[12:15], v[132:135], v[224:227], v[12:15]
	v_mfma_f32_16x16x32_bf16 v[8:11], v[140:143], v[224:227], v[8:11]
	v_mfma_f32_16x16x32_bf16 v[52:55], v[166:169], v[190:193], v[52:55]
	v_mfma_f32_16x16x32_bf16 v[48:51], v[182:185], v[190:193], v[48:51]
	v_mfma_f32_16x16x32_bf16 v[36:39], v[166:169], v[198:201], v[36:39]
	v_mfma_f32_16x16x32_bf16 v[32:35], v[182:185], v[198:201], v[32:35]
	v_mfma_f32_16x16x32_bf16 v[20:23], v[166:169], v[206:209], v[20:23]
	v_mfma_f32_16x16x32_bf16 v[16:19], v[182:185], v[206:209], v[16:19]
	v_mfma_f32_16x16x32_bf16 v[4:7], v[166:169], v[214:217], v[4:7]
	v_mfma_f32_16x16x32_bf16 v[0:3], v[182:185], v[214:217], v[0:3]
	v_mfma_f32_16x16x32_bf16 v[52:55], v[170:173], v[194:197], v[52:55]
	v_mfma_f32_16x16x32_bf16 v[48:51], v[186:189], v[194:197], v[48:51]
	v_mfma_f32_16x16x32_bf16 v[36:39], v[170:173], v[202:205], v[36:39]
	v_mfma_f32_16x16x32_bf16 v[32:35], v[186:189], v[202:205], v[32:35]
	v_mfma_f32_16x16x32_bf16 v[20:23], v[170:173], v[210:213], v[20:23]
	v_mfma_f32_16x16x32_bf16 v[16:19], v[186:189], v[210:213], v[16:19]
	v_mfma_f32_16x16x32_bf16 v[4:7], v[170:173], v[224:227], v[4:7]
	v_mfma_f32_16x16x32_bf16 v[0:3], v[186:189], v[224:227], v[0:3]
	s_barrier
	s_setprio 0
.LBB0_142:
	ds_read_b128 v[128:131], v175
	ds_read_b128 v[132:135], v175 offset:1024
	ds_read_b128 v[136:139], v175 offset:2048
	ds_read_b128 v[140:143], v175 offset:3072
	ds_read_b128 v[166:169], v176
	ds_read_b128 v[170:173], v176 offset:1024
	ds_read_b128 v[182:185], v176 offset:2048
	ds_read_b128 v[186:189], v176 offset:3072
	s_add_u32 s8, s6, 0x100
	s_addc_u32 s9, s7, 0
	s_cmp_eq_u32 s50, 12
	s_cselect_b32 s89, s5, s9
	s_cselect_b32 s88, s22, s8
	s_cselect_b32 s87, s34, s41
	s_cselect_b32 s86, s35, s40
	v_lshl_add_u64 v[220:221], s[6:7], 0, v[158:159]
	s_add_i32 m0, s61, 0xc000
	ds_read_b128 v[190:193], v177
	ds_read_b128 v[194:197], v177 offset:1024
	ds_read_b128 v[198:201], v177 offset:2048
	ds_read_b128 v[202:205], v177 offset:3072
	ds_read_b128 v[206:209], v177 offset:4096
	ds_read_b128 v[210:213], v177 offset:5120
	ds_read_b128 v[214:217], v177 offset:6144
	ds_read_b128 v[224:227], v177 offset:7168
	global_load_lds_dwordx4 v[220:221], off
	s_add_i32 m0, s61, 0xe000
	v_lshl_add_u64 v[220:221], s[6:7], 0, v[160:161]
	global_load_lds_dwordx4 v[220:221], off
	s_setprio 1
	s_waitcnt vmcnt(8) lgkmcnt(0)
	s_barrier
	v_mfma_f32_16x16x32_bf16 v[124:127], v[128:131], v[190:193], v[124:127]
	v_mfma_f32_16x16x32_bf16 v[120:123], v[136:139], v[190:193], v[120:123]
	v_mfma_f32_16x16x32_bf16 v[108:111], v[128:131], v[198:201], v[108:111]
	v_mfma_f32_16x16x32_bf16 v[104:107], v[136:139], v[198:201], v[104:107]
	v_mfma_f32_16x16x32_bf16 v[92:95], v[128:131], v[206:209], v[92:95]
	v_mfma_f32_16x16x32_bf16 v[88:91], v[136:139], v[206:209], v[88:91]
	v_mfma_f32_16x16x32_bf16 v[76:79], v[128:131], v[214:217], v[76:79]
	v_mfma_f32_16x16x32_bf16 v[72:75], v[136:139], v[214:217], v[72:75]
	v_mfma_f32_16x16x32_bf16 v[124:127], v[132:135], v[194:197], v[124:127]
	v_mfma_f32_16x16x32_bf16 v[120:123], v[140:143], v[194:197], v[120:123]
	v_mfma_f32_16x16x32_bf16 v[108:111], v[132:135], v[202:205], v[108:111]
	v_mfma_f32_16x16x32_bf16 v[104:107], v[140:143], v[202:205], v[104:107]
	v_mfma_f32_16x16x32_bf16 v[92:95], v[132:135], v[210:213], v[92:95]
	v_mfma_f32_16x16x32_bf16 v[88:91], v[140:143], v[210:213], v[88:91]
	v_mfma_f32_16x16x32_bf16 v[76:79], v[132:135], v[224:227], v[76:79]
	v_mfma_f32_16x16x32_bf16 v[72:75], v[140:143], v[224:227], v[72:75]
	v_mfma_f32_16x16x32_bf16 v[116:119], v[166:169], v[190:193], v[116:119]
	v_mfma_f32_16x16x32_bf16 v[112:115], v[182:185], v[190:193], v[112:115]
	v_mfma_f32_16x16x32_bf16 v[100:103], v[166:169], v[198:201], v[100:103]
	v_mfma_f32_16x16x32_bf16 v[96:99], v[182:185], v[198:201], v[96:99]
	v_mfma_f32_16x16x32_bf16 v[84:87], v[166:169], v[206:209], v[84:87]
	v_mfma_f32_16x16x32_bf16 v[80:83], v[182:185], v[206:209], v[80:83]
	v_mfma_f32_16x16x32_bf16 v[68:71], v[166:169], v[214:217], v[68:71]
	v_mfma_f32_16x16x32_bf16 v[64:67], v[182:185], v[214:217], v[64:67]
	v_mfma_f32_16x16x32_bf16 v[116:119], v[170:173], v[194:197], v[116:119]
	v_mfma_f32_16x16x32_bf16 v[112:115], v[186:189], v[194:197], v[112:115]
	v_mfma_f32_16x16x32_bf16 v[100:103], v[170:173], v[202:205], v[100:103]
	v_mfma_f32_16x16x32_bf16 v[96:99], v[186:189], v[202:205], v[96:99]
	v_mfma_f32_16x16x32_bf16 v[84:87], v[170:173], v[210:213], v[84:87]
	v_mfma_f32_16x16x32_bf16 v[80:83], v[186:189], v[210:213], v[80:83]
	v_mfma_f32_16x16x32_bf16 v[68:71], v[170:173], v[224:227], v[68:71]
	v_mfma_f32_16x16x32_bf16 v[64:67], v[186:189], v[224:227], v[64:67]
	s_barrier
	s_setprio 0
	s_add_i32 s6, s37, s59
	v_lshl_add_u64 v[220:221], s[86:87], 0, v[148:149]
	s_mov_b32 m0, s6
	ds_read_b128 v[190:193], v177 offset:16384
	ds_read_b128 v[194:197], v177 offset:17408
	ds_read_b128 v[198:201], v177 offset:18432
	ds_read_b128 v[202:205], v177 offset:19456
	ds_read_b128 v[206:209], v177 offset:20480
	ds_read_b128 v[210:213], v177 offset:21504
	ds_read_b128 v[214:217], v177 offset:22528
	ds_read_b128 v[224:227], v177 offset:23552
	global_load_lds_dwordx4 v[220:221], off
	s_add_i32 m0, s6, 0x2000
	s_add_u32 s6, s86, 0x40000
	v_lshl_add_u64 v[228:229], s[86:87], 0, v[152:153]
	s_addc_u32 s7, s87, 0
	s_add_i32 s51, s97, s59
	global_load_lds_dwordx4 v[228:229], off
	v_lshl_add_u64 v[230:231], s[6:7], 0, v[148:149]
	s_mov_b32 m0, s51
	v_lshl_add_u64 v[232:233], s[88:89], 0, v[150:151]
	global_load_lds_dwordx4 v[230:231], off
	v_lshl_add_u64 v[230:231], s[6:7], 0, v[152:153]
	s_add_i32 m0, s51, 0x2000
	v_lshl_add_u64 v[234:235], v[232:233], 0, s[68:69]
	global_load_lds_dwordx4 v[230:231], off
	s_mov_b32 m0, s61
	v_lshl_add_u64 v[230:231], s[88:89], 0, v[146:147]
	global_load_lds_dwordx4 v[230:231], off
	s_mov_b32 m0, s63
	s_nop 0
	global_load_lds_dwordx4 v[234:235], off
	s_setprio 1
	s_waitcnt vmcnt(8) lgkmcnt(0)
	s_barrier
	v_mfma_f32_16x16x32_bf16 v[60:63], v[128:131], v[190:193], v[60:63]
	v_mfma_f32_16x16x32_bf16 v[56:59], v[136:139], v[190:193], v[56:59]
	v_mfma_f32_16x16x32_bf16 v[44:47], v[128:131], v[198:201], v[44:47]
	v_mfma_f32_16x16x32_bf16 v[40:43], v[136:139], v[198:201], v[40:43]
	v_mfma_f32_16x16x32_bf16 v[28:31], v[128:131], v[206:209], v[28:31]
	v_mfma_f32_16x16x32_bf16 v[24:27], v[136:139], v[206:209], v[24:27]
	v_mfma_f32_16x16x32_bf16 v[12:15], v[128:131], v[214:217], v[12:15]
	v_mfma_f32_16x16x32_bf16 v[8:11], v[136:139], v[214:217], v[8:11]
	v_mfma_f32_16x16x32_bf16 v[60:63], v[132:135], v[194:197], v[60:63]
	v_mfma_f32_16x16x32_bf16 v[56:59], v[140:143], v[194:197], v[56:59]
	v_mfma_f32_16x16x32_bf16 v[44:47], v[132:135], v[202:205], v[44:47]
	v_mfma_f32_16x16x32_bf16 v[40:43], v[140:143], v[202:205], v[40:43]
	v_mfma_f32_16x16x32_bf16 v[28:31], v[132:135], v[210:213], v[28:31]
	v_mfma_f32_16x16x32_bf16 v[24:27], v[140:143], v[210:213], v[24:27]
	v_mfma_f32_16x16x32_bf16 v[12:15], v[132:135], v[224:227], v[12:15]
	v_mfma_f32_16x16x32_bf16 v[8:11], v[140:143], v[224:227], v[8:11]
	v_mfma_f32_16x16x32_bf16 v[52:55], v[166:169], v[190:193], v[52:55]
	v_mfma_f32_16x16x32_bf16 v[48:51], v[182:185], v[190:193], v[48:51]
	v_mfma_f32_16x16x32_bf16 v[36:39], v[166:169], v[198:201], v[36:39]
	v_mfma_f32_16x16x32_bf16 v[32:35], v[182:185], v[198:201], v[32:35]
	v_mfma_f32_16x16x32_bf16 v[20:23], v[166:169], v[206:209], v[20:23]
	v_mfma_f32_16x16x32_bf16 v[16:19], v[182:185], v[206:209], v[16:19]
	v_mfma_f32_16x16x32_bf16 v[4:7], v[166:169], v[214:217], v[4:7]
	v_mfma_f32_16x16x32_bf16 v[0:3], v[182:185], v[214:217], v[0:3]
	v_mfma_f32_16x16x32_bf16 v[52:55], v[170:173], v[194:197], v[52:55]
	v_mfma_f32_16x16x32_bf16 v[48:51], v[186:189], v[194:197], v[48:51]
	v_mfma_f32_16x16x32_bf16 v[36:39], v[170:173], v[202:205], v[36:39]
	v_mfma_f32_16x16x32_bf16 v[32:35], v[186:189], v[202:205], v[32:35]
	v_mfma_f32_16x16x32_bf16 v[20:23], v[170:173], v[210:213], v[20:23]
	v_mfma_f32_16x16x32_bf16 v[16:19], v[186:189], v[210:213], v[16:19]
	v_mfma_f32_16x16x32_bf16 v[4:7], v[170:173], v[224:227], v[4:7]
	v_mfma_f32_16x16x32_bf16 v[0:3], v[186:189], v[224:227], v[0:3]
	s_barrier
	s_setprio 0
	s_add_i32 s6, 0, 0x18000
	s_add_i32 s51, 0, 0x1c000
	v_add_u32_e32 v140, s6, v174
	v_add_u32_e32 v154, s51, v174
	ds_read_b128 v[128:131], v140
	ds_read_b128 v[132:135], v140 offset:1024
	ds_read_b128 v[136:139], v140 offset:2048
	ds_read_b128 v[140:143], v140 offset:3072
	ds_read_b128 v[166:169], v154
	ds_read_b128 v[170:173], v154 offset:1024
	ds_read_b128 v[182:185], v154 offset:2048
	ds_read_b128 v[186:189], v154 offset:3072
	s_mov_b32 m0, s65
	v_lshl_add_u64 v[234:235], v[230:231], 0, s[66:67]
	ds_read_b128 v[190:193], v177 offset:32768
	ds_read_b128 v[194:197], v177 offset:33792
	ds_read_b128 v[198:201], v177 offset:34816
	ds_read_b128 v[202:205], v177 offset:35840
	ds_read_b128 v[206:209], v177 offset:36864
	ds_read_b128 v[210:213], v177 offset:37888
	ds_read_b128 v[214:217], v177 offset:38912
	ds_read_b128 v[224:227], v177 offset:39936
	global_load_lds_dwordx4 v[234:235], off
	s_mov_b32 m0, s77
	v_lshl_add_u64 v[234:235], v[232:233], 0, s[46:47]
	global_load_lds_dwordx4 v[234:235], off
	s_setprio 1
	s_waitcnt vmcnt(8) lgkmcnt(0)
	s_barrier
	v_mfma_f32_16x16x32_bf16 v[124:127], v[128:131], v[190:193], v[124:127]
	v_mfma_f32_16x16x32_bf16 v[120:123], v[136:139], v[190:193], v[120:123]
	v_mfma_f32_16x16x32_bf16 v[108:111], v[128:131], v[198:201], v[108:111]
	v_mfma_f32_16x16x32_bf16 v[104:107], v[136:139], v[198:201], v[104:107]
	v_mfma_f32_16x16x32_bf16 v[92:95], v[128:131], v[206:209], v[92:95]
	v_mfma_f32_16x16x32_bf16 v[88:91], v[136:139], v[206:209], v[88:91]
	v_mfma_f32_16x16x32_bf16 v[76:79], v[128:131], v[214:217], v[76:79]
	v_mfma_f32_16x16x32_bf16 v[72:75], v[136:139], v[214:217], v[72:75]
	v_mfma_f32_16x16x32_bf16 v[124:127], v[132:135], v[194:197], v[124:127]
	v_mfma_f32_16x16x32_bf16 v[120:123], v[140:143], v[194:197], v[120:123]
	v_mfma_f32_16x16x32_bf16 v[108:111], v[132:135], v[202:205], v[108:111]
	v_mfma_f32_16x16x32_bf16 v[104:107], v[140:143], v[202:205], v[104:107]
	v_mfma_f32_16x16x32_bf16 v[92:95], v[132:135], v[210:213], v[92:95]
	v_mfma_f32_16x16x32_bf16 v[88:91], v[140:143], v[210:213], v[88:91]
	v_mfma_f32_16x16x32_bf16 v[76:79], v[132:135], v[224:227], v[76:79]
	v_mfma_f32_16x16x32_bf16 v[72:75], v[140:143], v[224:227], v[72:75]
	v_mfma_f32_16x16x32_bf16 v[116:119], v[166:169], v[190:193], v[116:119]
	v_mfma_f32_16x16x32_bf16 v[112:115], v[182:185], v[190:193], v[112:115]
	v_mfma_f32_16x16x32_bf16 v[100:103], v[166:169], v[198:201], v[100:103]
	v_mfma_f32_16x16x32_bf16 v[96:99], v[182:185], v[198:201], v[96:99]
	v_mfma_f32_16x16x32_bf16 v[84:87], v[166:169], v[206:209], v[84:87]
	v_mfma_f32_16x16x32_bf16 v[80:83], v[182:185], v[206:209], v[80:83]
	v_mfma_f32_16x16x32_bf16 v[68:71], v[166:169], v[214:217], v[68:71]
	v_mfma_f32_16x16x32_bf16 v[64:67], v[182:185], v[214:217], v[64:67]
	v_mfma_f32_16x16x32_bf16 v[116:119], v[170:173], v[194:197], v[116:119]
	v_mfma_f32_16x16x32_bf16 v[112:115], v[186:189], v[194:197], v[112:115]
	v_mfma_f32_16x16x32_bf16 v[100:103], v[170:173], v[202:205], v[100:103]
	v_mfma_f32_16x16x32_bf16 v[96:99], v[186:189], v[202:205], v[96:99]
	v_mfma_f32_16x16x32_bf16 v[84:87], v[170:173], v[210:213], v[84:87]
	v_mfma_f32_16x16x32_bf16 v[80:83], v[186:189], v[210:213], v[80:83]
	v_mfma_f32_16x16x32_bf16 v[68:71], v[170:173], v[224:227], v[68:71]
	v_mfma_f32_16x16x32_bf16 v[64:67], v[186:189], v[224:227], v[64:67]
	s_barrier
	s_setprio 0
	s_add_i32 s6, s6, s59
	v_lshl_add_u64 v[220:221], v[220:221], 0, s[42:43]
	s_mov_b32 m0, s6
	ds_read_b128 v[190:193], v177 offset:49152
	ds_read_b128 v[194:197], v177 offset:50176
	ds_read_b128 v[198:201], v177 offset:51200
	ds_read_b128 v[202:205], v177 offset:52224
	ds_read_b128 v[206:209], v177 offset:53248
	ds_read_b128 v[210:213], v177 offset:54272
	ds_read_b128 v[214:217], v177 offset:55296
	ds_read_b128 v[224:227], v177 offset:56320
	global_load_lds_dwordx4 v[220:221], off
	s_add_i32 m0, s6, 0x2000
	s_add_u32 s6, s86, 0x40080
	v_lshl_add_u64 v[220:221], v[228:229], 0, s[42:43]
	s_addc_u32 s7, s87, 0
	s_add_i32 s51, s51, s59
	global_load_lds_dwordx4 v[220:221], off
	s_mov_b32 m0, s51
	v_lshl_add_u64 v[220:221], s[6:7], 0, v[148:149]
	global_load_lds_dwordx4 v[220:221], off
	s_add_i32 m0, s51, 0x2000
	v_lshl_add_u64 v[220:221], s[6:7], 0, v[152:153]
	global_load_lds_dwordx4 v[220:221], off
	s_mov_b32 m0, s91
	v_lshl_add_u64 v[220:221], v[230:231], 0, s[42:43]
	global_load_lds_dwordx4 v[220:221], off
	s_mov_b32 m0, s92
	v_lshl_add_u64 v[220:221], v[232:233], 0, s[44:45]
	global_load_lds_dwordx4 v[220:221], off
	s_add_i32 s50, s50, 2
	s_add_u32 s40, s40, 0x100
	s_addc_u32 s41, s41, 0
	s_cmp_gt_u32 s50, 13
	s_mov_b64 s[6:7], s[8:9]
	s_setprio 1
	s_waitcnt vmcnt(8) lgkmcnt(0)
	s_barrier
	v_mfma_f32_16x16x32_bf16 v[60:63], v[128:131], v[190:193], v[60:63]
	v_mfma_f32_16x16x32_bf16 v[56:59], v[136:139], v[190:193], v[56:59]
	v_mfma_f32_16x16x32_bf16 v[44:47], v[128:131], v[198:201], v[44:47]
	v_mfma_f32_16x16x32_bf16 v[40:43], v[136:139], v[198:201], v[40:43]
	v_mfma_f32_16x16x32_bf16 v[28:31], v[128:131], v[206:209], v[28:31]
	v_mfma_f32_16x16x32_bf16 v[24:27], v[136:139], v[206:209], v[24:27]
	v_mfma_f32_16x16x32_bf16 v[12:15], v[128:131], v[214:217], v[12:15]
	v_mfma_f32_16x16x32_bf16 v[8:11], v[136:139], v[214:217], v[8:11]
	v_mfma_f32_16x16x32_bf16 v[60:63], v[132:135], v[194:197], v[60:63]
	v_mfma_f32_16x16x32_bf16 v[56:59], v[140:143], v[194:197], v[56:59]
	v_mfma_f32_16x16x32_bf16 v[44:47], v[132:135], v[202:205], v[44:47]
	v_mfma_f32_16x16x32_bf16 v[40:43], v[140:143], v[202:205], v[40:43]
	v_mfma_f32_16x16x32_bf16 v[28:31], v[132:135], v[210:213], v[28:31]
	v_mfma_f32_16x16x32_bf16 v[24:27], v[140:143], v[210:213], v[24:27]
	v_mfma_f32_16x16x32_bf16 v[12:15], v[132:135], v[224:227], v[12:15]
	v_mfma_f32_16x16x32_bf16 v[8:11], v[140:143], v[224:227], v[8:11]
	v_mfma_f32_16x16x32_bf16 v[52:55], v[166:169], v[190:193], v[52:55]
	v_mfma_f32_16x16x32_bf16 v[48:51], v[182:185], v[190:193], v[48:51]
	v_mfma_f32_16x16x32_bf16 v[36:39], v[166:169], v[198:201], v[36:39]
	v_mfma_f32_16x16x32_bf16 v[32:35], v[182:185], v[198:201], v[32:35]
	v_mfma_f32_16x16x32_bf16 v[20:23], v[166:169], v[206:209], v[20:23]
	v_mfma_f32_16x16x32_bf16 v[16:19], v[182:185], v[206:209], v[16:19]
	v_mfma_f32_16x16x32_bf16 v[4:7], v[166:169], v[214:217], v[4:7]
	v_mfma_f32_16x16x32_bf16 v[0:3], v[182:185], v[214:217], v[0:3]
	v_mfma_f32_16x16x32_bf16 v[52:55], v[170:173], v[194:197], v[52:55]
	v_mfma_f32_16x16x32_bf16 v[48:51], v[186:189], v[194:197], v[48:51]
	v_mfma_f32_16x16x32_bf16 v[36:39], v[170:173], v[202:205], v[36:39]
	v_mfma_f32_16x16x32_bf16 v[32:35], v[186:189], v[202:205], v[32:35]
	v_mfma_f32_16x16x32_bf16 v[20:23], v[170:173], v[210:213], v[20:23]
	v_mfma_f32_16x16x32_bf16 v[16:19], v[186:189], v[210:213], v[16:19]
	v_mfma_f32_16x16x32_bf16 v[4:7], v[170:173], v[224:227], v[4:7]
	v_mfma_f32_16x16x32_bf16 v[0:3], v[186:189], v[224:227], v[0:3]
	s_barrier
	s_setprio 0
	s_cbranch_scc0 .LBB0_142
	v_readlane_b32 s6, v249, 60
	v_readlane_b32 s7, v249, 61
	s_and_b64 vcc, exec, s[6:7]
	s_cbranch_vccz .LBB0_145
	s_barrier

.LBB0_392:
	s_lshl_b32 s40, s65, 8
	v_readlane_b32 s72, v249, 0
	s_ashr_i32 s41, s40, 31
	v_readlane_b32 s84, v249, 12
	v_readlane_b32 s85, v249, 13
	s_lshl_b64 s[40:41], s[40:41], 10
	v_readlane_b32 s86, v249, 14
	v_readlane_b32 s87, v249, 15
	s_mov_b64 s[28:29], s[84:85]
	s_add_u32 s40, s28, s40
	s_addc_u32 s41, s29, s41
	s_and_b64 s[42:43], s[0:1], exec
	s_cselect_b32 s67, s41, s45
	s_cselect_b32 s72, s40, s44
	s_ashr_i32 s39, s38, 31
	s_lshl_b64 s[42:43], s[38:39], 18
	s_add_u32 s42, s10, s42
	s_addc_u32 s43, s11, s43
	s_and_b64 s[48:49], s[0:1], exec
	v_readlane_b32 s73, v249, 1
	v_readlane_b32 s74, v249, 2
	s_cselect_b32 s39, s43, s47
	s_cselect_b32 s50, s42, s46
	s_add_u32 s51, s46, 0x100
	s_addc_u32 s73, s47, 0
	s_mov_b32 s74, -2
	s_waitcnt vmcnt(0)
	s_waitcnt lgkmcnt(0)
	v_readlane_b32 s75, v249, 3
	v_readlane_b32 s76, v249, 4
	v_readlane_b32 s77, v249, 5
	v_readlane_b32 s78, v249, 6
	v_readlane_b32 s79, v249, 7
	v_readlane_b32 s80, v249, 8
	v_readlane_b32 s81, v249, 9
	v_readlane_b32 s82, v249, 10
	v_readlane_b32 s83, v249, 11
	s_mov_b64 s[30:31], s[86:87]
	ds_read_b128 v[144:147], v153
	ds_read_b128 v[156:159], v153 offset:1024
	ds_read_b128 v[160:163], v153 offset:2048
	ds_read_b128 v[164:167], v153 offset:3072
	ds_read_b128 v[168:171], v154
	ds_read_b128 v[172:175], v154 offset:1024
	ds_read_b128 v[176:179], v154 offset:2048
	ds_read_b128 v[180:183], v154 offset:3072
	s_add_u32 s46, s44, 0x100
	s_addc_u32 s47, s45, 0
	s_cmp_eq_u32 s74, 4
	s_cselect_b32 s77, s67, s47
	s_cselect_b32 s76, s72, s46
	s_cselect_b32 s49, s39, s73
	s_cselect_b32 s48, s50, s51
	v_lshl_add_u64 v[148:149], s[44:45], 0, v[136:137]
	s_add_i32 m0, s52, 0xc000
	ds_read_b128 v[184:187], v155
	ds_read_b128 v[188:191], v155 offset:1024
	ds_read_b128 v[192:195], v155 offset:2048
	ds_read_b128 v[196:199], v155 offset:3072
	ds_read_b128 v[200:203], v155 offset:4096
	ds_read_b128 v[204:207], v155 offset:5120
	ds_read_b128 v[208:211], v155 offset:6144
	ds_read_b128 v[212:215], v155 offset:7168
	global_load_lds_dwordx4 v[148:149], off
	s_add_i32 m0, s52, 0xe000
	v_lshl_add_u64 v[148:149], s[44:45], 0, v[138:139]
	global_load_lds_dwordx4 v[148:149], off
	s_setprio 1
	s_waitcnt vmcnt(8) lgkmcnt(0)
	s_barrier
	v_mfma_f32_16x16x32_bf16 v[124:127], v[144:147], v[184:187], 0
	v_mfma_f32_16x16x32_bf16 v[120:123], v[160:163], v[184:187], 0
	v_mfma_f32_16x16x32_bf16 v[108:111], v[144:147], v[192:195], 0
	v_mfma_f32_16x16x32_bf16 v[104:107], v[160:163], v[192:195], 0
	v_mfma_f32_16x16x32_bf16 v[92:95], v[144:147], v[200:203], 0
	v_mfma_f32_16x16x32_bf16 v[88:91], v[160:163], v[200:203], 0
	v_mfma_f32_16x16x32_bf16 v[76:79], v[144:147], v[208:211], 0
	v_mfma_f32_16x16x32_bf16 v[72:75], v[160:163], v[208:211], 0
	v_mfma_f32_16x16x32_bf16 v[124:127], v[156:159], v[188:191], v[124:127]
	v_mfma_f32_16x16x32_bf16 v[120:123], v[164:167], v[188:191], v[120:123]
	v_mfma_f32_16x16x32_bf16 v[108:111], v[156:159], v[196:199], v[108:111]
	v_mfma_f32_16x16x32_bf16 v[104:107], v[164:167], v[196:199], v[104:107]
	v_mfma_f32_16x16x32_bf16 v[92:95], v[156:159], v[204:207], v[92:95]
	v_mfma_f32_16x16x32_bf16 v[88:91], v[164:167], v[204:207], v[88:91]
	v_mfma_f32_16x16x32_bf16 v[76:79], v[156:159], v[212:215], v[76:79]
	v_mfma_f32_16x16x32_bf16 v[72:75], v[164:167], v[212:215], v[72:75]
	v_mfma_f32_16x16x32_bf16 v[116:119], v[168:171], v[184:187], 0
	v_mfma_f32_16x16x32_bf16 v[112:115], v[176:179], v[184:187], 0
	v_mfma_f32_16x16x32_bf16 v[100:103], v[168:171], v[192:195], 0
	v_mfma_f32_16x16x32_bf16 v[96:99], v[176:179], v[192:195], 0
	v_mfma_f32_16x16x32_bf16 v[84:87], v[168:171], v[200:203], 0
	v_mfma_f32_16x16x32_bf16 v[80:83], v[176:179], v[200:203], 0
	v_mfma_f32_16x16x32_bf16 v[68:71], v[168:171], v[208:211], 0
	v_mfma_f32_16x16x32_bf16 v[64:67], v[176:179], v[208:211], 0
	v_mfma_f32_16x16x32_bf16 v[116:119], v[172:175], v[188:191], v[116:119]
	v_mfma_f32_16x16x32_bf16 v[112:115], v[180:183], v[188:191], v[112:115]
	v_mfma_f32_16x16x32_bf16 v[100:103], v[172:175], v[196:199], v[100:103]
	v_mfma_f32_16x16x32_bf16 v[96:99], v[180:183], v[196:199], v[96:99]
	v_mfma_f32_16x16x32_bf16 v[84:87], v[172:175], v[204:207], v[84:87]
	v_mfma_f32_16x16x32_bf16 v[80:83], v[180:183], v[204:207], v[80:83]
	v_mfma_f32_16x16x32_bf16 v[68:71], v[172:175], v[212:215], v[68:71]
	v_mfma_f32_16x16x32_bf16 v[64:67], v[180:183], v[212:215], v[64:67]
	s_barrier
	s_setprio 0
	s_add_i32 s44, s61, s33
	v_lshl_add_u64 v[148:149], s[48:49], 0, v[132:133]
	s_mov_b32 m0, s44
	ds_read_b128 v[184:187], v155 offset:16384
	ds_read_b128 v[188:191], v155 offset:17408
	ds_read_b128 v[192:195], v155 offset:18432
	ds_read_b128 v[196:199], v155 offset:19456
	ds_read_b128 v[200:203], v155 offset:20480
	ds_read_b128 v[204:207], v155 offset:21504
	ds_read_b128 v[208:211], v155 offset:22528
	ds_read_b128 v[212:215], v155 offset:23552
	global_load_lds_dwordx4 v[148:149], off
	s_add_i32 m0, s44, 0x2000
	s_add_u32 s44, s48, 0x20000
	v_lshl_add_u64 v[216:217], s[48:49], 0, v[128:129]
	s_addc_u32 s45, s49, 0
	s_add_i32 s68, s62, s33
	global_load_lds_dwordx4 v[216:217], off
	v_lshl_add_u64 v[220:221], s[44:45], 0, v[132:133]
	s_mov_b32 m0, s68
	v_lshl_add_u64 v[224:225], s[76:77], 0, v[130:131]
	global_load_lds_dwordx4 v[220:221], off
	v_lshl_add_u64 v[220:221], s[44:45], 0, v[128:129]
	s_add_i32 m0, s68, 0x2000
	v_lshl_add_u64 v[226:227], v[224:225], 0, s[8:9]
	global_load_lds_dwordx4 v[220:221], off
	s_mov_b32 m0, s52
	v_lshl_add_u64 v[220:221], s[76:77], 0, v[134:135]
	global_load_lds_dwordx4 v[220:221], off
	s_mov_b32 m0, s53
	s_nop 0
	global_load_lds_dwordx4 v[226:227], off
	s_setprio 1
	s_waitcnt vmcnt(8) lgkmcnt(0)
	s_barrier
	v_mfma_f32_16x16x32_bf16 v[60:63], v[144:147], v[184:187], 0
	v_mfma_f32_16x16x32_bf16 v[56:59], v[160:163], v[184:187], 0
	v_mfma_f32_16x16x32_bf16 v[44:47], v[144:147], v[192:195], 0
	v_mfma_f32_16x16x32_bf16 v[40:43], v[160:163], v[192:195], 0
	v_mfma_f32_16x16x32_bf16 v[28:31], v[144:147], v[200:203], 0
	v_mfma_f32_16x16x32_bf16 v[24:27], v[160:163], v[200:203], 0
	v_mfma_f32_16x16x32_bf16 v[12:15], v[144:147], v[208:211], 0
	v_mfma_f32_16x16x32_bf16 v[8:11], v[160:163], v[208:211], 0
	v_mfma_f32_16x16x32_bf16 v[60:63], v[156:159], v[188:191], v[60:63]
	v_mfma_f32_16x16x32_bf16 v[56:59], v[164:167], v[188:191], v[56:59]
	v_mfma_f32_16x16x32_bf16 v[44:47], v[156:159], v[196:199], v[44:47]
	v_mfma_f32_16x16x32_bf16 v[40:43], v[164:167], v[196:199], v[40:43]
	v_mfma_f32_16x16x32_bf16 v[28:31], v[156:159], v[204:207], v[28:31]
	v_mfma_f32_16x16x32_bf16 v[24:27], v[164:167], v[204:207], v[24:27]
	v_mfma_f32_16x16x32_bf16 v[12:15], v[156:159], v[212:215], v[12:15]
	v_mfma_f32_16x16x32_bf16 v[8:11], v[164:167], v[212:215], v[8:11]
	v_mfma_f32_16x16x32_bf16 v[52:55], v[168:171], v[184:187], 0
	v_mfma_f32_16x16x32_bf16 v[48:51], v[176:179], v[184:187], 0
	v_mfma_f32_16x16x32_bf16 v[36:39], v[168:171], v[192:195], 0
	v_mfma_f32_16x16x32_bf16 v[32:35], v[176:179], v[192:195], 0
	v_mfma_f32_16x16x32_bf16 v[20:23], v[168:171], v[200:203], 0
	v_mfma_f32_16x16x32_bf16 v[16:19], v[176:179], v[200:203], 0
	v_mfma_f32_16x16x32_bf16 v[4:7], v[168:171], v[208:211], 0
	v_mfma_f32_16x16x32_bf16 v[0:3], v[176:179], v[208:211], 0
	v_mfma_f32_16x16x32_bf16 v[52:55], v[172:175], v[188:191], v[52:55]
	v_mfma_f32_16x16x32_bf16 v[48:51], v[180:183], v[188:191], v[48:51]
	v_mfma_f32_16x16x32_bf16 v[36:39], v[172:175], v[196:199], v[36:39]
	v_mfma_f32_16x16x32_bf16 v[32:35], v[180:183], v[196:199], v[32:35]
	v_mfma_f32_16x16x32_bf16 v[20:23], v[172:175], v[204:207], v[20:23]
	v_mfma_f32_16x16x32_bf16 v[16:19], v[180:183], v[204:207], v[16:19]
	v_mfma_f32_16x16x32_bf16 v[4:7], v[172:175], v[212:215], v[4:7]
	v_mfma_f32_16x16x32_bf16 v[0:3], v[180:183], v[212:215], v[0:3]
	s_barrier
	s_setprio 0
	s_add_i32 s44, 0, 0x18000
	s_add_i32 s68, 0, 0x1c000
	v_add_u32_e32 v164, s44, v151
	v_add_u32_e32 v180, s68, v151
	ds_read_b128 v[144:147], v164
	ds_read_b128 v[156:159], v164 offset:1024
	ds_read_b128 v[160:163], v164 offset:2048
	ds_read_b128 v[164:167], v164 offset:3072
	ds_read_b128 v[168:171], v180
	ds_read_b128 v[172:175], v180 offset:1024
	ds_read_b128 v[176:179], v180 offset:2048
	ds_read_b128 v[180:183], v180 offset:3072
	s_mov_b32 m0, s54
	v_lshl_add_u64 v[226:227], v[220:221], 0, s[6:7]
	ds_read_b128 v[184:187], v155 offset:32768
	ds_read_b128 v[188:191], v155 offset:33792
	ds_read_b128 v[192:195], v155 offset:34816
	ds_read_b128 v[196:199], v155 offset:35840
	ds_read_b128 v[200:203], v155 offset:36864
	ds_read_b128 v[204:207], v155 offset:37888
	ds_read_b128 v[208:211], v155 offset:38912
	ds_read_b128 v[212:215], v155 offset:39936
	global_load_lds_dwordx4 v[226:227], off
	s_mov_b32 m0, s55
	v_lshl_add_u64 v[226:227], v[224:225], 0, s[12:13]
	global_load_lds_dwordx4 v[226:227], off
	s_setprio 1
	s_waitcnt vmcnt(8) lgkmcnt(0)
	s_barrier
	v_mfma_f32_16x16x32_bf16 v[124:127], v[144:147], v[184:187], v[124:127]
	v_mfma_f32_16x16x32_bf16 v[120:123], v[160:163], v[184:187], v[120:123]
	v_mfma_f32_16x16x32_bf16 v[108:111], v[144:147], v[192:195], v[108:111]
	v_mfma_f32_16x16x32_bf16 v[104:107], v[160:163], v[192:195], v[104:107]
	v_mfma_f32_16x16x32_bf16 v[92:95], v[144:147], v[200:203], v[92:95]
	v_mfma_f32_16x16x32_bf16 v[88:91], v[160:163], v[200:203], v[88:91]
	v_mfma_f32_16x16x32_bf16 v[76:79], v[144:147], v[208:211], v[76:79]
	v_mfma_f32_16x16x32_bf16 v[72:75], v[160:163], v[208:211], v[72:75]
	v_mfma_f32_16x16x32_bf16 v[124:127], v[156:159], v[188:191], v[124:127]
	v_mfma_f32_16x16x32_bf16 v[120:123], v[164:167], v[188:191], v[120:123]
	v_mfma_f32_16x16x32_bf16 v[108:111], v[156:159], v[196:199], v[108:111]
	v_mfma_f32_16x16x32_bf16 v[104:107], v[164:167], v[196:199], v[104:107]
	v_mfma_f32_16x16x32_bf16 v[92:95], v[156:159], v[204:207], v[92:95]
	v_mfma_f32_16x16x32_bf16 v[88:91], v[164:167], v[204:207], v[88:91]
	v_mfma_f32_16x16x32_bf16 v[76:79], v[156:159], v[212:215], v[76:79]
	v_mfma_f32_16x16x32_bf16 v[72:75], v[164:167], v[212:215], v[72:75]
	v_mfma_f32_16x16x32_bf16 v[116:119], v[168:171], v[184:187], v[116:119]
	v_mfma_f32_16x16x32_bf16 v[112:115], v[176:179], v[184:187], v[112:115]
	v_mfma_f32_16x16x32_bf16 v[100:103], v[168:171], v[192:195], v[100:103]
	v_mfma_f32_16x16x32_bf16 v[96:99], v[176:179], v[192:195], v[96:99]
	v_mfma_f32_16x16x32_bf16 v[84:87], v[168:171], v[200:203], v[84:87]
	v_mfma_f32_16x16x32_bf16 v[80:83], v[176:179], v[200:203], v[80:83]
	v_mfma_f32_16x16x32_bf16 v[68:71], v[168:171], v[208:211], v[68:71]
	v_mfma_f32_16x16x32_bf16 v[64:67], v[176:179], v[208:211], v[64:67]
	v_mfma_f32_16x16x32_bf16 v[116:119], v[172:175], v[188:191], v[116:119]
	v_mfma_f32_16x16x32_bf16 v[112:115], v[180:183], v[188:191], v[112:115]
	v_mfma_f32_16x16x32_bf16 v[100:103], v[172:175], v[196:199], v[100:103]
	v_mfma_f32_16x16x32_bf16 v[96:99], v[180:183], v[196:199], v[96:99]
	v_mfma_f32_16x16x32_bf16 v[84:87], v[172:175], v[204:207], v[84:87]
	v_mfma_f32_16x16x32_bf16 v[80:83], v[180:183], v[204:207], v[80:83]
	v_mfma_f32_16x16x32_bf16 v[68:71], v[172:175], v[212:215], v[68:71]
	v_mfma_f32_16x16x32_bf16 v[64:67], v[180:183], v[212:215], v[64:67]
	s_barrier
	s_setprio 0
	s_add_i32 s44, s44, s33
	v_lshl_add_u64 v[148:149], v[148:149], 0, s[22:23]
	s_mov_b32 m0, s44
	ds_read_b128 v[184:187], v155 offset:49152
	ds_read_b128 v[188:191], v155 offset:50176
	ds_read_b128 v[192:195], v155 offset:51200
	ds_read_b128 v[196:199], v155 offset:52224
	ds_read_b128 v[200:203], v155 offset:53248
	ds_read_b128 v[204:207], v155 offset:54272
	ds_read_b128 v[208:211], v155 offset:55296
	ds_read_b128 v[212:215], v155 offset:56320
	global_load_lds_dwordx4 v[148:149], off
	s_add_i32 m0, s44, 0x2000
	s_add_u32 s44, s48, 0x20080
	v_lshl_add_u64 v[148:149], v[216:217], 0, s[22:23]
	s_addc_u32 s45, s49, 0
	s_add_i32 s48, s68, s33
	global_load_lds_dwordx4 v[148:149], off
	s_mov_b32 m0, s48
	v_lshl_add_u64 v[148:149], s[44:45], 0, v[132:133]
	global_load_lds_dwordx4 v[148:149], off
	s_add_i32 m0, s48, 0x2000
	v_lshl_add_u64 v[148:149], s[44:45], 0, v[128:129]
	global_load_lds_dwordx4 v[148:149], off
	s_mov_b32 m0, s57
	v_lshl_add_u64 v[148:149], v[220:221], 0, s[22:23]
	global_load_lds_dwordx4 v[148:149], off
	s_mov_b32 m0, s58
	v_lshl_add_u64 v[148:149], v[224:225], 0, s[24:25]
	global_load_lds_dwordx4 v[148:149], off
	s_add_i32 s74, s74, 2
	s_add_u32 s51, s51, 0x100
	s_addc_u32 s73, s73, 0
	s_cmp_gt_u32 s74, 5
	s_mov_b64 s[44:45], s[46:47]
	s_setprio 1
	s_waitcnt vmcnt(8) lgkmcnt(0)
	s_barrier
	v_mfma_f32_16x16x32_bf16 v[60:63], v[144:147], v[184:187], v[60:63]
	v_mfma_f32_16x16x32_bf16 v[56:59], v[160:163], v[184:187], v[56:59]
	v_mfma_f32_16x16x32_bf16 v[44:47], v[144:147], v[192:195], v[44:47]
	v_mfma_f32_16x16x32_bf16 v[40:43], v[160:163], v[192:195], v[40:43]
	v_mfma_f32_16x16x32_bf16 v[28:31], v[144:147], v[200:203], v[28:31]
	v_mfma_f32_16x16x32_bf16 v[24:27], v[160:163], v[200:203], v[24:27]
	v_mfma_f32_16x16x32_bf16 v[12:15], v[144:147], v[208:211], v[12:15]
	v_mfma_f32_16x16x32_bf16 v[8:11], v[160:163], v[208:211], v[8:11]
	v_mfma_f32_16x16x32_bf16 v[60:63], v[156:159], v[188:191], v[60:63]
	v_mfma_f32_16x16x32_bf16 v[56:59], v[164:167], v[188:191], v[56:59]
	v_mfma_f32_16x16x32_bf16 v[44:47], v[156:159], v[196:199], v[44:47]
	v_mfma_f32_16x16x32_bf16 v[40:43], v[164:167], v[196:199], v[40:43]
	v_mfma_f32_16x16x32_bf16 v[28:31], v[156:159], v[204:207], v[28:31]
	v_mfma_f32_16x16x32_bf16 v[24:27], v[164:167], v[204:207], v[24:27]
	v_mfma_f32_16x16x32_bf16 v[12:15], v[156:159], v[212:215], v[12:15]
	v_mfma_f32_16x16x32_bf16 v[8:11], v[164:167], v[212:215], v[8:11]
	v_mfma_f32_16x16x32_bf16 v[52:55], v[168:171], v[184:187], v[52:55]
	v_mfma_f32_16x16x32_bf16 v[48:51], v[176:179], v[184:187], v[48:51]
	v_mfma_f32_16x16x32_bf16 v[36:39], v[168:171], v[192:195], v[36:39]
	v_mfma_f32_16x16x32_bf16 v[32:35], v[176:179], v[192:195], v[32:35]
	v_mfma_f32_16x16x32_bf16 v[20:23], v[168:171], v[200:203], v[20:23]
	v_mfma_f32_16x16x32_bf16 v[16:19], v[176:179], v[200:203], v[16:19]
	v_mfma_f32_16x16x32_bf16 v[4:7], v[168:171], v[208:211], v[4:7]
	v_mfma_f32_16x16x32_bf16 v[0:3], v[176:179], v[208:211], v[0:3]
	v_mfma_f32_16x16x32_bf16 v[52:55], v[172:175], v[188:191], v[52:55]
	v_mfma_f32_16x16x32_bf16 v[48:51], v[180:183], v[188:191], v[48:51]
	v_mfma_f32_16x16x32_bf16 v[36:39], v[172:175], v[196:199], v[36:39]
	v_mfma_f32_16x16x32_bf16 v[32:35], v[180:183], v[196:199], v[32:35]
	v_mfma_f32_16x16x32_bf16 v[20:23], v[172:175], v[204:207], v[20:23]
	v_mfma_f32_16x16x32_bf16 v[16:19], v[180:183], v[204:207], v[16:19]
	v_mfma_f32_16x16x32_bf16 v[4:7], v[172:175], v[212:215], v[4:7]
	v_mfma_f32_16x16x32_bf16 v[0:3], v[180:183], v[212:215], v[0:3]
	s_barrier
	s_setprio 0
.LBB0_393:
	ds_read_b128 v[144:147], v153
	ds_read_b128 v[156:159], v153 offset:1024
	ds_read_b128 v[160:163], v153 offset:2048
	ds_read_b128 v[164:167], v153 offset:3072
	ds_read_b128 v[168:171], v154
	ds_read_b128 v[172:175], v154 offset:1024
	ds_read_b128 v[176:179], v154 offset:2048
	ds_read_b128 v[180:183], v154 offset:3072
	s_add_u32 s46, s44, 0x100
	s_addc_u32 s47, s45, 0
	s_cmp_eq_u32 s74, 4
	s_cselect_b32 s77, s67, s47
	s_cselect_b32 s76, s72, s46
	s_cselect_b32 s49, s39, s73
	s_cselect_b32 s48, s50, s51
	v_lshl_add_u64 v[148:149], s[44:45], 0, v[136:137]
	s_add_i32 m0, s52, 0xc000
	ds_read_b128 v[184:187], v155
	ds_read_b128 v[188:191], v155 offset:1024
	ds_read_b128 v[192:195], v155 offset:2048
	ds_read_b128 v[196:199], v155 offset:3072
	ds_read_b128 v[200:203], v155 offset:4096
	ds_read_b128 v[204:207], v155 offset:5120
	ds_read_b128 v[208:211], v155 offset:6144
	ds_read_b128 v[212:215], v155 offset:7168
	global_load_lds_dwordx4 v[148:149], off
	s_add_i32 m0, s52, 0xe000
	v_lshl_add_u64 v[148:149], s[44:45], 0, v[138:139]
	global_load_lds_dwordx4 v[148:149], off
	s_setprio 1
	s_waitcnt vmcnt(8) lgkmcnt(0)
	s_barrier
	v_mfma_f32_16x16x32_bf16 v[124:127], v[144:147], v[184:187], v[124:127]
	v_mfma_f32_16x16x32_bf16 v[120:123], v[160:163], v[184:187], v[120:123]
	v_mfma_f32_16x16x32_bf16 v[108:111], v[144:147], v[192:195], v[108:111]
	v_mfma_f32_16x16x32_bf16 v[104:107], v[160:163], v[192:195], v[104:107]
	v_mfma_f32_16x16x32_bf16 v[92:95], v[144:147], v[200:203], v[92:95]
	v_mfma_f32_16x16x32_bf16 v[88:91], v[160:163], v[200:203], v[88:91]
	v_mfma_f32_16x16x32_bf16 v[76:79], v[144:147], v[208:211], v[76:79]
	v_mfma_f32_16x16x32_bf16 v[72:75], v[160:163], v[208:211], v[72:75]
	v_mfma_f32_16x16x32_bf16 v[124:127], v[156:159], v[188:191], v[124:127]
	v_mfma_f32_16x16x32_bf16 v[120:123], v[164:167], v[188:191], v[120:123]
	v_mfma_f32_16x16x32_bf16 v[108:111], v[156:159], v[196:199], v[108:111]
	v_mfma_f32_16x16x32_bf16 v[104:107], v[164:167], v[196:199], v[104:107]
	v_mfma_f32_16x16x32_bf16 v[92:95], v[156:159], v[204:207], v[92:95]
	v_mfma_f32_16x16x32_bf16 v[88:91], v[164:167], v[204:207], v[88:91]
	v_mfma_f32_16x16x32_bf16 v[76:79], v[156:159], v[212:215], v[76:79]
	v_mfma_f32_16x16x32_bf16 v[72:75], v[164:167], v[212:215], v[72:75]
	v_mfma_f32_16x16x32_bf16 v[116:119], v[168:171], v[184:187], v[116:119]
	v_mfma_f32_16x16x32_bf16 v[112:115], v[176:179], v[184:187], v[112:115]
	v_mfma_f32_16x16x32_bf16 v[100:103], v[168:171], v[192:195], v[100:103]
	v_mfma_f32_16x16x32_bf16 v[96:99], v[176:179], v[192:195], v[96:99]
	v_mfma_f32_16x16x32_bf16 v[84:87], v[168:171], v[200:203], v[84:87]
	v_mfma_f32_16x16x32_bf16 v[80:83], v[176:179], v[200:203], v[80:83]
	v_mfma_f32_16x16x32_bf16 v[68:71], v[168:171], v[208:211], v[68:71]
	v_mfma_f32_16x16x32_bf16 v[64:67], v[176:179], v[208:211], v[64:67]
	v_mfma_f32_16x16x32_bf16 v[116:119], v[172:175], v[188:191], v[116:119]
	v_mfma_f32_16x16x32_bf16 v[112:115], v[180:183], v[188:191], v[112:115]
	v_mfma_f32_16x16x32_bf16 v[100:103], v[172:175], v[196:199], v[100:103]
	v_mfma_f32_16x16x32_bf16 v[96:99], v[180:183], v[196:199], v[96:99]
	v_mfma_f32_16x16x32_bf16 v[84:87], v[172:175], v[204:207], v[84:87]
	v_mfma_f32_16x16x32_bf16 v[80:83], v[180:183], v[204:207], v[80:83]
	v_mfma_f32_16x16x32_bf16 v[68:71], v[172:175], v[212:215], v[68:71]
	v_mfma_f32_16x16x32_bf16 v[64:67], v[180:183], v[212:215], v[64:67]
	s_barrier
	s_setprio 0
	s_add_i32 s44, s61, s33
	v_lshl_add_u64 v[148:149], s[48:49], 0, v[132:133]
	s_mov_b32 m0, s44
	ds_read_b128 v[184:187], v155 offset:16384
	ds_read_b128 v[188:191], v155 offset:17408
	ds_read_b128 v[192:195], v155 offset:18432
	ds_read_b128 v[196:199], v155 offset:19456
	ds_read_b128 v[200:203], v155 offset:20480
	ds_read_b128 v[204:207], v155 offset:21504
	ds_read_b128 v[208:211], v155 offset:22528
	ds_read_b128 v[212:215], v155 offset:23552
	global_load_lds_dwordx4 v[148:149], off
	s_add_i32 m0, s44, 0x2000
	s_add_u32 s44, s48, 0x20000
	v_lshl_add_u64 v[216:217], s[48:49], 0, v[128:129]
	s_addc_u32 s45, s49, 0
	s_add_i32 s68, s62, s33
	global_load_lds_dwordx4 v[216:217], off
	v_lshl_add_u64 v[220:221], s[44:45], 0, v[132:133]
	s_mov_b32 m0, s68
	v_lshl_add_u64 v[224:225], s[76:77], 0, v[130:131]
	global_load_lds_dwordx4 v[220:221], off
	v_lshl_add_u64 v[220:221], s[44:45], 0, v[128:129]
	s_add_i32 m0, s68, 0x2000
	v_lshl_add_u64 v[226:227], v[224:225], 0, s[8:9]
	global_load_lds_dwordx4 v[220:221], off
	s_mov_b32 m0, s52
	v_lshl_add_u64 v[220:221], s[76:77], 0, v[134:135]
	global_load_lds_dwordx4 v[220:221], off
	s_mov_b32 m0, s53
	s_nop 0
	global_load_lds_dwordx4 v[226:227], off
	s_setprio 1
	s_waitcnt vmcnt(8) lgkmcnt(0)
	s_barrier
	v_mfma_f32_16x16x32_bf16 v[60:63], v[144:147], v[184:187], v[60:63]
	v_mfma_f32_16x16x32_bf16 v[56:59], v[160:163], v[184:187], v[56:59]
	v_mfma_f32_16x16x32_bf16 v[44:47], v[144:147], v[192:195], v[44:47]
	v_mfma_f32_16x16x32_bf16 v[40:43], v[160:163], v[192:195], v[40:43]
	v_mfma_f32_16x16x32_bf16 v[28:31], v[144:147], v[200:203], v[28:31]
	v_mfma_f32_16x16x32_bf16 v[24:27], v[160:163], v[200:203], v[24:27]
	v_mfma_f32_16x16x32_bf16 v[12:15], v[144:147], v[208:211], v[12:15]
	v_mfma_f32_16x16x32_bf16 v[8:11], v[160:163], v[208:211], v[8:11]
	v_mfma_f32_16x16x32_bf16 v[60:63], v[156:159], v[188:191], v[60:63]
	v_mfma_f32_16x16x32_bf16 v[56:59], v[164:167], v[188:191], v[56:59]
	v_mfma_f32_16x16x32_bf16 v[44:47], v[156:159], v[196:199], v[44:47]
	v_mfma_f32_16x16x32_bf16 v[40:43], v[164:167], v[196:199], v[40:43]
	v_mfma_f32_16x16x32_bf16 v[28:31], v[156:159], v[204:207], v[28:31]
	v_mfma_f32_16x16x32_bf16 v[24:27], v[164:167], v[204:207], v[24:27]
	v_mfma_f32_16x16x32_bf16 v[12:15], v[156:159], v[212:215], v[12:15]
	v_mfma_f32_16x16x32_bf16 v[8:11], v[164:167], v[212:215], v[8:11]
	v_mfma_f32_16x16x32_bf16 v[52:55], v[168:171], v[184:187], v[52:55]
	v_mfma_f32_16x16x32_bf16 v[48:51], v[176:179], v[184:187], v[48:51]
	v_mfma_f32_16x16x32_bf16 v[36:39], v[168:171], v[192:195], v[36:39]
	v_mfma_f32_16x16x32_bf16 v[32:35], v[176:179], v[192:195], v[32:35]
	v_mfma_f32_16x16x32_bf16 v[20:23], v[168:171], v[200:203], v[20:23]
	v_mfma_f32_16x16x32_bf16 v[16:19], v[176:179], v[200:203], v[16:19]
	v_mfma_f32_16x16x32_bf16 v[4:7], v[168:171], v[208:211], v[4:7]
	v_mfma_f32_16x16x32_bf16 v[0:3], v[176:179], v[208:211], v[0:3]
	v_mfma_f32_16x16x32_bf16 v[52:55], v[172:175], v[188:191], v[52:55]
	v_mfma_f32_16x16x32_bf16 v[48:51], v[180:183], v[188:191], v[48:51]
	v_mfma_f32_16x16x32_bf16 v[36:39], v[172:175], v[196:199], v[36:39]
	v_mfma_f32_16x16x32_bf16 v[32:35], v[180:183], v[196:199], v[32:35]
	v_mfma_f32_16x16x32_bf16 v[20:23], v[172:175], v[204:207], v[20:23]
	v_mfma_f32_16x16x32_bf16 v[16:19], v[180:183], v[204:207], v[16:19]
	v_mfma_f32_16x16x32_bf16 v[4:7], v[172:175], v[212:215], v[4:7]
	v_mfma_f32_16x16x32_bf16 v[0:3], v[180:183], v[212:215], v[0:3]
	s_barrier
	s_setprio 0
	s_add_i32 s44, 0, 0x18000
	s_add_i32 s68, 0, 0x1c000
	v_add_u32_e32 v164, s44, v151
	v_add_u32_e32 v180, s68, v151
	ds_read_b128 v[144:147], v164
	ds_read_b128 v[156:159], v164 offset:1024
	ds_read_b128 v[160:163], v164 offset:2048
	ds_read_b128 v[164:167], v164 offset:3072
	ds_read_b128 v[168:171], v180
	ds_read_b128 v[172:175], v180 offset:1024
	ds_read_b128 v[176:179], v180 offset:2048
	ds_read_b128 v[180:183], v180 offset:3072
	s_mov_b32 m0, s54
	v_lshl_add_u64 v[226:227], v[220:221], 0, s[6:7]
	ds_read_b128 v[184:187], v155 offset:32768
	ds_read_b128 v[188:191], v155 offset:33792
	ds_read_b128 v[192:195], v155 offset:34816
	ds_read_b128 v[196:199], v155 offset:35840
	ds_read_b128 v[200:203], v155 offset:36864
	ds_read_b128 v[204:207], v155 offset:37888
	ds_read_b128 v[208:211], v155 offset:38912
	ds_read_b128 v[212:215], v155 offset:39936
	global_load_lds_dwordx4 v[226:227], off
	s_mov_b32 m0, s55
	v_lshl_add_u64 v[226:227], v[224:225], 0, s[12:13]
	global_load_lds_dwordx4 v[226:227], off
	s_setprio 1
	s_waitcnt vmcnt(8) lgkmcnt(0)
	s_barrier
	v_mfma_f32_16x16x32_bf16 v[124:127], v[144:147], v[184:187], v[124:127]
	v_mfma_f32_16x16x32_bf16 v[120:123], v[160:163], v[184:187], v[120:123]
	v_mfma_f32_16x16x32_bf16 v[108:111], v[144:147], v[192:195], v[108:111]
	v_mfma_f32_16x16x32_bf16 v[104:107], v[160:163], v[192:195], v[104:107]
	v_mfma_f32_16x16x32_bf16 v[92:95], v[144:147], v[200:203], v[92:95]
	v_mfma_f32_16x16x32_bf16 v[88:91], v[160:163], v[200:203], v[88:91]
	v_mfma_f32_16x16x32_bf16 v[76:79], v[144:147], v[208:211], v[76:79]
	v_mfma_f32_16x16x32_bf16 v[72:75], v[160:163], v[208:211], v[72:75]
	v_mfma_f32_16x16x32_bf16 v[124:127], v[156:159], v[188:191], v[124:127]
	v_mfma_f32_16x16x32_bf16 v[120:123], v[164:167], v[188:191], v[120:123]
	v_mfma_f32_16x16x32_bf16 v[108:111], v[156:159], v[196:199], v[108:111]
	v_mfma_f32_16x16x32_bf16 v[104:107], v[164:167], v[196:199], v[104:107]
	v_mfma_f32_16x16x32_bf16 v[92:95], v[156:159], v[204:207], v[92:95]
	v_mfma_f32_16x16x32_bf16 v[88:91], v[164:167], v[204:207], v[88:91]
	v_mfma_f32_16x16x32_bf16 v[76:79], v[156:159], v[212:215], v[76:79]
	v_mfma_f32_16x16x32_bf16 v[72:75], v[164:167], v[212:215], v[72:75]
	v_mfma_f32_16x16x32_bf16 v[116:119], v[168:171], v[184:187], v[116:119]
	v_mfma_f32_16x16x32_bf16 v[112:115], v[176:179], v[184:187], v[112:115]
	v_mfma_f32_16x16x32_bf16 v[100:103], v[168:171], v[192:195], v[100:103]
	v_mfma_f32_16x16x32_bf16 v[96:99], v[176:179], v[192:195], v[96:99]
	v_mfma_f32_16x16x32_bf16 v[84:87], v[168:171], v[200:203], v[84:87]
	v_mfma_f32_16x16x32_bf16 v[80:83], v[176:179], v[200:203], v[80:83]
	v_mfma_f32_16x16x32_bf16 v[68:71], v[168:171], v[208:211], v[68:71]
	v_mfma_f32_16x16x32_bf16 v[64:67], v[176:179], v[208:211], v[64:67]
	v_mfma_f32_16x16x32_bf16 v[116:119], v[172:175], v[188:191], v[116:119]
	v_mfma_f32_16x16x32_bf16 v[112:115], v[180:183], v[188:191], v[112:115]
	v_mfma_f32_16x16x32_bf16 v[100:103], v[172:175], v[196:199], v[100:103]
	v_mfma_f32_16x16x32_bf16 v[96:99], v[180:183], v[196:199], v[96:99]
	v_mfma_f32_16x16x32_bf16 v[84:87], v[172:175], v[204:207], v[84:87]
	v_mfma_f32_16x16x32_bf16 v[80:83], v[180:183], v[204:207], v[80:83]
	v_mfma_f32_16x16x32_bf16 v[68:71], v[172:175], v[212:215], v[68:71]
	v_mfma_f32_16x16x32_bf16 v[64:67], v[180:183], v[212:215], v[64:67]
	s_barrier
	s_setprio 0
	s_add_i32 s44, s44, s33
	v_lshl_add_u64 v[148:149], v[148:149], 0, s[22:23]
	s_mov_b32 m0, s44
	ds_read_b128 v[184:187], v155 offset:49152
	ds_read_b128 v[188:191], v155 offset:50176
	ds_read_b128 v[192:195], v155 offset:51200
	ds_read_b128 v[196:199], v155 offset:52224
	ds_read_b128 v[200:203], v155 offset:53248
	ds_read_b128 v[204:207], v155 offset:54272
	ds_read_b128 v[208:211], v155 offset:55296
	ds_read_b128 v[212:215], v155 offset:56320
	global_load_lds_dwordx4 v[148:149], off
	s_add_i32 m0, s44, 0x2000
	s_add_u32 s44, s48, 0x20080
	v_lshl_add_u64 v[148:149], v[216:217], 0, s[22:23]
	s_addc_u32 s45, s49, 0
	s_add_i32 s48, s68, s33
	global_load_lds_dwordx4 v[148:149], off
	s_mov_b32 m0, s48
	v_lshl_add_u64 v[148:149], s[44:45], 0, v[132:133]
	global_load_lds_dwordx4 v[148:149], off
	s_add_i32 m0, s48, 0x2000
	v_lshl_add_u64 v[148:149], s[44:45], 0, v[128:129]
	global_load_lds_dwordx4 v[148:149], off
	s_mov_b32 m0, s57
	v_lshl_add_u64 v[148:149], v[220:221], 0, s[22:23]
	global_load_lds_dwordx4 v[148:149], off
	s_mov_b32 m0, s58
	v_lshl_add_u64 v[148:149], v[224:225], 0, s[24:25]
	global_load_lds_dwordx4 v[148:149], off
	s_add_i32 s74, s74, 2
	s_add_u32 s51, s51, 0x100
	s_addc_u32 s73, s73, 0
	s_cmp_gt_u32 s74, 5
	s_mov_b64 s[44:45], s[46:47]
	s_setprio 1
	s_waitcnt vmcnt(8) lgkmcnt(0)
	s_barrier
	v_mfma_f32_16x16x32_bf16 v[60:63], v[144:147], v[184:187], v[60:63]
	v_mfma_f32_16x16x32_bf16 v[56:59], v[160:163], v[184:187], v[56:59]
	v_mfma_f32_16x16x32_bf16 v[44:47], v[144:147], v[192:195], v[44:47]
	v_mfma_f32_16x16x32_bf16 v[40:43], v[160:163], v[192:195], v[40:43]
	v_mfma_f32_16x16x32_bf16 v[28:31], v[144:147], v[200:203], v[28:31]
	v_mfma_f32_16x16x32_bf16 v[24:27], v[160:163], v[200:203], v[24:27]
	v_mfma_f32_16x16x32_bf16 v[12:15], v[144:147], v[208:211], v[12:15]
	v_mfma_f32_16x16x32_bf16 v[8:11], v[160:163], v[208:211], v[8:11]
	v_mfma_f32_16x16x32_bf16 v[60:63], v[156:159], v[188:191], v[60:63]
	v_mfma_f32_16x16x32_bf16 v[56:59], v[164:167], v[188:191], v[56:59]
	v_mfma_f32_16x16x32_bf16 v[44:47], v[156:159], v[196:199], v[44:47]
	v_mfma_f32_16x16x32_bf16 v[40:43], v[164:167], v[196:199], v[40:43]
	v_mfma_f32_16x16x32_bf16 v[28:31], v[156:159], v[204:207], v[28:31]
	v_mfma_f32_16x16x32_bf16 v[24:27], v[164:167], v[204:207], v[24:27]
	v_mfma_f32_16x16x32_bf16 v[12:15], v[156:159], v[212:215], v[12:15]
	v_mfma_f32_16x16x32_bf16 v[8:11], v[164:167], v[212:215], v[8:11]
	v_mfma_f32_16x16x32_bf16 v[52:55], v[168:171], v[184:187], v[52:55]
	v_mfma_f32_16x16x32_bf16 v[48:51], v[176:179], v[184:187], v[48:51]
	v_mfma_f32_16x16x32_bf16 v[36:39], v[168:171], v[192:195], v[36:39]
	v_mfma_f32_16x16x32_bf16 v[32:35], v[176:179], v[192:195], v[32:35]
	v_mfma_f32_16x16x32_bf16 v[20:23], v[168:171], v[200:203], v[20:23]
	v_mfma_f32_16x16x32_bf16 v[16:19], v[176:179], v[200:203], v[16:19]
	v_mfma_f32_16x16x32_bf16 v[4:7], v[168:171], v[208:211], v[4:7]
	v_mfma_f32_16x16x32_bf16 v[0:3], v[176:179], v[208:211], v[0:3]
	v_mfma_f32_16x16x32_bf16 v[52:55], v[172:175], v[188:191], v[52:55]
	v_mfma_f32_16x16x32_bf16 v[48:51], v[180:183], v[188:191], v[48:51]
	v_mfma_f32_16x16x32_bf16 v[36:39], v[172:175], v[196:199], v[36:39]
	v_mfma_f32_16x16x32_bf16 v[32:35], v[180:183], v[196:199], v[32:35]
	v_mfma_f32_16x16x32_bf16 v[20:23], v[172:175], v[204:207], v[20:23]
	v_mfma_f32_16x16x32_bf16 v[16:19], v[180:183], v[204:207], v[16:19]
	v_mfma_f32_16x16x32_bf16 v[4:7], v[172:175], v[212:215], v[4:7]
	v_mfma_f32_16x16x32_bf16 v[0:3], v[180:183], v[212:215], v[0:3]
	s_barrier
	s_setprio 0
	s_cbranch_scc0 .LBB0_393
	s_and_b64 vcc, exec, s[36:37]
	s_cbranch_vccz .LBB0_396
	s_barrier

.LBB0_465:
	s_lshl_b32 s42, s73, 8
	s_ashr_i32 s43, s42, 31
	s_lshl_b64 s[42:43], s[42:43], 11
	s_add_u32 s42, s10, s42
	s_addc_u32 s43, s11, s43
	s_and_b64 s[44:45], s[4:5], exec
	s_cselect_b32 s47, s43, s49
	s_cselect_b32 s74, s42, s48
	s_ashr_i32 s41, s40, 31
	s_lshl_b64 s[44:45], s[40:41], 19
	s_add_u32 s44, s33, s44
	s_addc_u32 s45, s34, s45
	s_and_b64 s[50:51], s[4:5], exec
	s_cselect_b32 s41, s45, s53
	s_cselect_b32 s50, s44, s52
	s_add_u32 s51, s52, 0x100
	s_addc_u32 s75, s53, 0
	s_mov_b32 s76, -2
	s_waitcnt lgkmcnt(0)
	s_waitcnt vmcnt(0)
	s_waitcnt lgkmcnt(0)
	ds_read_b128 v[144:147], v151
	ds_read_b128 v[156:159], v151 offset:1024
	ds_read_b128 v[160:163], v151 offset:2048
	ds_read_b128 v[164:167], v151 offset:3072
	ds_read_b128 v[168:171], v152
	ds_read_b128 v[172:175], v152 offset:1024
	ds_read_b128 v[176:179], v152 offset:2048
	ds_read_b128 v[180:183], v152 offset:3072
	s_add_u32 s52, s48, 0x100
	s_addc_u32 s53, s49, 0
	s_cmp_eq_u32 s76, 12
	s_cselect_b32 s79, s47, s53
	s_cselect_b32 s78, s74, s52
	s_cselect_b32 s55, s41, s75
	s_cselect_b32 s54, s50, s51
	v_lshl_add_u64 v[216:217], s[48:49], 0, v[136:137]
	s_add_i32 m0, s56, 0xc000
	ds_read_b128 v[184:187], v153
	ds_read_b128 v[188:191], v153 offset:1024
	ds_read_b128 v[192:195], v153 offset:2048
	ds_read_b128 v[196:199], v153 offset:3072
	ds_read_b128 v[200:203], v153 offset:4096
	ds_read_b128 v[204:207], v153 offset:5120
	ds_read_b128 v[208:211], v153 offset:6144
	ds_read_b128 v[212:215], v153 offset:7168
	global_load_lds_dwordx4 v[216:217], off
	s_add_i32 m0, s56, 0xe000
	v_lshl_add_u64 v[216:217], s[48:49], 0, v[138:139]
	global_load_lds_dwordx4 v[216:217], off
	s_setprio 1
	s_waitcnt vmcnt(8) lgkmcnt(0)
	s_barrier
	v_mfma_f32_16x16x32_bf16 v[124:127], v[144:147], v[184:187], 0
	v_mfma_f32_16x16x32_bf16 v[120:123], v[160:163], v[184:187], 0
	v_mfma_f32_16x16x32_bf16 v[108:111], v[144:147], v[192:195], 0
	v_mfma_f32_16x16x32_bf16 v[104:107], v[160:163], v[192:195], 0
	v_mfma_f32_16x16x32_bf16 v[92:95], v[144:147], v[200:203], 0
	v_mfma_f32_16x16x32_bf16 v[88:91], v[160:163], v[200:203], 0
	v_mfma_f32_16x16x32_bf16 v[76:79], v[144:147], v[208:211], 0
	v_mfma_f32_16x16x32_bf16 v[72:75], v[160:163], v[208:211], 0
	v_mfma_f32_16x16x32_bf16 v[124:127], v[156:159], v[188:191], v[124:127]
	v_mfma_f32_16x16x32_bf16 v[120:123], v[164:167], v[188:191], v[120:123]
	v_mfma_f32_16x16x32_bf16 v[108:111], v[156:159], v[196:199], v[108:111]
	v_mfma_f32_16x16x32_bf16 v[104:107], v[164:167], v[196:199], v[104:107]
	v_mfma_f32_16x16x32_bf16 v[92:95], v[156:159], v[204:207], v[92:95]
	v_mfma_f32_16x16x32_bf16 v[88:91], v[164:167], v[204:207], v[88:91]
	v_mfma_f32_16x16x32_bf16 v[76:79], v[156:159], v[212:215], v[76:79]
	v_mfma_f32_16x16x32_bf16 v[72:75], v[164:167], v[212:215], v[72:75]
	v_mfma_f32_16x16x32_bf16 v[116:119], v[168:171], v[184:187], 0
	v_mfma_f32_16x16x32_bf16 v[112:115], v[176:179], v[184:187], 0
	v_mfma_f32_16x16x32_bf16 v[100:103], v[168:171], v[192:195], 0
	v_mfma_f32_16x16x32_bf16 v[96:99], v[176:179], v[192:195], 0
	v_mfma_f32_16x16x32_bf16 v[84:87], v[168:171], v[200:203], 0
	v_mfma_f32_16x16x32_bf16 v[80:83], v[176:179], v[200:203], 0
	v_mfma_f32_16x16x32_bf16 v[68:71], v[168:171], v[208:211], 0
	v_mfma_f32_16x16x32_bf16 v[64:67], v[176:179], v[208:211], 0
	v_mfma_f32_16x16x32_bf16 v[116:119], v[172:175], v[188:191], v[116:119]
	v_mfma_f32_16x16x32_bf16 v[112:115], v[180:183], v[188:191], v[112:115]
	v_mfma_f32_16x16x32_bf16 v[100:103], v[172:175], v[196:199], v[100:103]
	v_mfma_f32_16x16x32_bf16 v[96:99], v[180:183], v[196:199], v[96:99]
	v_mfma_f32_16x16x32_bf16 v[84:87], v[172:175], v[204:207], v[84:87]
	v_mfma_f32_16x16x32_bf16 v[80:83], v[180:183], v[204:207], v[80:83]
	v_mfma_f32_16x16x32_bf16 v[68:71], v[172:175], v[212:215], v[68:71]
	v_mfma_f32_16x16x32_bf16 v[64:67], v[180:183], v[212:215], v[64:67]
	s_barrier
	s_setprio 0
	s_add_i32 s48, s67, s35
	v_lshl_add_u64 v[216:217], s[54:55], 0, v[130:131]
	s_mov_b32 m0, s48
	ds_read_b128 v[184:187], v153 offset:16384
	ds_read_b128 v[188:191], v153 offset:17408
	ds_read_b128 v[192:195], v153 offset:18432
	ds_read_b128 v[196:199], v153 offset:19456
	ds_read_b128 v[200:203], v153 offset:20480
	ds_read_b128 v[204:207], v153 offset:21504
	ds_read_b128 v[208:211], v153 offset:22528
	ds_read_b128 v[212:215], v153 offset:23552
	global_load_lds_dwordx4 v[216:217], off
	s_add_i32 m0, s48, 0x2000
	s_add_u32 s48, s54, 0x40000
	v_lshl_add_u64 v[220:221], s[54:55], 0, v[134:135]
	s_addc_u32 s49, s55, 0
	s_add_i32 s68, s72, s35
	global_load_lds_dwordx4 v[220:221], off
	v_lshl_add_u64 v[224:225], s[48:49], 0, v[130:131]
	s_mov_b32 m0, s68
	v_lshl_add_u64 v[226:227], s[78:79], 0, v[132:133]
	global_load_lds_dwordx4 v[224:225], off
	v_lshl_add_u64 v[224:225], s[48:49], 0, v[134:135]
	s_add_i32 m0, s68, 0x2000
	v_lshl_add_u64 v[228:229], v[226:227], 0, s[12:13]
	global_load_lds_dwordx4 v[224:225], off
	s_mov_b32 m0, s56
	v_lshl_add_u64 v[224:225], s[78:79], 0, v[128:129]
	global_load_lds_dwordx4 v[224:225], off
	s_mov_b32 m0, s57
	s_nop 0
	global_load_lds_dwordx4 v[228:229], off
	s_setprio 1
	s_waitcnt vmcnt(8) lgkmcnt(0)
	s_barrier
	v_mfma_f32_16x16x32_bf16 v[60:63], v[144:147], v[184:187], 0
	v_mfma_f32_16x16x32_bf16 v[56:59], v[160:163], v[184:187], 0
	v_mfma_f32_16x16x32_bf16 v[44:47], v[144:147], v[192:195], 0
	v_mfma_f32_16x16x32_bf16 v[40:43], v[160:163], v[192:195], 0
	v_mfma_f32_16x16x32_bf16 v[28:31], v[144:147], v[200:203], 0
	v_mfma_f32_16x16x32_bf16 v[24:27], v[160:163], v[200:203], 0
	v_mfma_f32_16x16x32_bf16 v[12:15], v[144:147], v[208:211], 0
	v_mfma_f32_16x16x32_bf16 v[8:11], v[160:163], v[208:211], 0
	v_mfma_f32_16x16x32_bf16 v[60:63], v[156:159], v[188:191], v[60:63]
	v_mfma_f32_16x16x32_bf16 v[56:59], v[164:167], v[188:191], v[56:59]
	v_mfma_f32_16x16x32_bf16 v[44:47], v[156:159], v[196:199], v[44:47]
	v_mfma_f32_16x16x32_bf16 v[40:43], v[164:167], v[196:199], v[40:43]
	v_mfma_f32_16x16x32_bf16 v[28:31], v[156:159], v[204:207], v[28:31]
	v_mfma_f32_16x16x32_bf16 v[24:27], v[164:167], v[204:207], v[24:27]
	v_mfma_f32_16x16x32_bf16 v[12:15], v[156:159], v[212:215], v[12:15]
	v_mfma_f32_16x16x32_bf16 v[8:11], v[164:167], v[212:215], v[8:11]
	v_mfma_f32_16x16x32_bf16 v[52:55], v[168:171], v[184:187], 0
	v_mfma_f32_16x16x32_bf16 v[48:51], v[176:179], v[184:187], 0
	v_mfma_f32_16x16x32_bf16 v[36:39], v[168:171], v[192:195], 0
	v_mfma_f32_16x16x32_bf16 v[32:35], v[176:179], v[192:195], 0
	v_mfma_f32_16x16x32_bf16 v[20:23], v[168:171], v[200:203], 0
	v_mfma_f32_16x16x32_bf16 v[16:19], v[176:179], v[200:203], 0
	v_mfma_f32_16x16x32_bf16 v[4:7], v[168:171], v[208:211], 0
	v_mfma_f32_16x16x32_bf16 v[0:3], v[176:179], v[208:211], 0
	v_mfma_f32_16x16x32_bf16 v[52:55], v[172:175], v[188:191], v[52:55]
	v_mfma_f32_16x16x32_bf16 v[48:51], v[180:183], v[188:191], v[48:51]
	v_mfma_f32_16x16x32_bf16 v[36:39], v[172:175], v[196:199], v[36:39]
	v_mfma_f32_16x16x32_bf16 v[32:35], v[180:183], v[196:199], v[32:35]
	v_mfma_f32_16x16x32_bf16 v[20:23], v[172:175], v[204:207], v[20:23]
	v_mfma_f32_16x16x32_bf16 v[16:19], v[180:183], v[204:207], v[16:19]
	v_mfma_f32_16x16x32_bf16 v[4:7], v[172:175], v[212:215], v[4:7]
	v_mfma_f32_16x16x32_bf16 v[0:3], v[180:183], v[212:215], v[0:3]
	s_barrier
	s_setprio 0
	s_add_i32 s48, 0, 0x18000
	v_add_u32_e32 v155, s48, v149
	s_add_i32 s68, 0, 0x1c000
	ds_read_b128 v[144:147], v155
	ds_read_b128 v[156:159], v155 offset:1024
	ds_read_b128 v[160:163], v155 offset:2048
	ds_read_b128 v[164:167], v155 offset:3072
	v_add_u32_e32 v155, s68, v149
	ds_read_b128 v[168:171], v155
	ds_read_b128 v[172:175], v155 offset:1024
	ds_read_b128 v[176:179], v155 offset:2048
	ds_read_b128 v[180:183], v155 offset:3072
	s_mov_b32 m0, s58
	v_lshl_add_u64 v[228:229], v[224:225], 0, s[8:9]
	ds_read_b128 v[184:187], v153 offset:32768
	ds_read_b128 v[188:191], v153 offset:33792
	ds_read_b128 v[192:195], v153 offset:34816
	ds_read_b128 v[196:199], v153 offset:35840
	ds_read_b128 v[200:203], v153 offset:36864
	ds_read_b128 v[204:207], v153 offset:37888
	ds_read_b128 v[208:211], v153 offset:38912
	ds_read_b128 v[212:215], v153 offset:39936
	global_load_lds_dwordx4 v[228:229], off
	s_mov_b32 m0, s59
	v_lshl_add_u64 v[228:229], v[226:227], 0, s[14:15]
	global_load_lds_dwordx4 v[228:229], off
	s_setprio 1
	s_waitcnt vmcnt(8) lgkmcnt(0)
	s_barrier
	v_mfma_f32_16x16x32_bf16 v[124:127], v[144:147], v[184:187], v[124:127]
	v_mfma_f32_16x16x32_bf16 v[120:123], v[160:163], v[184:187], v[120:123]
	v_mfma_f32_16x16x32_bf16 v[108:111], v[144:147], v[192:195], v[108:111]
	v_mfma_f32_16x16x32_bf16 v[104:107], v[160:163], v[192:195], v[104:107]
	v_mfma_f32_16x16x32_bf16 v[92:95], v[144:147], v[200:203], v[92:95]
	v_mfma_f32_16x16x32_bf16 v[88:91], v[160:163], v[200:203], v[88:91]
	v_mfma_f32_16x16x32_bf16 v[76:79], v[144:147], v[208:211], v[76:79]
	v_mfma_f32_16x16x32_bf16 v[72:75], v[160:163], v[208:211], v[72:75]
	v_mfma_f32_16x16x32_bf16 v[124:127], v[156:159], v[188:191], v[124:127]
	v_mfma_f32_16x16x32_bf16 v[120:123], v[164:167], v[188:191], v[120:123]
	v_mfma_f32_16x16x32_bf16 v[108:111], v[156:159], v[196:199], v[108:111]
	v_mfma_f32_16x16x32_bf16 v[104:107], v[164:167], v[196:199], v[104:107]
	v_mfma_f32_16x16x32_bf16 v[92:95], v[156:159], v[204:207], v[92:95]
	v_mfma_f32_16x16x32_bf16 v[88:91], v[164:167], v[204:207], v[88:91]
	v_mfma_f32_16x16x32_bf16 v[76:79], v[156:159], v[212:215], v[76:79]
	v_mfma_f32_16x16x32_bf16 v[72:75], v[164:167], v[212:215], v[72:75]
	v_mfma_f32_16x16x32_bf16 v[116:119], v[168:171], v[184:187], v[116:119]
	v_mfma_f32_16x16x32_bf16 v[112:115], v[176:179], v[184:187], v[112:115]
	v_mfma_f32_16x16x32_bf16 v[100:103], v[168:171], v[192:195], v[100:103]
	v_mfma_f32_16x16x32_bf16 v[96:99], v[176:179], v[192:195], v[96:99]
	v_mfma_f32_16x16x32_bf16 v[84:87], v[168:171], v[200:203], v[84:87]
	v_mfma_f32_16x16x32_bf16 v[80:83], v[176:179], v[200:203], v[80:83]
	v_mfma_f32_16x16x32_bf16 v[68:71], v[168:171], v[208:211], v[68:71]
	v_mfma_f32_16x16x32_bf16 v[64:67], v[176:179], v[208:211], v[64:67]
	v_mfma_f32_16x16x32_bf16 v[116:119], v[172:175], v[188:191], v[116:119]
	v_mfma_f32_16x16x32_bf16 v[112:115], v[180:183], v[188:191], v[112:115]
	v_mfma_f32_16x16x32_bf16 v[100:103], v[172:175], v[196:199], v[100:103]
	v_mfma_f32_16x16x32_bf16 v[96:99], v[180:183], v[196:199], v[96:99]
	v_mfma_f32_16x16x32_bf16 v[84:87], v[172:175], v[204:207], v[84:87]
	v_mfma_f32_16x16x32_bf16 v[80:83], v[180:183], v[204:207], v[80:83]
	v_mfma_f32_16x16x32_bf16 v[68:71], v[172:175], v[212:215], v[68:71]
	v_mfma_f32_16x16x32_bf16 v[64:67], v[180:183], v[212:215], v[64:67]
	s_barrier
	s_setprio 0
	s_add_i32 s48, s48, s35
	v_lshl_add_u64 v[216:217], v[216:217], 0, s[24:25]
	s_mov_b32 m0, s48
	ds_read_b128 v[184:187], v153 offset:49152
	ds_read_b128 v[188:191], v153 offset:50176
	ds_read_b128 v[192:195], v153 offset:51200
	ds_read_b128 v[196:199], v153 offset:52224
	ds_read_b128 v[200:203], v153 offset:53248
	ds_read_b128 v[204:207], v153 offset:54272
	ds_read_b128 v[208:211], v153 offset:55296
	ds_read_b128 v[212:215], v153 offset:56320
	global_load_lds_dwordx4 v[216:217], off
	s_add_i32 m0, s48, 0x2000
	s_add_u32 s48, s54, 0x40080
	v_lshl_add_u64 v[216:217], v[220:221], 0, s[24:25]
	s_addc_u32 s49, s55, 0
	s_add_i32 s54, s68, s35
	global_load_lds_dwordx4 v[216:217], off
	s_mov_b32 m0, s54
	v_lshl_add_u64 v[216:217], s[48:49], 0, v[130:131]
	global_load_lds_dwordx4 v[216:217], off
	s_add_i32 m0, s54, 0x2000
	v_lshl_add_u64 v[216:217], s[48:49], 0, v[134:135]
	global_load_lds_dwordx4 v[216:217], off
	s_mov_b32 m0, s61
	v_lshl_add_u64 v[216:217], v[224:225], 0, s[24:25]
	global_load_lds_dwordx4 v[216:217], off
	s_mov_b32 m0, s62
	v_lshl_add_u64 v[216:217], v[226:227], 0, s[36:37]
	global_load_lds_dwordx4 v[216:217], off
	s_add_i32 s76, s76, 2
	s_add_u32 s51, s51, 0x100
	s_addc_u32 s75, s75, 0
	s_cmp_gt_u32 s76, 13
	s_mov_b64 s[48:49], s[52:53]
	s_setprio 1
	s_waitcnt vmcnt(8) lgkmcnt(0)
	s_barrier
	v_mfma_f32_16x16x32_bf16 v[60:63], v[144:147], v[184:187], v[60:63]
	v_mfma_f32_16x16x32_bf16 v[56:59], v[160:163], v[184:187], v[56:59]
	v_mfma_f32_16x16x32_bf16 v[44:47], v[144:147], v[192:195], v[44:47]
	v_mfma_f32_16x16x32_bf16 v[40:43], v[160:163], v[192:195], v[40:43]
	v_mfma_f32_16x16x32_bf16 v[28:31], v[144:147], v[200:203], v[28:31]
	v_mfma_f32_16x16x32_bf16 v[24:27], v[160:163], v[200:203], v[24:27]
	v_mfma_f32_16x16x32_bf16 v[12:15], v[144:147], v[208:211], v[12:15]
	v_mfma_f32_16x16x32_bf16 v[8:11], v[160:163], v[208:211], v[8:11]
	v_mfma_f32_16x16x32_bf16 v[60:63], v[156:159], v[188:191], v[60:63]
	v_mfma_f32_16x16x32_bf16 v[56:59], v[164:167], v[188:191], v[56:59]
	v_mfma_f32_16x16x32_bf16 v[44:47], v[156:159], v[196:199], v[44:47]
	v_mfma_f32_16x16x32_bf16 v[40:43], v[164:167], v[196:199], v[40:43]
	v_mfma_f32_16x16x32_bf16 v[28:31], v[156:159], v[204:207], v[28:31]
	v_mfma_f32_16x16x32_bf16 v[24:27], v[164:167], v[204:207], v[24:27]
	v_mfma_f32_16x16x32_bf16 v[12:15], v[156:159], v[212:215], v[12:15]
	v_mfma_f32_16x16x32_bf16 v[8:11], v[164:167], v[212:215], v[8:11]
	v_mfma_f32_16x16x32_bf16 v[52:55], v[168:171], v[184:187], v[52:55]
	v_mfma_f32_16x16x32_bf16 v[48:51], v[176:179], v[184:187], v[48:51]
	v_mfma_f32_16x16x32_bf16 v[36:39], v[168:171], v[192:195], v[36:39]
	v_mfma_f32_16x16x32_bf16 v[32:35], v[176:179], v[192:195], v[32:35]
	v_mfma_f32_16x16x32_bf16 v[20:23], v[168:171], v[200:203], v[20:23]
	v_mfma_f32_16x16x32_bf16 v[16:19], v[176:179], v[200:203], v[16:19]
	v_mfma_f32_16x16x32_bf16 v[4:7], v[168:171], v[208:211], v[4:7]
	v_mfma_f32_16x16x32_bf16 v[0:3], v[176:179], v[208:211], v[0:3]
	v_mfma_f32_16x16x32_bf16 v[52:55], v[172:175], v[188:191], v[52:55]
	v_mfma_f32_16x16x32_bf16 v[48:51], v[180:183], v[188:191], v[48:51]
	v_mfma_f32_16x16x32_bf16 v[36:39], v[172:175], v[196:199], v[36:39]
	v_mfma_f32_16x16x32_bf16 v[32:35], v[180:183], v[196:199], v[32:35]
	v_mfma_f32_16x16x32_bf16 v[20:23], v[172:175], v[204:207], v[20:23]
	v_mfma_f32_16x16x32_bf16 v[16:19], v[180:183], v[204:207], v[16:19]
	v_mfma_f32_16x16x32_bf16 v[4:7], v[172:175], v[212:215], v[4:7]
	v_mfma_f32_16x16x32_bf16 v[0:3], v[180:183], v[212:215], v[0:3]
	s_barrier
	s_setprio 0
.LBB0_466:
	ds_read_b128 v[144:147], v151
	ds_read_b128 v[156:159], v151 offset:1024
	ds_read_b128 v[160:163], v151 offset:2048
	ds_read_b128 v[164:167], v151 offset:3072
	ds_read_b128 v[168:171], v152
	ds_read_b128 v[172:175], v152 offset:1024
	ds_read_b128 v[176:179], v152 offset:2048
	ds_read_b128 v[180:183], v152 offset:3072
	s_add_u32 s52, s48, 0x100
	s_addc_u32 s53, s49, 0
	s_cmp_eq_u32 s76, 12
	s_cselect_b32 s79, s47, s53
	s_cselect_b32 s78, s74, s52
	s_cselect_b32 s55, s41, s75
	s_cselect_b32 s54, s50, s51
	v_lshl_add_u64 v[216:217], s[48:49], 0, v[136:137]
	s_add_i32 m0, s56, 0xc000
	ds_read_b128 v[184:187], v153
	ds_read_b128 v[188:191], v153 offset:1024
	ds_read_b128 v[192:195], v153 offset:2048
	ds_read_b128 v[196:199], v153 offset:3072
	ds_read_b128 v[200:203], v153 offset:4096
	ds_read_b128 v[204:207], v153 offset:5120
	ds_read_b128 v[208:211], v153 offset:6144
	ds_read_b128 v[212:215], v153 offset:7168
	global_load_lds_dwordx4 v[216:217], off
	s_add_i32 m0, s56, 0xe000
	v_lshl_add_u64 v[216:217], s[48:49], 0, v[138:139]
	global_load_lds_dwordx4 v[216:217], off
	s_setprio 1
	s_waitcnt vmcnt(8) lgkmcnt(0)
	s_barrier
	v_mfma_f32_16x16x32_bf16 v[124:127], v[144:147], v[184:187], v[124:127]
	v_mfma_f32_16x16x32_bf16 v[120:123], v[160:163], v[184:187], v[120:123]
	v_mfma_f32_16x16x32_bf16 v[108:111], v[144:147], v[192:195], v[108:111]
	v_mfma_f32_16x16x32_bf16 v[104:107], v[160:163], v[192:195], v[104:107]
	v_mfma_f32_16x16x32_bf16 v[92:95], v[144:147], v[200:203], v[92:95]
	v_mfma_f32_16x16x32_bf16 v[88:91], v[160:163], v[200:203], v[88:91]
	v_mfma_f32_16x16x32_bf16 v[76:79], v[144:147], v[208:211], v[76:79]
	v_mfma_f32_16x16x32_bf16 v[72:75], v[160:163], v[208:211], v[72:75]
	v_mfma_f32_16x16x32_bf16 v[124:127], v[156:159], v[188:191], v[124:127]
	v_mfma_f32_16x16x32_bf16 v[120:123], v[164:167], v[188:191], v[120:123]
	v_mfma_f32_16x16x32_bf16 v[108:111], v[156:159], v[196:199], v[108:111]
	v_mfma_f32_16x16x32_bf16 v[104:107], v[164:167], v[196:199], v[104:107]
	v_mfma_f32_16x16x32_bf16 v[92:95], v[156:159], v[204:207], v[92:95]
	v_mfma_f32_16x16x32_bf16 v[88:91], v[164:167], v[204:207], v[88:91]
	v_mfma_f32_16x16x32_bf16 v[76:79], v[156:159], v[212:215], v[76:79]
	v_mfma_f32_16x16x32_bf16 v[72:75], v[164:167], v[212:215], v[72:75]
	v_mfma_f32_16x16x32_bf16 v[116:119], v[168:171], v[184:187], v[116:119]
	v_mfma_f32_16x16x32_bf16 v[112:115], v[176:179], v[184:187], v[112:115]
	v_mfma_f32_16x16x32_bf16 v[100:103], v[168:171], v[192:195], v[100:103]
	v_mfma_f32_16x16x32_bf16 v[96:99], v[176:179], v[192:195], v[96:99]
	v_mfma_f32_16x16x32_bf16 v[84:87], v[168:171], v[200:203], v[84:87]
	v_mfma_f32_16x16x32_bf16 v[80:83], v[176:179], v[200:203], v[80:83]
	v_mfma_f32_16x16x32_bf16 v[68:71], v[168:171], v[208:211], v[68:71]
	v_mfma_f32_16x16x32_bf16 v[64:67], v[176:179], v[208:211], v[64:67]
	v_mfma_f32_16x16x32_bf16 v[116:119], v[172:175], v[188:191], v[116:119]
	v_mfma_f32_16x16x32_bf16 v[112:115], v[180:183], v[188:191], v[112:115]
	v_mfma_f32_16x16x32_bf16 v[100:103], v[172:175], v[196:199], v[100:103]
	v_mfma_f32_16x16x32_bf16 v[96:99], v[180:183], v[196:199], v[96:99]
	v_mfma_f32_16x16x32_bf16 v[84:87], v[172:175], v[204:207], v[84:87]
	v_mfma_f32_16x16x32_bf16 v[80:83], v[180:183], v[204:207], v[80:83]
	v_mfma_f32_16x16x32_bf16 v[68:71], v[172:175], v[212:215], v[68:71]
	v_mfma_f32_16x16x32_bf16 v[64:67], v[180:183], v[212:215], v[64:67]
	s_barrier
	s_setprio 0
	s_add_i32 s48, s67, s35
	v_lshl_add_u64 v[216:217], s[54:55], 0, v[130:131]
	s_mov_b32 m0, s48
	ds_read_b128 v[184:187], v153 offset:16384
	ds_read_b128 v[188:191], v153 offset:17408
	ds_read_b128 v[192:195], v153 offset:18432
	ds_read_b128 v[196:199], v153 offset:19456
	ds_read_b128 v[200:203], v153 offset:20480
	ds_read_b128 v[204:207], v153 offset:21504
	ds_read_b128 v[208:211], v153 offset:22528
	ds_read_b128 v[212:215], v153 offset:23552
	global_load_lds_dwordx4 v[216:217], off
	s_add_i32 m0, s48, 0x2000
	s_add_u32 s48, s54, 0x40000
	v_lshl_add_u64 v[220:221], s[54:55], 0, v[134:135]
	s_addc_u32 s49, s55, 0
	s_add_i32 s68, s72, s35
	global_load_lds_dwordx4 v[220:221], off
	v_lshl_add_u64 v[224:225], s[48:49], 0, v[130:131]
	s_mov_b32 m0, s68
	v_lshl_add_u64 v[226:227], s[78:79], 0, v[132:133]
	global_load_lds_dwordx4 v[224:225], off
	v_lshl_add_u64 v[224:225], s[48:49], 0, v[134:135]
	s_add_i32 m0, s68, 0x2000
	v_lshl_add_u64 v[228:229], v[226:227], 0, s[12:13]
	global_load_lds_dwordx4 v[224:225], off
	s_mov_b32 m0, s56
	v_lshl_add_u64 v[224:225], s[78:79], 0, v[128:129]
	global_load_lds_dwordx4 v[224:225], off
	s_mov_b32 m0, s57
	s_nop 0
	global_load_lds_dwordx4 v[228:229], off
	s_setprio 1
	s_waitcnt vmcnt(8) lgkmcnt(0)
	s_barrier
	v_mfma_f32_16x16x32_bf16 v[60:63], v[144:147], v[184:187], v[60:63]
	v_mfma_f32_16x16x32_bf16 v[56:59], v[160:163], v[184:187], v[56:59]
	v_mfma_f32_16x16x32_bf16 v[44:47], v[144:147], v[192:195], v[44:47]
	v_mfma_f32_16x16x32_bf16 v[40:43], v[160:163], v[192:195], v[40:43]
	v_mfma_f32_16x16x32_bf16 v[28:31], v[144:147], v[200:203], v[28:31]
	v_mfma_f32_16x16x32_bf16 v[24:27], v[160:163], v[200:203], v[24:27]
	v_mfma_f32_16x16x32_bf16 v[12:15], v[144:147], v[208:211], v[12:15]
	v_mfma_f32_16x16x32_bf16 v[8:11], v[160:163], v[208:211], v[8:11]
	v_mfma_f32_16x16x32_bf16 v[60:63], v[156:159], v[188:191], v[60:63]
	v_mfma_f32_16x16x32_bf16 v[56:59], v[164:167], v[188:191], v[56:59]
	v_mfma_f32_16x16x32_bf16 v[44:47], v[156:159], v[196:199], v[44:47]
	v_mfma_f32_16x16x32_bf16 v[40:43], v[164:167], v[196:199], v[40:43]
	v_mfma_f32_16x16x32_bf16 v[28:31], v[156:159], v[204:207], v[28:31]
	v_mfma_f32_16x16x32_bf16 v[24:27], v[164:167], v[204:207], v[24:27]
	v_mfma_f32_16x16x32_bf16 v[12:15], v[156:159], v[212:215], v[12:15]
	v_mfma_f32_16x16x32_bf16 v[8:11], v[164:167], v[212:215], v[8:11]
	v_mfma_f32_16x16x32_bf16 v[52:55], v[168:171], v[184:187], v[52:55]
	v_mfma_f32_16x16x32_bf16 v[48:51], v[176:179], v[184:187], v[48:51]
	v_mfma_f32_16x16x32_bf16 v[36:39], v[168:171], v[192:195], v[36:39]
	v_mfma_f32_16x16x32_bf16 v[32:35], v[176:179], v[192:195], v[32:35]
	v_mfma_f32_16x16x32_bf16 v[20:23], v[168:171], v[200:203], v[20:23]
	v_mfma_f32_16x16x32_bf16 v[16:19], v[176:179], v[200:203], v[16:19]
	v_mfma_f32_16x16x32_bf16 v[4:7], v[168:171], v[208:211], v[4:7]
	v_mfma_f32_16x16x32_bf16 v[0:3], v[176:179], v[208:211], v[0:3]
	v_mfma_f32_16x16x32_bf16 v[52:55], v[172:175], v[188:191], v[52:55]
	v_mfma_f32_16x16x32_bf16 v[48:51], v[180:183], v[188:191], v[48:51]
	v_mfma_f32_16x16x32_bf16 v[36:39], v[172:175], v[196:199], v[36:39]
	v_mfma_f32_16x16x32_bf16 v[32:35], v[180:183], v[196:199], v[32:35]
	v_mfma_f32_16x16x32_bf16 v[20:23], v[172:175], v[204:207], v[20:23]
	v_mfma_f32_16x16x32_bf16 v[16:19], v[180:183], v[204:207], v[16:19]
	v_mfma_f32_16x16x32_bf16 v[4:7], v[172:175], v[212:215], v[4:7]
	v_mfma_f32_16x16x32_bf16 v[0:3], v[180:183], v[212:215], v[0:3]
	s_barrier
	s_setprio 0
	s_add_i32 s48, 0, 0x18000
	v_add_u32_e32 v155, s48, v149
	s_add_i32 s68, 0, 0x1c000
	ds_read_b128 v[144:147], v155
	ds_read_b128 v[156:159], v155 offset:1024
	ds_read_b128 v[160:163], v155 offset:2048
	ds_read_b128 v[164:167], v155 offset:3072
	v_add_u32_e32 v155, s68, v149
	ds_read_b128 v[168:171], v155
	ds_read_b128 v[172:175], v155 offset:1024
	ds_read_b128 v[176:179], v155 offset:2048
	ds_read_b128 v[180:183], v155 offset:3072
	s_mov_b32 m0, s58
	v_lshl_add_u64 v[228:229], v[224:225], 0, s[8:9]
	ds_read_b128 v[184:187], v153 offset:32768
	ds_read_b128 v[188:191], v153 offset:33792
	ds_read_b128 v[192:195], v153 offset:34816
	ds_read_b128 v[196:199], v153 offset:35840
	ds_read_b128 v[200:203], v153 offset:36864
	ds_read_b128 v[204:207], v153 offset:37888
	ds_read_b128 v[208:211], v153 offset:38912
	ds_read_b128 v[212:215], v153 offset:39936
	global_load_lds_dwordx4 v[228:229], off
	s_mov_b32 m0, s59
	v_lshl_add_u64 v[228:229], v[226:227], 0, s[14:15]
	global_load_lds_dwordx4 v[228:229], off
	s_setprio 1
	s_waitcnt vmcnt(8) lgkmcnt(0)
	s_barrier
	v_mfma_f32_16x16x32_bf16 v[124:127], v[144:147], v[184:187], v[124:127]
	v_mfma_f32_16x16x32_bf16 v[120:123], v[160:163], v[184:187], v[120:123]
	v_mfma_f32_16x16x32_bf16 v[108:111], v[144:147], v[192:195], v[108:111]
	v_mfma_f32_16x16x32_bf16 v[104:107], v[160:163], v[192:195], v[104:107]
	v_mfma_f32_16x16x32_bf16 v[92:95], v[144:147], v[200:203], v[92:95]
	v_mfma_f32_16x16x32_bf16 v[88:91], v[160:163], v[200:203], v[88:91]
	v_mfma_f32_16x16x32_bf16 v[76:79], v[144:147], v[208:211], v[76:79]
	v_mfma_f32_16x16x32_bf16 v[72:75], v[160:163], v[208:211], v[72:75]
	v_mfma_f32_16x16x32_bf16 v[124:127], v[156:159], v[188:191], v[124:127]
	v_mfma_f32_16x16x32_bf16 v[120:123], v[164:167], v[188:191], v[120:123]
	v_mfma_f32_16x16x32_bf16 v[108:111], v[156:159], v[196:199], v[108:111]
	v_mfma_f32_16x16x32_bf16 v[104:107], v[164:167], v[196:199], v[104:107]
	v_mfma_f32_16x16x32_bf16 v[92:95], v[156:159], v[204:207], v[92:95]
	v_mfma_f32_16x16x32_bf16 v[88:91], v[164:167], v[204:207], v[88:91]
	v_mfma_f32_16x16x32_bf16 v[76:79], v[156:159], v[212:215], v[76:79]
	v_mfma_f32_16x16x32_bf16 v[72:75], v[164:167], v[212:215], v[72:75]
	v_mfma_f32_16x16x32_bf16 v[116:119], v[168:171], v[184:187], v[116:119]
	v_mfma_f32_16x16x32_bf16 v[112:115], v[176:179], v[184:187], v[112:115]
	v_mfma_f32_16x16x32_bf16 v[100:103], v[168:171], v[192:195], v[100:103]
	v_mfma_f32_16x16x32_bf16 v[96:99], v[176:179], v[192:195], v[96:99]
	v_mfma_f32_16x16x32_bf16 v[84:87], v[168:171], v[200:203], v[84:87]
	v_mfma_f32_16x16x32_bf16 v[80:83], v[176:179], v[200:203], v[80:83]
	v_mfma_f32_16x16x32_bf16 v[68:71], v[168:171], v[208:211], v[68:71]
	v_mfma_f32_16x16x32_bf16 v[64:67], v[176:179], v[208:211], v[64:67]
	v_mfma_f32_16x16x32_bf16 v[116:119], v[172:175], v[188:191], v[116:119]
	v_mfma_f32_16x16x32_bf16 v[112:115], v[180:183], v[188:191], v[112:115]
	v_mfma_f32_16x16x32_bf16 v[100:103], v[172:175], v[196:199], v[100:103]
	v_mfma_f32_16x16x32_bf16 v[96:99], v[180:183], v[196:199], v[96:99]
	v_mfma_f32_16x16x32_bf16 v[84:87], v[172:175], v[204:207], v[84:87]
	v_mfma_f32_16x16x32_bf16 v[80:83], v[180:183], v[204:207], v[80:83]
	v_mfma_f32_16x16x32_bf16 v[68:71], v[172:175], v[212:215], v[68:71]
	v_mfma_f32_16x16x32_bf16 v[64:67], v[180:183], v[212:215], v[64:67]
	s_barrier
	s_setprio 0
	s_add_i32 s48, s48, s35
	v_lshl_add_u64 v[216:217], v[216:217], 0, s[24:25]
	s_mov_b32 m0, s48
	ds_read_b128 v[184:187], v153 offset:49152
	ds_read_b128 v[188:191], v153 offset:50176
	ds_read_b128 v[192:195], v153 offset:51200
	ds_read_b128 v[196:199], v153 offset:52224
	ds_read_b128 v[200:203], v153 offset:53248
	ds_read_b128 v[204:207], v153 offset:54272
	ds_read_b128 v[208:211], v153 offset:55296
	ds_read_b128 v[212:215], v153 offset:56320
	global_load_lds_dwordx4 v[216:217], off
	s_add_i32 m0, s48, 0x2000
	s_add_u32 s48, s54, 0x40080
	v_lshl_add_u64 v[216:217], v[220:221], 0, s[24:25]
	s_addc_u32 s49, s55, 0
	s_add_i32 s54, s68, s35
	global_load_lds_dwordx4 v[216:217], off
	s_mov_b32 m0, s54
	v_lshl_add_u64 v[216:217], s[48:49], 0, v[130:131]
	global_load_lds_dwordx4 v[216:217], off
	s_add_i32 m0, s54, 0x2000
	v_lshl_add_u64 v[216:217], s[48:49], 0, v[134:135]
	global_load_lds_dwordx4 v[216:217], off
	s_mov_b32 m0, s61
	v_lshl_add_u64 v[216:217], v[224:225], 0, s[24:25]
	global_load_lds_dwordx4 v[216:217], off
	s_mov_b32 m0, s62
	v_lshl_add_u64 v[216:217], v[226:227], 0, s[36:37]
	global_load_lds_dwordx4 v[216:217], off
	s_add_i32 s76, s76, 2
	s_add_u32 s51, s51, 0x100
	s_addc_u32 s75, s75, 0
	s_cmp_gt_u32 s76, 13
	s_mov_b64 s[48:49], s[52:53]
	s_setprio 1
	s_waitcnt vmcnt(8) lgkmcnt(0)
	s_barrier
	v_mfma_f32_16x16x32_bf16 v[60:63], v[144:147], v[184:187], v[60:63]
	v_mfma_f32_16x16x32_bf16 v[56:59], v[160:163], v[184:187], v[56:59]
	v_mfma_f32_16x16x32_bf16 v[44:47], v[144:147], v[192:195], v[44:47]
	v_mfma_f32_16x16x32_bf16 v[40:43], v[160:163], v[192:195], v[40:43]
	v_mfma_f32_16x16x32_bf16 v[28:31], v[144:147], v[200:203], v[28:31]
	v_mfma_f32_16x16x32_bf16 v[24:27], v[160:163], v[200:203], v[24:27]
	v_mfma_f32_16x16x32_bf16 v[12:15], v[144:147], v[208:211], v[12:15]
	v_mfma_f32_16x16x32_bf16 v[8:11], v[160:163], v[208:211], v[8:11]
	v_mfma_f32_16x16x32_bf16 v[60:63], v[156:159], v[188:191], v[60:63]
	v_mfma_f32_16x16x32_bf16 v[56:59], v[164:167], v[188:191], v[56:59]
	v_mfma_f32_16x16x32_bf16 v[44:47], v[156:159], v[196:199], v[44:47]
	v_mfma_f32_16x16x32_bf16 v[40:43], v[164:167], v[196:199], v[40:43]
	v_mfma_f32_16x16x32_bf16 v[28:31], v[156:159], v[204:207], v[28:31]
	v_mfma_f32_16x16x32_bf16 v[24:27], v[164:167], v[204:207], v[24:27]
	v_mfma_f32_16x16x32_bf16 v[12:15], v[156:159], v[212:215], v[12:15]
	v_mfma_f32_16x16x32_bf16 v[8:11], v[164:167], v[212:215], v[8:11]
	v_mfma_f32_16x16x32_bf16 v[52:55], v[168:171], v[184:187], v[52:55]
	v_mfma_f32_16x16x32_bf16 v[48:51], v[176:179], v[184:187], v[48:51]
	v_mfma_f32_16x16x32_bf16 v[36:39], v[168:171], v[192:195], v[36:39]
	v_mfma_f32_16x16x32_bf16 v[32:35], v[176:179], v[192:195], v[32:35]
	v_mfma_f32_16x16x32_bf16 v[20:23], v[168:171], v[200:203], v[20:23]
	v_mfma_f32_16x16x32_bf16 v[16:19], v[176:179], v[200:203], v[16:19]
	v_mfma_f32_16x16x32_bf16 v[4:7], v[168:171], v[208:211], v[4:7]
	v_mfma_f32_16x16x32_bf16 v[0:3], v[176:179], v[208:211], v[0:3]
	v_mfma_f32_16x16x32_bf16 v[52:55], v[172:175], v[188:191], v[52:55]
	v_mfma_f32_16x16x32_bf16 v[48:51], v[180:183], v[188:191], v[48:51]
	v_mfma_f32_16x16x32_bf16 v[36:39], v[172:175], v[196:199], v[36:39]
	v_mfma_f32_16x16x32_bf16 v[32:35], v[180:183], v[196:199], v[32:35]
	v_mfma_f32_16x16x32_bf16 v[20:23], v[172:175], v[204:207], v[20:23]
	v_mfma_f32_16x16x32_bf16 v[16:19], v[180:183], v[204:207], v[16:19]
	v_mfma_f32_16x16x32_bf16 v[4:7], v[172:175], v[212:215], v[4:7]
	v_mfma_f32_16x16x32_bf16 v[0:3], v[180:183], v[212:215], v[0:3]
	s_barrier
	s_setprio 0
	s_cbranch_scc0 .LBB0_466

.LBB0_564:
	s_ashr_i32 s77, s76, 31
	s_lshl_b64 s[50:51], s[76:77], 19
	s_add_u32 s82, s49, s50
	s_addc_u32 s83, s53, s51
	s_and_b64 s[0:1], s[0:1], exec
	s_cselect_b32 s13, s83, s89
	s_cselect_b32 s77, s82, s88
	v_lshl_add_u64 v[92:93], s[84:85], 0, v[168:169]
	s_add_u32 vcc_lo, s88, 0x100
	v_lshl_add_u64 v[130:131], v[92:93], 0, s[86:87]
	s_addc_u32 vcc_hi, s89, 0
	s_mov_b32 s50, -2
	s_mov_b64 s[0:1], 0
	s_waitcnt vmcnt(0)
	ds_read_b128 v[132:135], v207
	ds_read_b128 v[136:139], v207 offset:1024
	ds_read_b128 v[140:143], v207 offset:2048
	ds_read_b128 v[144:147], v207 offset:3072
	ds_read_b128 v[148:151], v208
	ds_read_b128 v[152:155], v208 offset:1024
	ds_read_b128 v[156:159], v208 offset:2048
	ds_read_b128 v[174:177], v208 offset:3072
	s_add_u32 s51, s84, s0
	s_addc_u32 s68, s85, s1
	s_add_u32 s51, s51, 0x100
	s_addc_u32 s68, s68, 0
	s_add_u32 s69, vcc_lo, s0
	s_addc_u32 s70, vcc_hi, s1
	s_cmpk_eq_i32 s0, 0x700
	s_cselect_b32 s91, s79, s68
	s_cselect_b32 s90, s78, s51
	s_cselect_b32 s51, s81, s87
	s_cselect_b32 s71, s80, s86
	s_cselect_b32 s89, s13, s70
	s_cselect_b32 s88, s77, s69
	v_lshl_add_u64 v[160:161], v[92:93], 0, s[0:1]
	s_add_i32 m0, s59, 0xc000
	ds_read_b128 v[194:197], v209
	ds_read_b128 v[198:201], v209 offset:1024
	ds_read_b128 v[212:215], v209 offset:2048
	ds_read_b128 v[224:227], v209 offset:3072
	ds_read_b128 v[228:231], v209 offset:4096
	ds_read_b128 v[232:235], v209 offset:5120
	ds_read_b128 v[236:239], v209 offset:6144
	ds_read_b128 v[240:243], v209 offset:7168
	global_load_lds_dwordx4 v[160:161], off
	s_add_i32 m0, s59, 0xe000
	v_lshl_add_u64 v[160:161], v[130:131], 0, s[0:1]
	global_load_lds_dwordx4 v[160:161], off
	s_setprio 1
	s_waitcnt vmcnt(8) lgkmcnt(0)
	s_barrier
	v_mfma_f32_16x16x32_bf16 v[126:129], v[132:135], v[194:197], 0
	v_mfma_f32_16x16x32_bf16 v[60:63], v[140:143], v[194:197], 0
	v_mfma_f32_16x16x32_bf16 v[118:121], v[132:135], v[212:215], 0
	v_mfma_f32_16x16x32_bf16 v[52:55], v[140:143], v[212:215], 0
	v_mfma_f32_16x16x32_bf16 v[110:113], v[132:135], v[228:231], 0
	v_mfma_f32_16x16x32_bf16 v[44:47], v[140:143], v[228:231], 0
	v_mfma_f32_16x16x32_bf16 v[94:97], v[132:135], v[236:239], 0
	v_mfma_f32_16x16x32_bf16 v[28:31], v[140:143], v[236:239], 0
	v_mfma_f32_16x16x32_bf16 v[126:129], v[136:139], v[198:201], v[126:129]
	v_mfma_f32_16x16x32_bf16 v[60:63], v[144:147], v[198:201], v[60:63]
	v_mfma_f32_16x16x32_bf16 v[118:121], v[136:139], v[224:227], v[118:121]
	v_mfma_f32_16x16x32_bf16 v[52:55], v[144:147], v[224:227], v[52:55]
	v_mfma_f32_16x16x32_bf16 v[110:113], v[136:139], v[232:235], v[110:113]
	v_mfma_f32_16x16x32_bf16 v[44:47], v[144:147], v[232:235], v[44:47]
	v_mfma_f32_16x16x32_bf16 v[94:97], v[136:139], v[240:243], v[94:97]
	v_mfma_f32_16x16x32_bf16 v[28:31], v[144:147], v[240:243], v[28:31]
	v_mfma_f32_16x16x32_bf16 v[122:125], v[148:151], v[194:197], 0
	v_mfma_f32_16x16x32_bf16 v[56:59], v[156:159], v[194:197], 0
	v_mfma_f32_16x16x32_bf16 v[114:117], v[148:151], v[212:215], 0
	v_mfma_f32_16x16x32_bf16 v[48:51], v[156:159], v[212:215], 0
	v_mfma_f32_16x16x32_bf16 v[102:105], v[148:151], v[228:231], 0
	v_mfma_f32_16x16x32_bf16 v[36:39], v[156:159], v[228:231], 0
	v_mfma_f32_16x16x32_bf16 v[88:91], v[148:151], v[236:239], 0
	v_mfma_f32_16x16x32_bf16 v[24:27], v[156:159], v[236:239], 0
	v_mfma_f32_16x16x32_bf16 v[122:125], v[152:155], v[198:201], v[122:125]
	v_mfma_f32_16x16x32_bf16 v[56:59], v[174:177], v[198:201], v[56:59]
	v_mfma_f32_16x16x32_bf16 v[114:117], v[152:155], v[224:227], v[114:117]
	v_mfma_f32_16x16x32_bf16 v[48:51], v[174:177], v[224:227], v[48:51]
	v_mfma_f32_16x16x32_bf16 v[102:105], v[152:155], v[232:235], v[102:105]
	v_mfma_f32_16x16x32_bf16 v[36:39], v[174:177], v[232:235], v[36:39]
	v_mfma_f32_16x16x32_bf16 v[88:91], v[152:155], v[240:243], v[88:91]
	v_mfma_f32_16x16x32_bf16 v[24:27], v[174:177], v[240:243], v[24:27]
	s_barrier
	s_setprio 0
	s_add_i32 s68, s95, s57
	v_lshl_add_u64 v[160:161], s[88:89], 0, v[164:165]
	s_mov_b32 m0, s68
	ds_read_b128 v[194:197], v209 offset:16384
	ds_read_b128 v[198:201], v209 offset:17408
	ds_read_b128 v[212:215], v209 offset:18432
	ds_read_b128 v[224:227], v209 offset:19456
	ds_read_b128 v[228:231], v209 offset:20480
	ds_read_b128 v[232:235], v209 offset:21504
	ds_read_b128 v[236:239], v209 offset:22528
	ds_read_b128 v[240:243], v209 offset:23552
	global_load_lds_dwordx4 v[160:161], off
	s_add_i32 m0, s68, 0x2000
	s_add_u32 s68, s88, 0x40000
	v_lshl_add_u64 v[216:217], s[88:89], 0, v[166:167]
	s_addc_u32 s69, s89, 0
	s_add_i32 s70, s96, s57
	global_load_lds_dwordx4 v[216:217], off
	s_mov_b32 m0, s70
	v_lshl_add_u64 v[220:221], s[68:69], 0, v[164:165]
	global_load_lds_dwordx4 v[220:221], off
	s_add_i32 m0, s70, 0x2000
	v_lshl_add_u64 v[220:221], s[68:69], 0, v[166:167]
	s_add_u32 s68, s90, s71
	global_load_lds_dwordx4 v[220:221], off
	v_lshl_add_u64 v[220:221], s[90:91], 0, v[162:163]
	s_mov_b32 m0, s59
	s_addc_u32 s69, s91, s51
	global_load_lds_dwordx4 v[220:221], off
	s_mov_b32 m0, s61
	v_lshl_add_u64 v[244:245], s[68:69], 0, v[162:163]
	global_load_lds_dwordx4 v[244:245], off
	s_setprio 1
	s_waitcnt vmcnt(8) lgkmcnt(0)
	s_barrier
	v_mfma_f32_16x16x32_bf16 v[84:87], v[132:135], v[194:197], 0
	v_mfma_f32_16x16x32_bf16 v[20:23], v[140:143], v[194:197], 0
	v_mfma_f32_16x16x32_bf16 v[76:79], v[132:135], v[212:215], 0
	v_mfma_f32_16x16x32_bf16 v[12:15], v[140:143], v[212:215], 0
	v_mfma_f32_16x16x32_bf16 v[68:71], v[132:135], v[228:231], 0
	v_mfma_f32_16x16x32_bf16 v[4:7], v[140:143], v[228:231], 0
	v_mfma_f32_16x16x32_bf16 v[106:109], v[132:135], v[236:239], 0
	v_mfma_f32_16x16x32_bf16 v[40:43], v[140:143], v[236:239], 0
	v_mfma_f32_16x16x32_bf16 v[84:87], v[136:139], v[198:201], v[84:87]
	v_mfma_f32_16x16x32_bf16 v[20:23], v[144:147], v[198:201], v[20:23]
	v_mfma_f32_16x16x32_bf16 v[76:79], v[136:139], v[224:227], v[76:79]
	v_mfma_f32_16x16x32_bf16 v[12:15], v[144:147], v[224:227], v[12:15]
	v_mfma_f32_16x16x32_bf16 v[68:71], v[136:139], v[232:235], v[68:71]
	v_mfma_f32_16x16x32_bf16 v[4:7], v[144:147], v[232:235], v[4:7]
	v_mfma_f32_16x16x32_bf16 v[106:109], v[136:139], v[240:243], v[106:109]
	v_mfma_f32_16x16x32_bf16 v[40:43], v[144:147], v[240:243], v[40:43]
	v_mfma_f32_16x16x32_bf16 v[80:83], v[148:151], v[194:197], 0
	v_mfma_f32_16x16x32_bf16 v[16:19], v[156:159], v[194:197], 0
	v_mfma_f32_16x16x32_bf16 v[72:75], v[148:151], v[212:215], 0
	v_mfma_f32_16x16x32_bf16 v[8:11], v[156:159], v[212:215], 0
	v_mfma_f32_16x16x32_bf16 v[64:67], v[148:151], v[228:231], 0
	v_mfma_f32_16x16x32_bf16 v[0:3], v[156:159], v[228:231], 0
	v_mfma_f32_16x16x32_bf16 v[98:101], v[148:151], v[236:239], 0
	v_mfma_f32_16x16x32_bf16 v[32:35], v[156:159], v[236:239], 0
	v_mfma_f32_16x16x32_bf16 v[80:83], v[152:155], v[198:201], v[80:83]
	v_mfma_f32_16x16x32_bf16 v[16:19], v[174:177], v[198:201], v[16:19]
	v_mfma_f32_16x16x32_bf16 v[72:75], v[152:155], v[224:227], v[72:75]
	v_mfma_f32_16x16x32_bf16 v[8:11], v[174:177], v[224:227], v[8:11]
	v_mfma_f32_16x16x32_bf16 v[64:67], v[152:155], v[232:235], v[64:67]
	v_mfma_f32_16x16x32_bf16 v[0:3], v[174:177], v[232:235], v[0:3]
	v_mfma_f32_16x16x32_bf16 v[98:101], v[152:155], v[240:243], v[98:101]
	v_mfma_f32_16x16x32_bf16 v[32:35], v[174:177], v[240:243], v[32:35]
	s_barrier
	s_setprio 0
	s_add_i32 s70, 0, 0x18000
	s_add_i32 s14, 0, 0x1c000
	v_add_u32_e32 v144, s70, v203
	v_add_u32_e32 v174, s14, v203
	ds_read_b128 v[132:135], v144
	ds_read_b128 v[136:139], v144 offset:1024
	ds_read_b128 v[140:143], v144 offset:2048
	ds_read_b128 v[144:147], v144 offset:3072
	ds_read_b128 v[148:151], v174
	ds_read_b128 v[152:155], v174 offset:1024
	ds_read_b128 v[156:159], v174 offset:2048
	ds_read_b128 v[174:177], v174 offset:3072
	s_add_u32 s68, s90, 0x2000
	s_addc_u32 s69, s91, 0
	v_lshl_add_u64 v[246:247], s[68:69], 0, v[162:163]
	s_add_u32 s68, s68, s71
	s_mov_b32 m0, s63
	s_addc_u32 s69, s69, s51
	ds_read_b128 v[194:197], v209 offset:32768
	ds_read_b128 v[198:201], v209 offset:33792
	ds_read_b128 v[212:215], v209 offset:34816
	ds_read_b128 v[224:227], v209 offset:35840
	ds_read_b128 v[228:231], v209 offset:36864
	ds_read_b128 v[232:235], v209 offset:37888
	ds_read_b128 v[236:239], v209 offset:38912
	ds_read_b128 v[240:243], v209 offset:39936
	global_load_lds_dwordx4 v[246:247], off
	s_mov_b32 m0, s67
	v_lshl_add_u64 v[246:247], s[68:69], 0, v[162:163]
	global_load_lds_dwordx4 v[246:247], off
	s_setprio 1
	s_waitcnt vmcnt(8) lgkmcnt(0)
	s_barrier
	v_mfma_f32_16x16x32_bf16 v[126:129], v[132:135], v[194:197], v[126:129]
	v_mfma_f32_16x16x32_bf16 v[60:63], v[140:143], v[194:197], v[60:63]
	v_mfma_f32_16x16x32_bf16 v[118:121], v[132:135], v[212:215], v[118:121]
	v_mfma_f32_16x16x32_bf16 v[52:55], v[140:143], v[212:215], v[52:55]
	v_mfma_f32_16x16x32_bf16 v[110:113], v[132:135], v[228:231], v[110:113]
	v_mfma_f32_16x16x32_bf16 v[44:47], v[140:143], v[228:231], v[44:47]
	v_mfma_f32_16x16x32_bf16 v[94:97], v[132:135], v[236:239], v[94:97]
	v_mfma_f32_16x16x32_bf16 v[28:31], v[140:143], v[236:239], v[28:31]
	v_mfma_f32_16x16x32_bf16 v[126:129], v[136:139], v[198:201], v[126:129]
	v_mfma_f32_16x16x32_bf16 v[60:63], v[144:147], v[198:201], v[60:63]
	v_mfma_f32_16x16x32_bf16 v[118:121], v[136:139], v[224:227], v[118:121]
	v_mfma_f32_16x16x32_bf16 v[52:55], v[144:147], v[224:227], v[52:55]
	v_mfma_f32_16x16x32_bf16 v[110:113], v[136:139], v[232:235], v[110:113]
	v_mfma_f32_16x16x32_bf16 v[44:47], v[144:147], v[232:235], v[44:47]
	v_mfma_f32_16x16x32_bf16 v[94:97], v[136:139], v[240:243], v[94:97]
	v_mfma_f32_16x16x32_bf16 v[28:31], v[144:147], v[240:243], v[28:31]
	v_mfma_f32_16x16x32_bf16 v[122:125], v[148:151], v[194:197], v[122:125]
	v_mfma_f32_16x16x32_bf16 v[56:59], v[156:159], v[194:197], v[56:59]
	v_mfma_f32_16x16x32_bf16 v[114:117], v[148:151], v[212:215], v[114:117]
	v_mfma_f32_16x16x32_bf16 v[48:51], v[156:159], v[212:215], v[48:51]
	v_mfma_f32_16x16x32_bf16 v[102:105], v[148:151], v[228:231], v[102:105]
	v_mfma_f32_16x16x32_bf16 v[36:39], v[156:159], v[228:231], v[36:39]
	v_mfma_f32_16x16x32_bf16 v[88:91], v[148:151], v[236:239], v[88:91]
	v_mfma_f32_16x16x32_bf16 v[24:27], v[156:159], v[236:239], v[24:27]
	v_mfma_f32_16x16x32_bf16 v[122:125], v[152:155], v[198:201], v[122:125]
	v_mfma_f32_16x16x32_bf16 v[56:59], v[174:177], v[198:201], v[56:59]
	v_mfma_f32_16x16x32_bf16 v[114:117], v[152:155], v[224:227], v[114:117]
	v_mfma_f32_16x16x32_bf16 v[48:51], v[174:177], v[224:227], v[48:51]
	v_mfma_f32_16x16x32_bf16 v[102:105], v[152:155], v[232:235], v[102:105]
	v_mfma_f32_16x16x32_bf16 v[36:39], v[174:177], v[232:235], v[36:39]
	v_mfma_f32_16x16x32_bf16 v[88:91], v[152:155], v[240:243], v[88:91]
	v_mfma_f32_16x16x32_bf16 v[24:27], v[174:177], v[240:243], v[24:27]
	s_barrier
	s_setprio 0
	s_add_i32 s15, s70, s57
	v_lshl_add_u64 v[160:161], v[160:161], 0, s[22:23]
	s_mov_b32 m0, s15
	ds_read_b128 v[194:197], v209 offset:49152
	ds_read_b128 v[198:201], v209 offset:50176
	ds_read_b128 v[212:215], v209 offset:51200
	ds_read_b128 v[224:227], v209 offset:52224
	ds_read_b128 v[228:231], v209 offset:53248
	ds_read_b128 v[232:235], v209 offset:54272
	ds_read_b128 v[236:239], v209 offset:55296
	ds_read_b128 v[240:243], v209 offset:56320
	global_load_lds_dwordx4 v[160:161], off
	s_add_i32 m0, s15, 0x2000
	s_add_u32 s68, s88, 0x40080
	v_lshl_add_u64 v[160:161], v[216:217], 0, s[22:23]
	s_addc_u32 s69, s89, 0
	s_add_i32 s14, s14, s57
	global_load_lds_dwordx4 v[160:161], off
	s_mov_b32 m0, s14
	v_lshl_add_u64 v[160:161], s[68:69], 0, v[164:165]
	global_load_lds_dwordx4 v[160:161], off
	s_add_i32 m0, s14, 0x2000
	v_lshl_add_u64 v[160:161], s[68:69], 0, v[166:167]
	global_load_lds_dwordx4 v[160:161], off
	s_mov_b32 m0, s75
	v_lshl_add_u64 v[160:161], v[220:221], 0, s[22:23]
	global_load_lds_dwordx4 v[160:161], off
	s_mov_b32 m0, s92
	v_lshl_add_u64 v[160:161], v[244:245], 0, s[22:23]
	global_load_lds_dwordx4 v[160:161], off
	s_add_i32 s50, s50, 2
	s_add_u32 s0, s0, 0x100
	s_addc_u32 s1, s1, 0
	s_cmp_gt_u32 s50, 13
	s_setprio 1
	s_waitcnt vmcnt(8) lgkmcnt(0)
	s_barrier
	v_mfma_f32_16x16x32_bf16 v[84:87], v[132:135], v[194:197], v[84:87]
	v_mfma_f32_16x16x32_bf16 v[20:23], v[140:143], v[194:197], v[20:23]
	v_mfma_f32_16x16x32_bf16 v[76:79], v[132:135], v[212:215], v[76:79]
	v_mfma_f32_16x16x32_bf16 v[12:15], v[140:143], v[212:215], v[12:15]
	v_mfma_f32_16x16x32_bf16 v[68:71], v[132:135], v[228:231], v[68:71]
	v_mfma_f32_16x16x32_bf16 v[4:7], v[140:143], v[228:231], v[4:7]
	v_mfma_f32_16x16x32_bf16 v[106:109], v[132:135], v[236:239], v[106:109]
	v_mfma_f32_16x16x32_bf16 v[40:43], v[140:143], v[236:239], v[40:43]
	v_mfma_f32_16x16x32_bf16 v[84:87], v[136:139], v[198:201], v[84:87]
	v_mfma_f32_16x16x32_bf16 v[20:23], v[144:147], v[198:201], v[20:23]
	v_mfma_f32_16x16x32_bf16 v[76:79], v[136:139], v[224:227], v[76:79]
	v_mfma_f32_16x16x32_bf16 v[12:15], v[144:147], v[224:227], v[12:15]
	v_mfma_f32_16x16x32_bf16 v[68:71], v[136:139], v[232:235], v[68:71]
	v_mfma_f32_16x16x32_bf16 v[4:7], v[144:147], v[232:235], v[4:7]
	v_mfma_f32_16x16x32_bf16 v[106:109], v[136:139], v[240:243], v[106:109]
	v_mfma_f32_16x16x32_bf16 v[40:43], v[144:147], v[240:243], v[40:43]
	v_mfma_f32_16x16x32_bf16 v[80:83], v[148:151], v[194:197], v[80:83]
	v_mfma_f32_16x16x32_bf16 v[16:19], v[156:159], v[194:197], v[16:19]
	v_mfma_f32_16x16x32_bf16 v[72:75], v[148:151], v[212:215], v[72:75]
	v_mfma_f32_16x16x32_bf16 v[8:11], v[156:159], v[212:215], v[8:11]
	v_mfma_f32_16x16x32_bf16 v[64:67], v[148:151], v[228:231], v[64:67]
	v_mfma_f32_16x16x32_bf16 v[0:3], v[156:159], v[228:231], v[0:3]
	v_mfma_f32_16x16x32_bf16 v[98:101], v[148:151], v[236:239], v[98:101]
	v_mfma_f32_16x16x32_bf16 v[32:35], v[156:159], v[236:239], v[32:35]
	v_mfma_f32_16x16x32_bf16 v[80:83], v[152:155], v[198:201], v[80:83]
	v_mfma_f32_16x16x32_bf16 v[16:19], v[174:177], v[198:201], v[16:19]
	v_mfma_f32_16x16x32_bf16 v[72:75], v[152:155], v[224:227], v[72:75]
	v_mfma_f32_16x16x32_bf16 v[8:11], v[174:177], v[224:227], v[8:11]
	v_mfma_f32_16x16x32_bf16 v[64:67], v[152:155], v[232:235], v[64:67]
	v_mfma_f32_16x16x32_bf16 v[0:3], v[174:177], v[232:235], v[0:3]
	v_mfma_f32_16x16x32_bf16 v[98:101], v[152:155], v[240:243], v[98:101]
	v_mfma_f32_16x16x32_bf16 v[32:35], v[174:177], v[240:243], v[32:35]
	s_barrier
	s_setprio 0
.LBB0_565:
	ds_read_b128 v[132:135], v207
	ds_read_b128 v[136:139], v207 offset:1024
	ds_read_b128 v[140:143], v207 offset:2048
	ds_read_b128 v[144:147], v207 offset:3072
	ds_read_b128 v[148:151], v208
	ds_read_b128 v[152:155], v208 offset:1024
	ds_read_b128 v[156:159], v208 offset:2048
	ds_read_b128 v[174:177], v208 offset:3072
	s_add_u32 s51, s84, s0
	s_addc_u32 s68, s85, s1
	s_add_u32 s51, s51, 0x100
	s_addc_u32 s68, s68, 0
	s_add_u32 s69, vcc_lo, s0
	s_addc_u32 s70, vcc_hi, s1
	s_cmpk_eq_i32 s0, 0x700
	s_cselect_b32 s91, s79, s68
	s_cselect_b32 s90, s78, s51
	s_cselect_b32 s51, s81, s87
	s_cselect_b32 s71, s80, s86
	s_cselect_b32 s89, s13, s70
	s_cselect_b32 s88, s77, s69
	v_lshl_add_u64 v[160:161], v[92:93], 0, s[0:1]
	s_add_i32 m0, s59, 0xc000
	ds_read_b128 v[194:197], v209
	ds_read_b128 v[198:201], v209 offset:1024
	ds_read_b128 v[212:215], v209 offset:2048
	ds_read_b128 v[224:227], v209 offset:3072
	ds_read_b128 v[228:231], v209 offset:4096
	ds_read_b128 v[232:235], v209 offset:5120
	ds_read_b128 v[236:239], v209 offset:6144
	ds_read_b128 v[240:243], v209 offset:7168
	global_load_lds_dwordx4 v[160:161], off
	s_add_i32 m0, s59, 0xe000
	v_lshl_add_u64 v[160:161], v[130:131], 0, s[0:1]
	global_load_lds_dwordx4 v[160:161], off
	s_setprio 1
	s_waitcnt vmcnt(8) lgkmcnt(0)
	s_barrier
	v_mfma_f32_16x16x32_bf16 v[126:129], v[132:135], v[194:197], v[126:129]
	v_mfma_f32_16x16x32_bf16 v[60:63], v[140:143], v[194:197], v[60:63]
	v_mfma_f32_16x16x32_bf16 v[118:121], v[132:135], v[212:215], v[118:121]
	v_mfma_f32_16x16x32_bf16 v[52:55], v[140:143], v[212:215], v[52:55]
	v_mfma_f32_16x16x32_bf16 v[110:113], v[132:135], v[228:231], v[110:113]
	v_mfma_f32_16x16x32_bf16 v[44:47], v[140:143], v[228:231], v[44:47]
	v_mfma_f32_16x16x32_bf16 v[94:97], v[132:135], v[236:239], v[94:97]
	v_mfma_f32_16x16x32_bf16 v[28:31], v[140:143], v[236:239], v[28:31]
	v_mfma_f32_16x16x32_bf16 v[126:129], v[136:139], v[198:201], v[126:129]
	v_mfma_f32_16x16x32_bf16 v[60:63], v[144:147], v[198:201], v[60:63]
	v_mfma_f32_16x16x32_bf16 v[118:121], v[136:139], v[224:227], v[118:121]
	v_mfma_f32_16x16x32_bf16 v[52:55], v[144:147], v[224:227], v[52:55]
	v_mfma_f32_16x16x32_bf16 v[110:113], v[136:139], v[232:235], v[110:113]
	v_mfma_f32_16x16x32_bf16 v[44:47], v[144:147], v[232:235], v[44:47]
	v_mfma_f32_16x16x32_bf16 v[94:97], v[136:139], v[240:243], v[94:97]
	v_mfma_f32_16x16x32_bf16 v[28:31], v[144:147], v[240:243], v[28:31]
	v_mfma_f32_16x16x32_bf16 v[122:125], v[148:151], v[194:197], v[122:125]
	v_mfma_f32_16x16x32_bf16 v[56:59], v[156:159], v[194:197], v[56:59]
	v_mfma_f32_16x16x32_bf16 v[114:117], v[148:151], v[212:215], v[114:117]
	v_mfma_f32_16x16x32_bf16 v[48:51], v[156:159], v[212:215], v[48:51]
	v_mfma_f32_16x16x32_bf16 v[102:105], v[148:151], v[228:231], v[102:105]
	v_mfma_f32_16x16x32_bf16 v[36:39], v[156:159], v[228:231], v[36:39]
	v_mfma_f32_16x16x32_bf16 v[88:91], v[148:151], v[236:239], v[88:91]
	v_mfma_f32_16x16x32_bf16 v[24:27], v[156:159], v[236:239], v[24:27]
	v_mfma_f32_16x16x32_bf16 v[122:125], v[152:155], v[198:201], v[122:125]
	v_mfma_f32_16x16x32_bf16 v[56:59], v[174:177], v[198:201], v[56:59]
	v_mfma_f32_16x16x32_bf16 v[114:117], v[152:155], v[224:227], v[114:117]
	v_mfma_f32_16x16x32_bf16 v[48:51], v[174:177], v[224:227], v[48:51]
	v_mfma_f32_16x16x32_bf16 v[102:105], v[152:155], v[232:235], v[102:105]
	v_mfma_f32_16x16x32_bf16 v[36:39], v[174:177], v[232:235], v[36:39]
	v_mfma_f32_16x16x32_bf16 v[88:91], v[152:155], v[240:243], v[88:91]
	v_mfma_f32_16x16x32_bf16 v[24:27], v[174:177], v[240:243], v[24:27]
	s_barrier
	s_setprio 0
	s_add_i32 s68, s95, s57
	v_lshl_add_u64 v[160:161], s[88:89], 0, v[164:165]
	s_mov_b32 m0, s68
	ds_read_b128 v[194:197], v209 offset:16384
	ds_read_b128 v[198:201], v209 offset:17408
	ds_read_b128 v[212:215], v209 offset:18432
	ds_read_b128 v[224:227], v209 offset:19456
	ds_read_b128 v[228:231], v209 offset:20480
	ds_read_b128 v[232:235], v209 offset:21504
	ds_read_b128 v[236:239], v209 offset:22528
	ds_read_b128 v[240:243], v209 offset:23552
	global_load_lds_dwordx4 v[160:161], off
	s_add_i32 m0, s68, 0x2000
	s_add_u32 s68, s88, 0x40000
	v_lshl_add_u64 v[216:217], s[88:89], 0, v[166:167]
	s_addc_u32 s69, s89, 0
	s_add_i32 s70, s96, s57
	global_load_lds_dwordx4 v[216:217], off
	s_mov_b32 m0, s70
	v_lshl_add_u64 v[220:221], s[68:69], 0, v[164:165]
	global_load_lds_dwordx4 v[220:221], off
	s_add_i32 m0, s70, 0x2000
	v_lshl_add_u64 v[220:221], s[68:69], 0, v[166:167]
	s_add_u32 s68, s90, s71
	global_load_lds_dwordx4 v[220:221], off
	v_lshl_add_u64 v[220:221], s[90:91], 0, v[162:163]
	s_mov_b32 m0, s59
	s_addc_u32 s69, s91, s51
	global_load_lds_dwordx4 v[220:221], off
	s_mov_b32 m0, s61
	v_lshl_add_u64 v[244:245], s[68:69], 0, v[162:163]
	global_load_lds_dwordx4 v[244:245], off
	s_setprio 1
	s_waitcnt vmcnt(8) lgkmcnt(0)
	s_barrier
	v_mfma_f32_16x16x32_bf16 v[84:87], v[132:135], v[194:197], v[84:87]
	v_mfma_f32_16x16x32_bf16 v[20:23], v[140:143], v[194:197], v[20:23]
	v_mfma_f32_16x16x32_bf16 v[76:79], v[132:135], v[212:215], v[76:79]
	v_mfma_f32_16x16x32_bf16 v[12:15], v[140:143], v[212:215], v[12:15]
	v_mfma_f32_16x16x32_bf16 v[68:71], v[132:135], v[228:231], v[68:71]
	v_mfma_f32_16x16x32_bf16 v[4:7], v[140:143], v[228:231], v[4:7]
	v_mfma_f32_16x16x32_bf16 v[106:109], v[132:135], v[236:239], v[106:109]
	v_mfma_f32_16x16x32_bf16 v[40:43], v[140:143], v[236:239], v[40:43]
	v_mfma_f32_16x16x32_bf16 v[84:87], v[136:139], v[198:201], v[84:87]
	v_mfma_f32_16x16x32_bf16 v[20:23], v[144:147], v[198:201], v[20:23]
	v_mfma_f32_16x16x32_bf16 v[76:79], v[136:139], v[224:227], v[76:79]
	v_mfma_f32_16x16x32_bf16 v[12:15], v[144:147], v[224:227], v[12:15]
	v_mfma_f32_16x16x32_bf16 v[68:71], v[136:139], v[232:235], v[68:71]
	v_mfma_f32_16x16x32_bf16 v[4:7], v[144:147], v[232:235], v[4:7]
	v_mfma_f32_16x16x32_bf16 v[106:109], v[136:139], v[240:243], v[106:109]
	v_mfma_f32_16x16x32_bf16 v[40:43], v[144:147], v[240:243], v[40:43]
	v_mfma_f32_16x16x32_bf16 v[80:83], v[148:151], v[194:197], v[80:83]
	v_mfma_f32_16x16x32_bf16 v[16:19], v[156:159], v[194:197], v[16:19]
	v_mfma_f32_16x16x32_bf16 v[72:75], v[148:151], v[212:215], v[72:75]
	v_mfma_f32_16x16x32_bf16 v[8:11], v[156:159], v[212:215], v[8:11]
	v_mfma_f32_16x16x32_bf16 v[64:67], v[148:151], v[228:231], v[64:67]
	v_mfma_f32_16x16x32_bf16 v[0:3], v[156:159], v[228:231], v[0:3]
	v_mfma_f32_16x16x32_bf16 v[98:101], v[148:151], v[236:239], v[98:101]
	v_mfma_f32_16x16x32_bf16 v[32:35], v[156:159], v[236:239], v[32:35]
	v_mfma_f32_16x16x32_bf16 v[80:83], v[152:155], v[198:201], v[80:83]
	v_mfma_f32_16x16x32_bf16 v[16:19], v[174:177], v[198:201], v[16:19]
	v_mfma_f32_16x16x32_bf16 v[72:75], v[152:155], v[224:227], v[72:75]
	v_mfma_f32_16x16x32_bf16 v[8:11], v[174:177], v[224:227], v[8:11]
	v_mfma_f32_16x16x32_bf16 v[64:67], v[152:155], v[232:235], v[64:67]
	v_mfma_f32_16x16x32_bf16 v[0:3], v[174:177], v[232:235], v[0:3]
	v_mfma_f32_16x16x32_bf16 v[98:101], v[152:155], v[240:243], v[98:101]
	v_mfma_f32_16x16x32_bf16 v[32:35], v[174:177], v[240:243], v[32:35]
	s_barrier
	s_setprio 0
	s_add_i32 s70, 0, 0x18000
	s_add_i32 s14, 0, 0x1c000
	v_add_u32_e32 v144, s70, v203
	v_add_u32_e32 v174, s14, v203
	ds_read_b128 v[132:135], v144
	ds_read_b128 v[136:139], v144 offset:1024
	ds_read_b128 v[140:143], v144 offset:2048
	ds_read_b128 v[144:147], v144 offset:3072
	ds_read_b128 v[148:151], v174
	ds_read_b128 v[152:155], v174 offset:1024
	ds_read_b128 v[156:159], v174 offset:2048
	ds_read_b128 v[174:177], v174 offset:3072
	s_add_u32 s68, s90, 0x2000
	s_addc_u32 s69, s91, 0
	v_lshl_add_u64 v[246:247], s[68:69], 0, v[162:163]
	s_add_u32 s68, s68, s71
	s_mov_b32 m0, s63
	s_addc_u32 s69, s69, s51
	ds_read_b128 v[194:197], v209 offset:32768
	ds_read_b128 v[198:201], v209 offset:33792
	ds_read_b128 v[212:215], v209 offset:34816
	ds_read_b128 v[224:227], v209 offset:35840
	ds_read_b128 v[228:231], v209 offset:36864
	ds_read_b128 v[232:235], v209 offset:37888
	ds_read_b128 v[236:239], v209 offset:38912
	ds_read_b128 v[240:243], v209 offset:39936
	global_load_lds_dwordx4 v[246:247], off
	s_mov_b32 m0, s67
	v_lshl_add_u64 v[246:247], s[68:69], 0, v[162:163]
	global_load_lds_dwordx4 v[246:247], off
	s_setprio 1
	s_waitcnt vmcnt(8) lgkmcnt(0)
	s_barrier
	v_mfma_f32_16x16x32_bf16 v[126:129], v[132:135], v[194:197], v[126:129]
	v_mfma_f32_16x16x32_bf16 v[60:63], v[140:143], v[194:197], v[60:63]
	v_mfma_f32_16x16x32_bf16 v[118:121], v[132:135], v[212:215], v[118:121]
	v_mfma_f32_16x16x32_bf16 v[52:55], v[140:143], v[212:215], v[52:55]
	v_mfma_f32_16x16x32_bf16 v[110:113], v[132:135], v[228:231], v[110:113]
	v_mfma_f32_16x16x32_bf16 v[44:47], v[140:143], v[228:231], v[44:47]
	v_mfma_f32_16x16x32_bf16 v[94:97], v[132:135], v[236:239], v[94:97]
	v_mfma_f32_16x16x32_bf16 v[28:31], v[140:143], v[236:239], v[28:31]
	v_mfma_f32_16x16x32_bf16 v[126:129], v[136:139], v[198:201], v[126:129]
	v_mfma_f32_16x16x32_bf16 v[60:63], v[144:147], v[198:201], v[60:63]
	v_mfma_f32_16x16x32_bf16 v[118:121], v[136:139], v[224:227], v[118:121]
	v_mfma_f32_16x16x32_bf16 v[52:55], v[144:147], v[224:227], v[52:55]
	v_mfma_f32_16x16x32_bf16 v[110:113], v[136:139], v[232:235], v[110:113]
	v_mfma_f32_16x16x32_bf16 v[44:47], v[144:147], v[232:235], v[44:47]
	v_mfma_f32_16x16x32_bf16 v[94:97], v[136:139], v[240:243], v[94:97]
	v_mfma_f32_16x16x32_bf16 v[28:31], v[144:147], v[240:243], v[28:31]
	v_mfma_f32_16x16x32_bf16 v[122:125], v[148:151], v[194:197], v[122:125]
	v_mfma_f32_16x16x32_bf16 v[56:59], v[156:159], v[194:197], v[56:59]
	v_mfma_f32_16x16x32_bf16 v[114:117], v[148:151], v[212:215], v[114:117]
	v_mfma_f32_16x16x32_bf16 v[48:51], v[156:159], v[212:215], v[48:51]
	v_mfma_f32_16x16x32_bf16 v[102:105], v[148:151], v[228:231], v[102:105]
	v_mfma_f32_16x16x32_bf16 v[36:39], v[156:159], v[228:231], v[36:39]
	v_mfma_f32_16x16x32_bf16 v[88:91], v[148:151], v[236:239], v[88:91]
	v_mfma_f32_16x16x32_bf16 v[24:27], v[156:159], v[236:239], v[24:27]
	v_mfma_f32_16x16x32_bf16 v[122:125], v[152:155], v[198:201], v[122:125]
	v_mfma_f32_16x16x32_bf16 v[56:59], v[174:177], v[198:201], v[56:59]
	v_mfma_f32_16x16x32_bf16 v[114:117], v[152:155], v[224:227], v[114:117]
	v_mfma_f32_16x16x32_bf16 v[48:51], v[174:177], v[224:227], v[48:51]
	v_mfma_f32_16x16x32_bf16 v[102:105], v[152:155], v[232:235], v[102:105]
	v_mfma_f32_16x16x32_bf16 v[36:39], v[174:177], v[232:235], v[36:39]
	v_mfma_f32_16x16x32_bf16 v[88:91], v[152:155], v[240:243], v[88:91]
	v_mfma_f32_16x16x32_bf16 v[24:27], v[174:177], v[240:243], v[24:27]
	s_barrier
	s_setprio 0
	s_add_i32 s15, s70, s57
	v_lshl_add_u64 v[160:161], v[160:161], 0, s[22:23]
	s_mov_b32 m0, s15
	ds_read_b128 v[194:197], v209 offset:49152
	ds_read_b128 v[198:201], v209 offset:50176
	ds_read_b128 v[212:215], v209 offset:51200
	ds_read_b128 v[224:227], v209 offset:52224
	ds_read_b128 v[228:231], v209 offset:53248
	ds_read_b128 v[232:235], v209 offset:54272
	ds_read_b128 v[236:239], v209 offset:55296
	ds_read_b128 v[240:243], v209 offset:56320
	global_load_lds_dwordx4 v[160:161], off
	s_add_i32 m0, s15, 0x2000
	s_add_u32 s68, s88, 0x40080
	v_lshl_add_u64 v[160:161], v[216:217], 0, s[22:23]
	s_addc_u32 s69, s89, 0
	s_add_i32 s14, s14, s57
	global_load_lds_dwordx4 v[160:161], off
	s_mov_b32 m0, s14
	v_lshl_add_u64 v[160:161], s[68:69], 0, v[164:165]
	global_load_lds_dwordx4 v[160:161], off
	s_add_i32 m0, s14, 0x2000
	v_lshl_add_u64 v[160:161], s[68:69], 0, v[166:167]
	global_load_lds_dwordx4 v[160:161], off
	s_mov_b32 m0, s75
	v_lshl_add_u64 v[160:161], v[220:221], 0, s[22:23]
	global_load_lds_dwordx4 v[160:161], off
	s_mov_b32 m0, s92
	v_lshl_add_u64 v[160:161], v[244:245], 0, s[22:23]
	global_load_lds_dwordx4 v[160:161], off
	s_add_i32 s50, s50, 2
	s_add_u32 s0, s0, 0x100
	s_addc_u32 s1, s1, 0
	s_cmp_gt_u32 s50, 13
	s_setprio 1
	s_waitcnt vmcnt(8) lgkmcnt(0)
	s_barrier
	v_mfma_f32_16x16x32_bf16 v[84:87], v[132:135], v[194:197], v[84:87]
	v_mfma_f32_16x16x32_bf16 v[20:23], v[140:143], v[194:197], v[20:23]
	v_mfma_f32_16x16x32_bf16 v[76:79], v[132:135], v[212:215], v[76:79]
	v_mfma_f32_16x16x32_bf16 v[12:15], v[140:143], v[212:215], v[12:15]
	v_mfma_f32_16x16x32_bf16 v[68:71], v[132:135], v[228:231], v[68:71]
	v_mfma_f32_16x16x32_bf16 v[4:7], v[140:143], v[228:231], v[4:7]
	v_mfma_f32_16x16x32_bf16 v[106:109], v[132:135], v[236:239], v[106:109]
	v_mfma_f32_16x16x32_bf16 v[40:43], v[140:143], v[236:239], v[40:43]
	v_mfma_f32_16x16x32_bf16 v[84:87], v[136:139], v[198:201], v[84:87]
	v_mfma_f32_16x16x32_bf16 v[20:23], v[144:147], v[198:201], v[20:23]
	v_mfma_f32_16x16x32_bf16 v[76:79], v[136:139], v[224:227], v[76:79]
	v_mfma_f32_16x16x32_bf16 v[12:15], v[144:147], v[224:227], v[12:15]
	v_mfma_f32_16x16x32_bf16 v[68:71], v[136:139], v[232:235], v[68:71]
	v_mfma_f32_16x16x32_bf16 v[4:7], v[144:147], v[232:235], v[4:7]
	v_mfma_f32_16x16x32_bf16 v[106:109], v[136:139], v[240:243], v[106:109]
	v_mfma_f32_16x16x32_bf16 v[40:43], v[144:147], v[240:243], v[40:43]
	v_mfma_f32_16x16x32_bf16 v[80:83], v[148:151], v[194:197], v[80:83]
	v_mfma_f32_16x16x32_bf16 v[16:19], v[156:159], v[194:197], v[16:19]
	v_mfma_f32_16x16x32_bf16 v[72:75], v[148:151], v[212:215], v[72:75]
	v_mfma_f32_16x16x32_bf16 v[8:11], v[156:159], v[212:215], v[8:11]
	v_mfma_f32_16x16x32_bf16 v[64:67], v[148:151], v[228:231], v[64:67]
	v_mfma_f32_16x16x32_bf16 v[0:3], v[156:159], v[228:231], v[0:3]
	v_mfma_f32_16x16x32_bf16 v[98:101], v[148:151], v[236:239], v[98:101]
	v_mfma_f32_16x16x32_bf16 v[32:35], v[156:159], v[236:239], v[32:35]
	v_mfma_f32_16x16x32_bf16 v[80:83], v[152:155], v[198:201], v[80:83]
	v_mfma_f32_16x16x32_bf16 v[16:19], v[174:177], v[198:201], v[16:19]
	v_mfma_f32_16x16x32_bf16 v[72:75], v[152:155], v[224:227], v[72:75]
	v_mfma_f32_16x16x32_bf16 v[8:11], v[174:177], v[224:227], v[8:11]
	v_mfma_f32_16x16x32_bf16 v[64:67], v[152:155], v[232:235], v[64:67]
	v_mfma_f32_16x16x32_bf16 v[0:3], v[174:177], v[232:235], v[0:3]
	v_mfma_f32_16x16x32_bf16 v[98:101], v[152:155], v[240:243], v[98:101]
	v_mfma_f32_16x16x32_bf16 v[32:35], v[174:177], v[240:243], v[32:35]
	s_barrier
	s_setprio 0
	s_cbranch_scc0 .LBB0_565

.LBB0_661:
	s_add_u32 s64, s44, 0x100
	s_addc_u32 s65, s45, 0
	s_mov_b32 s66, -2
	s_waitcnt lgkmcnt(0)
	s_waitcnt vmcnt(0)
	ds_read_b128 v[144:147], v151
	ds_read_b128 v[156:159], v151 offset:1024
	ds_read_b128 v[160:163], v151 offset:2048
	ds_read_b128 v[164:167], v151 offset:3072
	ds_read_b128 v[168:171], v152
	ds_read_b128 v[172:175], v152 offset:1024
	ds_read_b128 v[176:179], v152 offset:2048
	ds_read_b128 v[180:183], v152 offset:3072
	s_add_u32 s44, s42, 0x100
	s_addc_u32 s45, s43, 0
	s_cmp_eq_u32 s66, 40
	s_cselect_b32 s69, s1, s45
	s_cselect_b32 s68, s0, s44
	s_cselect_b32 s47, s41, s65
	s_cselect_b32 s46, s40, s64
	v_lshl_add_u64 v[216:217], s[42:43], 0, v[136:137]
	s_add_i32 m0, s48, 0xc000
	ds_read_b128 v[184:187], v153
	ds_read_b128 v[188:191], v153 offset:1024
	ds_read_b128 v[192:195], v153 offset:2048
	ds_read_b128 v[196:199], v153 offset:3072
	ds_read_b128 v[200:203], v153 offset:4096
	ds_read_b128 v[204:207], v153 offset:5120
	ds_read_b128 v[208:211], v153 offset:6144
	ds_read_b128 v[212:215], v153 offset:7168
	global_load_lds_dwordx4 v[216:217], off
	s_add_i32 m0, s48, 0xe000
	v_lshl_add_u64 v[216:217], s[42:43], 0, v[138:139]
	global_load_lds_dwordx4 v[216:217], off
	s_setprio 1
	s_waitcnt vmcnt(8) lgkmcnt(0)
	s_barrier
	v_mfma_f32_16x16x32_bf16 v[124:127], v[144:147], v[184:187], 0
	v_mfma_f32_16x16x32_bf16 v[120:123], v[160:163], v[184:187], 0
	v_mfma_f32_16x16x32_bf16 v[108:111], v[144:147], v[192:195], 0
	v_mfma_f32_16x16x32_bf16 v[104:107], v[160:163], v[192:195], 0
	v_mfma_f32_16x16x32_bf16 v[92:95], v[144:147], v[200:203], 0
	v_mfma_f32_16x16x32_bf16 v[88:91], v[160:163], v[200:203], 0
	v_mfma_f32_16x16x32_bf16 v[76:79], v[144:147], v[208:211], 0
	v_mfma_f32_16x16x32_bf16 v[72:75], v[160:163], v[208:211], 0
	v_mfma_f32_16x16x32_bf16 v[124:127], v[156:159], v[188:191], v[124:127]
	v_mfma_f32_16x16x32_bf16 v[120:123], v[164:167], v[188:191], v[120:123]
	v_mfma_f32_16x16x32_bf16 v[108:111], v[156:159], v[196:199], v[108:111]
	v_mfma_f32_16x16x32_bf16 v[104:107], v[164:167], v[196:199], v[104:107]
	v_mfma_f32_16x16x32_bf16 v[92:95], v[156:159], v[204:207], v[92:95]
	v_mfma_f32_16x16x32_bf16 v[88:91], v[164:167], v[204:207], v[88:91]
	v_mfma_f32_16x16x32_bf16 v[76:79], v[156:159], v[212:215], v[76:79]
	v_mfma_f32_16x16x32_bf16 v[72:75], v[164:167], v[212:215], v[72:75]
	v_mfma_f32_16x16x32_bf16 v[116:119], v[168:171], v[184:187], 0
	v_mfma_f32_16x16x32_bf16 v[112:115], v[176:179], v[184:187], 0
	v_mfma_f32_16x16x32_bf16 v[100:103], v[168:171], v[192:195], 0
	v_mfma_f32_16x16x32_bf16 v[96:99], v[176:179], v[192:195], 0
	v_mfma_f32_16x16x32_bf16 v[84:87], v[168:171], v[200:203], 0
	v_mfma_f32_16x16x32_bf16 v[80:83], v[176:179], v[200:203], 0
	v_mfma_f32_16x16x32_bf16 v[68:71], v[168:171], v[208:211], 0
	v_mfma_f32_16x16x32_bf16 v[64:67], v[176:179], v[208:211], 0
	v_mfma_f32_16x16x32_bf16 v[116:119], v[172:175], v[188:191], v[116:119]
	v_mfma_f32_16x16x32_bf16 v[112:115], v[180:183], v[188:191], v[112:115]
	v_mfma_f32_16x16x32_bf16 v[100:103], v[172:175], v[196:199], v[100:103]
	v_mfma_f32_16x16x32_bf16 v[96:99], v[180:183], v[196:199], v[96:99]
	v_mfma_f32_16x16x32_bf16 v[84:87], v[172:175], v[204:207], v[84:87]
	v_mfma_f32_16x16x32_bf16 v[80:83], v[180:183], v[204:207], v[80:83]
	v_mfma_f32_16x16x32_bf16 v[68:71], v[172:175], v[212:215], v[68:71]
	v_mfma_f32_16x16x32_bf16 v[64:67], v[180:183], v[212:215], v[64:67]
	s_barrier
	s_setprio 0
	s_add_i32 s42, s59, s35
	v_lshl_add_u64 v[216:217], s[46:47], 0, v[130:131]
	s_mov_b32 m0, s42
	ds_read_b128 v[184:187], v153 offset:16384
	ds_read_b128 v[188:191], v153 offset:17408
	ds_read_b128 v[192:195], v153 offset:18432
	ds_read_b128 v[196:199], v153 offset:19456
	ds_read_b128 v[200:203], v153 offset:20480
	ds_read_b128 v[204:207], v153 offset:21504
	ds_read_b128 v[208:211], v153 offset:22528
	ds_read_b128 v[212:215], v153 offset:23552
	global_load_lds_dwordx4 v[216:217], off
	s_add_i32 m0, s42, 0x2000
	s_add_u32 s42, s46, 0xb0000
	v_lshl_add_u64 v[220:221], s[46:47], 0, v[134:135]
	s_addc_u32 s43, s47, 0
	s_add_i32 s67, s60, s35
	global_load_lds_dwordx4 v[220:221], off
	v_lshl_add_u64 v[224:225], s[42:43], 0, v[130:131]
	s_mov_b32 m0, s67
	v_lshl_add_u64 v[226:227], s[68:69], 0, v[132:133]
	global_load_lds_dwordx4 v[224:225], off
	v_lshl_add_u64 v[224:225], s[42:43], 0, v[134:135]
	s_add_i32 m0, s67, 0x2000
	v_lshl_add_u64 v[228:229], v[226:227], 0, s[14:15]
	global_load_lds_dwordx4 v[224:225], off
	s_mov_b32 m0, s48
	v_lshl_add_u64 v[224:225], s[68:69], 0, v[128:129]
	global_load_lds_dwordx4 v[224:225], off
	s_mov_b32 m0, s49
	s_nop 0
	global_load_lds_dwordx4 v[228:229], off
	s_setprio 1
	s_waitcnt vmcnt(8) lgkmcnt(0)
	s_barrier
	v_mfma_f32_16x16x32_bf16 v[60:63], v[144:147], v[184:187], 0
	v_mfma_f32_16x16x32_bf16 v[56:59], v[160:163], v[184:187], 0
	v_mfma_f32_16x16x32_bf16 v[44:47], v[144:147], v[192:195], 0
	v_mfma_f32_16x16x32_bf16 v[40:43], v[160:163], v[192:195], 0
	v_mfma_f32_16x16x32_bf16 v[28:31], v[144:147], v[200:203], 0
	v_mfma_f32_16x16x32_bf16 v[24:27], v[160:163], v[200:203], 0
	v_mfma_f32_16x16x32_bf16 v[12:15], v[144:147], v[208:211], 0
	v_mfma_f32_16x16x32_bf16 v[8:11], v[160:163], v[208:211], 0
	v_mfma_f32_16x16x32_bf16 v[60:63], v[156:159], v[188:191], v[60:63]
	v_mfma_f32_16x16x32_bf16 v[56:59], v[164:167], v[188:191], v[56:59]
	v_mfma_f32_16x16x32_bf16 v[44:47], v[156:159], v[196:199], v[44:47]
	v_mfma_f32_16x16x32_bf16 v[40:43], v[164:167], v[196:199], v[40:43]
	v_mfma_f32_16x16x32_bf16 v[28:31], v[156:159], v[204:207], v[28:31]
	v_mfma_f32_16x16x32_bf16 v[24:27], v[164:167], v[204:207], v[24:27]
	v_mfma_f32_16x16x32_bf16 v[12:15], v[156:159], v[212:215], v[12:15]
	v_mfma_f32_16x16x32_bf16 v[8:11], v[164:167], v[212:215], v[8:11]
	v_mfma_f32_16x16x32_bf16 v[52:55], v[168:171], v[184:187], 0
	v_mfma_f32_16x16x32_bf16 v[48:51], v[176:179], v[184:187], 0
	v_mfma_f32_16x16x32_bf16 v[36:39], v[168:171], v[192:195], 0
	v_mfma_f32_16x16x32_bf16 v[32:35], v[176:179], v[192:195], 0
	v_mfma_f32_16x16x32_bf16 v[20:23], v[168:171], v[200:203], 0
	v_mfma_f32_16x16x32_bf16 v[16:19], v[176:179], v[200:203], 0
	v_mfma_f32_16x16x32_bf16 v[4:7], v[168:171], v[208:211], 0
	v_mfma_f32_16x16x32_bf16 v[0:3], v[176:179], v[208:211], 0
	v_mfma_f32_16x16x32_bf16 v[52:55], v[172:175], v[188:191], v[52:55]
	v_mfma_f32_16x16x32_bf16 v[48:51], v[180:183], v[188:191], v[48:51]
	v_mfma_f32_16x16x32_bf16 v[36:39], v[172:175], v[196:199], v[36:39]
	v_mfma_f32_16x16x32_bf16 v[32:35], v[180:183], v[196:199], v[32:35]
	v_mfma_f32_16x16x32_bf16 v[20:23], v[172:175], v[204:207], v[20:23]
	v_mfma_f32_16x16x32_bf16 v[16:19], v[180:183], v[204:207], v[16:19]
	v_mfma_f32_16x16x32_bf16 v[4:7], v[172:175], v[212:215], v[4:7]
	v_mfma_f32_16x16x32_bf16 v[0:3], v[180:183], v[212:215], v[0:3]
	s_barrier
	s_setprio 0
	s_add_i32 s42, 0, 0x18000
	v_add_u32_e32 v155, s42, v149
	s_add_i32 s67, 0, 0x1c000
	ds_read_b128 v[144:147], v155
	ds_read_b128 v[156:159], v155 offset:1024
	ds_read_b128 v[160:163], v155 offset:2048
	ds_read_b128 v[164:167], v155 offset:3072
	v_add_u32_e32 v155, s67, v149
	ds_read_b128 v[168:171], v155
	ds_read_b128 v[172:175], v155 offset:1024
	ds_read_b128 v[176:179], v155 offset:2048
	ds_read_b128 v[180:183], v155 offset:3072
	s_mov_b32 m0, s50
	v_lshl_add_u64 v[228:229], v[224:225], 0, s[12:13]
	ds_read_b128 v[184:187], v153 offset:32768
	ds_read_b128 v[188:191], v153 offset:33792
	ds_read_b128 v[192:195], v153 offset:34816
	ds_read_b128 v[196:199], v153 offset:35840
	ds_read_b128 v[200:203], v153 offset:36864
	ds_read_b128 v[204:207], v153 offset:37888
	ds_read_b128 v[208:211], v153 offset:38912
	ds_read_b128 v[212:215], v153 offset:39936
	global_load_lds_dwordx4 v[228:229], off
	s_mov_b32 m0, s51
	v_lshl_add_u64 v[228:229], v[226:227], 0, s[16:17]
	global_load_lds_dwordx4 v[228:229], off
	s_setprio 1
	s_waitcnt vmcnt(8) lgkmcnt(0)
	s_barrier
	v_mfma_f32_16x16x32_bf16 v[124:127], v[144:147], v[184:187], v[124:127]
	v_mfma_f32_16x16x32_bf16 v[120:123], v[160:163], v[184:187], v[120:123]
	v_mfma_f32_16x16x32_bf16 v[108:111], v[144:147], v[192:195], v[108:111]
	v_mfma_f32_16x16x32_bf16 v[104:107], v[160:163], v[192:195], v[104:107]
	v_mfma_f32_16x16x32_bf16 v[92:95], v[144:147], v[200:203], v[92:95]
	v_mfma_f32_16x16x32_bf16 v[88:91], v[160:163], v[200:203], v[88:91]
	v_mfma_f32_16x16x32_bf16 v[76:79], v[144:147], v[208:211], v[76:79]
	v_mfma_f32_16x16x32_bf16 v[72:75], v[160:163], v[208:211], v[72:75]
	v_mfma_f32_16x16x32_bf16 v[124:127], v[156:159], v[188:191], v[124:127]
	v_mfma_f32_16x16x32_bf16 v[120:123], v[164:167], v[188:191], v[120:123]
	v_mfma_f32_16x16x32_bf16 v[108:111], v[156:159], v[196:199], v[108:111]
	v_mfma_f32_16x16x32_bf16 v[104:107], v[164:167], v[196:199], v[104:107]
	v_mfma_f32_16x16x32_bf16 v[92:95], v[156:159], v[204:207], v[92:95]
	v_mfma_f32_16x16x32_bf16 v[88:91], v[164:167], v[204:207], v[88:91]
	v_mfma_f32_16x16x32_bf16 v[76:79], v[156:159], v[212:215], v[76:79]
	v_mfma_f32_16x16x32_bf16 v[72:75], v[164:167], v[212:215], v[72:75]
	v_mfma_f32_16x16x32_bf16 v[116:119], v[168:171], v[184:187], v[116:119]
	v_mfma_f32_16x16x32_bf16 v[112:115], v[176:179], v[184:187], v[112:115]
	v_mfma_f32_16x16x32_bf16 v[100:103], v[168:171], v[192:195], v[100:103]
	v_mfma_f32_16x16x32_bf16 v[96:99], v[176:179], v[192:195], v[96:99]
	v_mfma_f32_16x16x32_bf16 v[84:87], v[168:171], v[200:203], v[84:87]
	v_mfma_f32_16x16x32_bf16 v[80:83], v[176:179], v[200:203], v[80:83]
	v_mfma_f32_16x16x32_bf16 v[68:71], v[168:171], v[208:211], v[68:71]
	v_mfma_f32_16x16x32_bf16 v[64:67], v[176:179], v[208:211], v[64:67]
	v_mfma_f32_16x16x32_bf16 v[116:119], v[172:175], v[188:191], v[116:119]
	v_mfma_f32_16x16x32_bf16 v[112:115], v[180:183], v[188:191], v[112:115]
	v_mfma_f32_16x16x32_bf16 v[100:103], v[172:175], v[196:199], v[100:103]
	v_mfma_f32_16x16x32_bf16 v[96:99], v[180:183], v[196:199], v[96:99]
	v_mfma_f32_16x16x32_bf16 v[84:87], v[172:175], v[204:207], v[84:87]
	v_mfma_f32_16x16x32_bf16 v[80:83], v[180:183], v[204:207], v[80:83]
	v_mfma_f32_16x16x32_bf16 v[68:71], v[172:175], v[212:215], v[68:71]
	v_mfma_f32_16x16x32_bf16 v[64:67], v[180:183], v[212:215], v[64:67]
	s_barrier
	s_setprio 0
	s_add_i32 s42, s42, s35
	v_lshl_add_u64 v[216:217], v[216:217], 0, s[24:25]
	s_mov_b32 m0, s42
	ds_read_b128 v[184:187], v153 offset:49152
	ds_read_b128 v[188:191], v153 offset:50176
	ds_read_b128 v[192:195], v153 offset:51200
	ds_read_b128 v[196:199], v153 offset:52224
	ds_read_b128 v[200:203], v153 offset:53248
	ds_read_b128 v[204:207], v153 offset:54272
	ds_read_b128 v[208:211], v153 offset:55296
	ds_read_b128 v[212:215], v153 offset:56320
	global_load_lds_dwordx4 v[216:217], off
	s_add_i32 m0, s42, 0x2000
	s_add_u32 s42, s46, 0xb0080
	v_lshl_add_u64 v[216:217], v[220:221], 0, s[24:25]
	s_addc_u32 s43, s47, 0
	s_add_i32 s46, s67, s35
	global_load_lds_dwordx4 v[216:217], off
	s_mov_b32 m0, s46
	v_lshl_add_u64 v[216:217], s[42:43], 0, v[130:131]
	global_load_lds_dwordx4 v[216:217], off
	s_add_i32 m0, s46, 0x2000
	v_lshl_add_u64 v[216:217], s[42:43], 0, v[134:135]
	global_load_lds_dwordx4 v[216:217], off
	s_mov_b32 m0, s53
	v_lshl_add_u64 v[216:217], v[224:225], 0, s[24:25]
	global_load_lds_dwordx4 v[216:217], off
	s_mov_b32 m0, s54
	v_lshl_add_u64 v[216:217], v[226:227], 0, s[36:37]
	global_load_lds_dwordx4 v[216:217], off
	s_add_i32 s66, s66, 2
	s_add_u32 s64, s64, 0x100
	s_addc_u32 s65, s65, 0
	s_cmp_gt_u32 s66, 41
	s_mov_b64 s[42:43], s[44:45]
	s_setprio 1
	s_waitcnt vmcnt(8) lgkmcnt(0)
	s_barrier
	v_mfma_f32_16x16x32_bf16 v[60:63], v[144:147], v[184:187], v[60:63]
	v_mfma_f32_16x16x32_bf16 v[56:59], v[160:163], v[184:187], v[56:59]
	v_mfma_f32_16x16x32_bf16 v[44:47], v[144:147], v[192:195], v[44:47]
	v_mfma_f32_16x16x32_bf16 v[40:43], v[160:163], v[192:195], v[40:43]
	v_mfma_f32_16x16x32_bf16 v[28:31], v[144:147], v[200:203], v[28:31]
	v_mfma_f32_16x16x32_bf16 v[24:27], v[160:163], v[200:203], v[24:27]
	v_mfma_f32_16x16x32_bf16 v[12:15], v[144:147], v[208:211], v[12:15]
	v_mfma_f32_16x16x32_bf16 v[8:11], v[160:163], v[208:211], v[8:11]
	v_mfma_f32_16x16x32_bf16 v[60:63], v[156:159], v[188:191], v[60:63]
	v_mfma_f32_16x16x32_bf16 v[56:59], v[164:167], v[188:191], v[56:59]
	v_mfma_f32_16x16x32_bf16 v[44:47], v[156:159], v[196:199], v[44:47]
	v_mfma_f32_16x16x32_bf16 v[40:43], v[164:167], v[196:199], v[40:43]
	v_mfma_f32_16x16x32_bf16 v[28:31], v[156:159], v[204:207], v[28:31]
	v_mfma_f32_16x16x32_bf16 v[24:27], v[164:167], v[204:207], v[24:27]
	v_mfma_f32_16x16x32_bf16 v[12:15], v[156:159], v[212:215], v[12:15]
	v_mfma_f32_16x16x32_bf16 v[8:11], v[164:167], v[212:215], v[8:11]
	v_mfma_f32_16x16x32_bf16 v[52:55], v[168:171], v[184:187], v[52:55]
	v_mfma_f32_16x16x32_bf16 v[48:51], v[176:179], v[184:187], v[48:51]
	v_mfma_f32_16x16x32_bf16 v[36:39], v[168:171], v[192:195], v[36:39]
	v_mfma_f32_16x16x32_bf16 v[32:35], v[176:179], v[192:195], v[32:35]
	v_mfma_f32_16x16x32_bf16 v[20:23], v[168:171], v[200:203], v[20:23]
	v_mfma_f32_16x16x32_bf16 v[16:19], v[176:179], v[200:203], v[16:19]
	v_mfma_f32_16x16x32_bf16 v[4:7], v[168:171], v[208:211], v[4:7]
	v_mfma_f32_16x16x32_bf16 v[0:3], v[176:179], v[208:211], v[0:3]
	v_mfma_f32_16x16x32_bf16 v[52:55], v[172:175], v[188:191], v[52:55]
	v_mfma_f32_16x16x32_bf16 v[48:51], v[180:183], v[188:191], v[48:51]
	v_mfma_f32_16x16x32_bf16 v[36:39], v[172:175], v[196:199], v[36:39]
	v_mfma_f32_16x16x32_bf16 v[32:35], v[180:183], v[196:199], v[32:35]
	v_mfma_f32_16x16x32_bf16 v[20:23], v[172:175], v[204:207], v[20:23]
	v_mfma_f32_16x16x32_bf16 v[16:19], v[180:183], v[204:207], v[16:19]
	v_mfma_f32_16x16x32_bf16 v[4:7], v[172:175], v[212:215], v[4:7]
	v_mfma_f32_16x16x32_bf16 v[0:3], v[180:183], v[212:215], v[0:3]
	s_barrier
	s_setprio 0
.LBB0_662:
	ds_read_b128 v[144:147], v151
	ds_read_b128 v[156:159], v151 offset:1024
	ds_read_b128 v[160:163], v151 offset:2048
	ds_read_b128 v[164:167], v151 offset:3072
	ds_read_b128 v[168:171], v152
	ds_read_b128 v[172:175], v152 offset:1024
	ds_read_b128 v[176:179], v152 offset:2048
	ds_read_b128 v[180:183], v152 offset:3072
	s_add_u32 s44, s42, 0x100
	s_addc_u32 s45, s43, 0
	s_cmp_eq_u32 s66, 40
	s_cselect_b32 s69, s1, s45
	s_cselect_b32 s68, s0, s44
	s_cselect_b32 s47, s41, s65
	s_cselect_b32 s46, s40, s64
	v_lshl_add_u64 v[216:217], s[42:43], 0, v[136:137]
	s_add_i32 m0, s48, 0xc000
	ds_read_b128 v[184:187], v153
	ds_read_b128 v[188:191], v153 offset:1024
	ds_read_b128 v[192:195], v153 offset:2048
	ds_read_b128 v[196:199], v153 offset:3072
	ds_read_b128 v[200:203], v153 offset:4096
	ds_read_b128 v[204:207], v153 offset:5120
	ds_read_b128 v[208:211], v153 offset:6144
	ds_read_b128 v[212:215], v153 offset:7168
	global_load_lds_dwordx4 v[216:217], off
	s_add_i32 m0, s48, 0xe000
	v_lshl_add_u64 v[216:217], s[42:43], 0, v[138:139]
	global_load_lds_dwordx4 v[216:217], off
	s_setprio 1
	s_waitcnt vmcnt(8) lgkmcnt(0)
	s_barrier
	v_mfma_f32_16x16x32_bf16 v[124:127], v[144:147], v[184:187], v[124:127]
	v_mfma_f32_16x16x32_bf16 v[120:123], v[160:163], v[184:187], v[120:123]
	v_mfma_f32_16x16x32_bf16 v[108:111], v[144:147], v[192:195], v[108:111]
	v_mfma_f32_16x16x32_bf16 v[104:107], v[160:163], v[192:195], v[104:107]
	v_mfma_f32_16x16x32_bf16 v[92:95], v[144:147], v[200:203], v[92:95]
	v_mfma_f32_16x16x32_bf16 v[88:91], v[160:163], v[200:203], v[88:91]
	v_mfma_f32_16x16x32_bf16 v[76:79], v[144:147], v[208:211], v[76:79]
	v_mfma_f32_16x16x32_bf16 v[72:75], v[160:163], v[208:211], v[72:75]
	v_mfma_f32_16x16x32_bf16 v[124:127], v[156:159], v[188:191], v[124:127]
	v_mfma_f32_16x16x32_bf16 v[120:123], v[164:167], v[188:191], v[120:123]
	v_mfma_f32_16x16x32_bf16 v[108:111], v[156:159], v[196:199], v[108:111]
	v_mfma_f32_16x16x32_bf16 v[104:107], v[164:167], v[196:199], v[104:107]
	v_mfma_f32_16x16x32_bf16 v[92:95], v[156:159], v[204:207], v[92:95]
	v_mfma_f32_16x16x32_bf16 v[88:91], v[164:167], v[204:207], v[88:91]
	v_mfma_f32_16x16x32_bf16 v[76:79], v[156:159], v[212:215], v[76:79]
	v_mfma_f32_16x16x32_bf16 v[72:75], v[164:167], v[212:215], v[72:75]
	v_mfma_f32_16x16x32_bf16 v[116:119], v[168:171], v[184:187], v[116:119]
	v_mfma_f32_16x16x32_bf16 v[112:115], v[176:179], v[184:187], v[112:115]
	v_mfma_f32_16x16x32_bf16 v[100:103], v[168:171], v[192:195], v[100:103]
	v_mfma_f32_16x16x32_bf16 v[96:99], v[176:179], v[192:195], v[96:99]
	v_mfma_f32_16x16x32_bf16 v[84:87], v[168:171], v[200:203], v[84:87]
	v_mfma_f32_16x16x32_bf16 v[80:83], v[176:179], v[200:203], v[80:83]
	v_mfma_f32_16x16x32_bf16 v[68:71], v[168:171], v[208:211], v[68:71]
	v_mfma_f32_16x16x32_bf16 v[64:67], v[176:179], v[208:211], v[64:67]
	v_mfma_f32_16x16x32_bf16 v[116:119], v[172:175], v[188:191], v[116:119]
	v_mfma_f32_16x16x32_bf16 v[112:115], v[180:183], v[188:191], v[112:115]
	v_mfma_f32_16x16x32_bf16 v[100:103], v[172:175], v[196:199], v[100:103]
	v_mfma_f32_16x16x32_bf16 v[96:99], v[180:183], v[196:199], v[96:99]
	v_mfma_f32_16x16x32_bf16 v[84:87], v[172:175], v[204:207], v[84:87]
	v_mfma_f32_16x16x32_bf16 v[80:83], v[180:183], v[204:207], v[80:83]
	v_mfma_f32_16x16x32_bf16 v[68:71], v[172:175], v[212:215], v[68:71]
	v_mfma_f32_16x16x32_bf16 v[64:67], v[180:183], v[212:215], v[64:67]
	s_barrier
	s_setprio 0
	s_add_i32 s42, s59, s35
	v_lshl_add_u64 v[216:217], s[46:47], 0, v[130:131]
	s_mov_b32 m0, s42
	ds_read_b128 v[184:187], v153 offset:16384
	ds_read_b128 v[188:191], v153 offset:17408
	ds_read_b128 v[192:195], v153 offset:18432
	ds_read_b128 v[196:199], v153 offset:19456
	ds_read_b128 v[200:203], v153 offset:20480
	ds_read_b128 v[204:207], v153 offset:21504
	ds_read_b128 v[208:211], v153 offset:22528
	ds_read_b128 v[212:215], v153 offset:23552
	global_load_lds_dwordx4 v[216:217], off
	s_add_i32 m0, s42, 0x2000
	s_add_u32 s42, s46, 0xb0000
	v_lshl_add_u64 v[220:221], s[46:47], 0, v[134:135]
	s_addc_u32 s43, s47, 0
	s_add_i32 s67, s60, s35
	global_load_lds_dwordx4 v[220:221], off
	v_lshl_add_u64 v[224:225], s[42:43], 0, v[130:131]
	s_mov_b32 m0, s67
	v_lshl_add_u64 v[226:227], s[68:69], 0, v[132:133]
	global_load_lds_dwordx4 v[224:225], off
	v_lshl_add_u64 v[224:225], s[42:43], 0, v[134:135]
	s_add_i32 m0, s67, 0x2000
	v_lshl_add_u64 v[228:229], v[226:227], 0, s[14:15]
	global_load_lds_dwordx4 v[224:225], off
	s_mov_b32 m0, s48
	v_lshl_add_u64 v[224:225], s[68:69], 0, v[128:129]
	global_load_lds_dwordx4 v[224:225], off
	s_mov_b32 m0, s49
	s_nop 0
	global_load_lds_dwordx4 v[228:229], off
	s_setprio 1
	s_waitcnt vmcnt(8) lgkmcnt(0)
	s_barrier
	v_mfma_f32_16x16x32_bf16 v[60:63], v[144:147], v[184:187], v[60:63]
	v_mfma_f32_16x16x32_bf16 v[56:59], v[160:163], v[184:187], v[56:59]
	v_mfma_f32_16x16x32_bf16 v[44:47], v[144:147], v[192:195], v[44:47]
	v_mfma_f32_16x16x32_bf16 v[40:43], v[160:163], v[192:195], v[40:43]
	v_mfma_f32_16x16x32_bf16 v[28:31], v[144:147], v[200:203], v[28:31]
	v_mfma_f32_16x16x32_bf16 v[24:27], v[160:163], v[200:203], v[24:27]
	v_mfma_f32_16x16x32_bf16 v[12:15], v[144:147], v[208:211], v[12:15]
	v_mfma_f32_16x16x32_bf16 v[8:11], v[160:163], v[208:211], v[8:11]
	v_mfma_f32_16x16x32_bf16 v[60:63], v[156:159], v[188:191], v[60:63]
	v_mfma_f32_16x16x32_bf16 v[56:59], v[164:167], v[188:191], v[56:59]
	v_mfma_f32_16x16x32_bf16 v[44:47], v[156:159], v[196:199], v[44:47]
	v_mfma_f32_16x16x32_bf16 v[40:43], v[164:167], v[196:199], v[40:43]
	v_mfma_f32_16x16x32_bf16 v[28:31], v[156:159], v[204:207], v[28:31]
	v_mfma_f32_16x16x32_bf16 v[24:27], v[164:167], v[204:207], v[24:27]
	v_mfma_f32_16x16x32_bf16 v[12:15], v[156:159], v[212:215], v[12:15]
	v_mfma_f32_16x16x32_bf16 v[8:11], v[164:167], v[212:215], v[8:11]
	v_mfma_f32_16x16x32_bf16 v[52:55], v[168:171], v[184:187], v[52:55]
	v_mfma_f32_16x16x32_bf16 v[48:51], v[176:179], v[184:187], v[48:51]
	v_mfma_f32_16x16x32_bf16 v[36:39], v[168:171], v[192:195], v[36:39]
	v_mfma_f32_16x16x32_bf16 v[32:35], v[176:179], v[192:195], v[32:35]
	v_mfma_f32_16x16x32_bf16 v[20:23], v[168:171], v[200:203], v[20:23]
	v_mfma_f32_16x16x32_bf16 v[16:19], v[176:179], v[200:203], v[16:19]
	v_mfma_f32_16x16x32_bf16 v[4:7], v[168:171], v[208:211], v[4:7]
	v_mfma_f32_16x16x32_bf16 v[0:3], v[176:179], v[208:211], v[0:3]
	v_mfma_f32_16x16x32_bf16 v[52:55], v[172:175], v[188:191], v[52:55]
	v_mfma_f32_16x16x32_bf16 v[48:51], v[180:183], v[188:191], v[48:51]
	v_mfma_f32_16x16x32_bf16 v[36:39], v[172:175], v[196:199], v[36:39]
	v_mfma_f32_16x16x32_bf16 v[32:35], v[180:183], v[196:199], v[32:35]
	v_mfma_f32_16x16x32_bf16 v[20:23], v[172:175], v[204:207], v[20:23]
	v_mfma_f32_16x16x32_bf16 v[16:19], v[180:183], v[204:207], v[16:19]
	v_mfma_f32_16x16x32_bf16 v[4:7], v[172:175], v[212:215], v[4:7]
	v_mfma_f32_16x16x32_bf16 v[0:3], v[180:183], v[212:215], v[0:3]
	s_barrier
	s_setprio 0
	s_add_i32 s42, 0, 0x18000
	v_add_u32_e32 v155, s42, v149
	s_add_i32 s67, 0, 0x1c000
	ds_read_b128 v[144:147], v155
	ds_read_b128 v[156:159], v155 offset:1024
	ds_read_b128 v[160:163], v155 offset:2048
	ds_read_b128 v[164:167], v155 offset:3072
	v_add_u32_e32 v155, s67, v149
	ds_read_b128 v[168:171], v155
	ds_read_b128 v[172:175], v155 offset:1024
	ds_read_b128 v[176:179], v155 offset:2048
	ds_read_b128 v[180:183], v155 offset:3072
	s_mov_b32 m0, s50
	v_lshl_add_u64 v[228:229], v[224:225], 0, s[12:13]
	ds_read_b128 v[184:187], v153 offset:32768
	ds_read_b128 v[188:191], v153 offset:33792
	ds_read_b128 v[192:195], v153 offset:34816
	ds_read_b128 v[196:199], v153 offset:35840
	ds_read_b128 v[200:203], v153 offset:36864
	ds_read_b128 v[204:207], v153 offset:37888
	ds_read_b128 v[208:211], v153 offset:38912
	ds_read_b128 v[212:215], v153 offset:39936
	global_load_lds_dwordx4 v[228:229], off
	s_mov_b32 m0, s51
	v_lshl_add_u64 v[228:229], v[226:227], 0, s[16:17]
	global_load_lds_dwordx4 v[228:229], off
	s_setprio 1
	s_waitcnt vmcnt(8) lgkmcnt(0)
	s_barrier
	v_mfma_f32_16x16x32_bf16 v[124:127], v[144:147], v[184:187], v[124:127]
	v_mfma_f32_16x16x32_bf16 v[120:123], v[160:163], v[184:187], v[120:123]
	v_mfma_f32_16x16x32_bf16 v[108:111], v[144:147], v[192:195], v[108:111]
	v_mfma_f32_16x16x32_bf16 v[104:107], v[160:163], v[192:195], v[104:107]
	v_mfma_f32_16x16x32_bf16 v[92:95], v[144:147], v[200:203], v[92:95]
	v_mfma_f32_16x16x32_bf16 v[88:91], v[160:163], v[200:203], v[88:91]
	v_mfma_f32_16x16x32_bf16 v[76:79], v[144:147], v[208:211], v[76:79]
	v_mfma_f32_16x16x32_bf16 v[72:75], v[160:163], v[208:211], v[72:75]
	v_mfma_f32_16x16x32_bf16 v[124:127], v[156:159], v[188:191], v[124:127]
	v_mfma_f32_16x16x32_bf16 v[120:123], v[164:167], v[188:191], v[120:123]
	v_mfma_f32_16x16x32_bf16 v[108:111], v[156:159], v[196:199], v[108:111]
	v_mfma_f32_16x16x32_bf16 v[104:107], v[164:167], v[196:199], v[104:107]
	v_mfma_f32_16x16x32_bf16 v[92:95], v[156:159], v[204:207], v[92:95]
	v_mfma_f32_16x16x32_bf16 v[88:91], v[164:167], v[204:207], v[88:91]
	v_mfma_f32_16x16x32_bf16 v[76:79], v[156:159], v[212:215], v[76:79]
	v_mfma_f32_16x16x32_bf16 v[72:75], v[164:167], v[212:215], v[72:75]
	v_mfma_f32_16x16x32_bf16 v[116:119], v[168:171], v[184:187], v[116:119]
	v_mfma_f32_16x16x32_bf16 v[112:115], v[176:179], v[184:187], v[112:115]
	v_mfma_f32_16x16x32_bf16 v[100:103], v[168:171], v[192:195], v[100:103]
	v_mfma_f32_16x16x32_bf16 v[96:99], v[176:179], v[192:195], v[96:99]
	v_mfma_f32_16x16x32_bf16 v[84:87], v[168:171], v[200:203], v[84:87]
	v_mfma_f32_16x16x32_bf16 v[80:83], v[176:179], v[200:203], v[80:83]
	v_mfma_f32_16x16x32_bf16 v[68:71], v[168:171], v[208:211], v[68:71]
	v_mfma_f32_16x16x32_bf16 v[64:67], v[176:179], v[208:211], v[64:67]
	v_mfma_f32_16x16x32_bf16 v[116:119], v[172:175], v[188:191], v[116:119]
	v_mfma_f32_16x16x32_bf16 v[112:115], v[180:183], v[188:191], v[112:115]
	v_mfma_f32_16x16x32_bf16 v[100:103], v[172:175], v[196:199], v[100:103]
	v_mfma_f32_16x16x32_bf16 v[96:99], v[180:183], v[196:199], v[96:99]
	v_mfma_f32_16x16x32_bf16 v[84:87], v[172:175], v[204:207], v[84:87]
	v_mfma_f32_16x16x32_bf16 v[80:83], v[180:183], v[204:207], v[80:83]
	v_mfma_f32_16x16x32_bf16 v[68:71], v[172:175], v[212:215], v[68:71]
	v_mfma_f32_16x16x32_bf16 v[64:67], v[180:183], v[212:215], v[64:67]
	s_barrier
	s_setprio 0
	s_add_i32 s42, s42, s35
	v_lshl_add_u64 v[216:217], v[216:217], 0, s[24:25]
	s_mov_b32 m0, s42
	ds_read_b128 v[184:187], v153 offset:49152
	ds_read_b128 v[188:191], v153 offset:50176
	ds_read_b128 v[192:195], v153 offset:51200
	ds_read_b128 v[196:199], v153 offset:52224
	ds_read_b128 v[200:203], v153 offset:53248
	ds_read_b128 v[204:207], v153 offset:54272
	ds_read_b128 v[208:211], v153 offset:55296
	ds_read_b128 v[212:215], v153 offset:56320
	global_load_lds_dwordx4 v[216:217], off
	s_add_i32 m0, s42, 0x2000
	s_add_u32 s42, s46, 0xb0080
	v_lshl_add_u64 v[216:217], v[220:221], 0, s[24:25]
	s_addc_u32 s43, s47, 0
	s_add_i32 s46, s67, s35
	global_load_lds_dwordx4 v[216:217], off
	s_mov_b32 m0, s46
	v_lshl_add_u64 v[216:217], s[42:43], 0, v[130:131]
	global_load_lds_dwordx4 v[216:217], off
	s_add_i32 m0, s46, 0x2000
	v_lshl_add_u64 v[216:217], s[42:43], 0, v[134:135]
	global_load_lds_dwordx4 v[216:217], off
	s_mov_b32 m0, s53
	v_lshl_add_u64 v[216:217], v[224:225], 0, s[24:25]
	global_load_lds_dwordx4 v[216:217], off
	s_mov_b32 m0, s54
	v_lshl_add_u64 v[216:217], v[226:227], 0, s[36:37]
	global_load_lds_dwordx4 v[216:217], off
	s_add_i32 s66, s66, 2
	s_add_u32 s64, s64, 0x100
	s_addc_u32 s65, s65, 0
	s_cmp_gt_u32 s66, 41
	s_mov_b64 s[42:43], s[44:45]
	s_setprio 1
	s_waitcnt vmcnt(8) lgkmcnt(0)
	s_barrier
	v_mfma_f32_16x16x32_bf16 v[60:63], v[144:147], v[184:187], v[60:63]
	v_mfma_f32_16x16x32_bf16 v[56:59], v[160:163], v[184:187], v[56:59]
	v_mfma_f32_16x16x32_bf16 v[44:47], v[144:147], v[192:195], v[44:47]
	v_mfma_f32_16x16x32_bf16 v[40:43], v[160:163], v[192:195], v[40:43]
	v_mfma_f32_16x16x32_bf16 v[28:31], v[144:147], v[200:203], v[28:31]
	v_mfma_f32_16x16x32_bf16 v[24:27], v[160:163], v[200:203], v[24:27]
	v_mfma_f32_16x16x32_bf16 v[12:15], v[144:147], v[208:211], v[12:15]
	v_mfma_f32_16x16x32_bf16 v[8:11], v[160:163], v[208:211], v[8:11]
	v_mfma_f32_16x16x32_bf16 v[60:63], v[156:159], v[188:191], v[60:63]
	v_mfma_f32_16x16x32_bf16 v[56:59], v[164:167], v[188:191], v[56:59]
	v_mfma_f32_16x16x32_bf16 v[44:47], v[156:159], v[196:199], v[44:47]
	v_mfma_f32_16x16x32_bf16 v[40:43], v[164:167], v[196:199], v[40:43]
	v_mfma_f32_16x16x32_bf16 v[28:31], v[156:159], v[204:207], v[28:31]
	v_mfma_f32_16x16x32_bf16 v[24:27], v[164:167], v[204:207], v[24:27]
	v_mfma_f32_16x16x32_bf16 v[12:15], v[156:159], v[212:215], v[12:15]
	v_mfma_f32_16x16x32_bf16 v[8:11], v[164:167], v[212:215], v[8:11]
	v_mfma_f32_16x16x32_bf16 v[52:55], v[168:171], v[184:187], v[52:55]
	v_mfma_f32_16x16x32_bf16 v[48:51], v[176:179], v[184:187], v[48:51]
	v_mfma_f32_16x16x32_bf16 v[36:39], v[168:171], v[192:195], v[36:39]
	v_mfma_f32_16x16x32_bf16 v[32:35], v[176:179], v[192:195], v[32:35]
	v_mfma_f32_16x16x32_bf16 v[20:23], v[168:171], v[200:203], v[20:23]
	v_mfma_f32_16x16x32_bf16 v[16:19], v[176:179], v[200:203], v[16:19]
	v_mfma_f32_16x16x32_bf16 v[4:7], v[168:171], v[208:211], v[4:7]
	v_mfma_f32_16x16x32_bf16 v[0:3], v[176:179], v[208:211], v[0:3]
	v_mfma_f32_16x16x32_bf16 v[52:55], v[172:175], v[188:191], v[52:55]
	v_mfma_f32_16x16x32_bf16 v[48:51], v[180:183], v[188:191], v[48:51]
	v_mfma_f32_16x16x32_bf16 v[36:39], v[172:175], v[196:199], v[36:39]
	v_mfma_f32_16x16x32_bf16 v[32:35], v[180:183], v[196:199], v[32:35]
	v_mfma_f32_16x16x32_bf16 v[20:23], v[172:175], v[204:207], v[20:23]
	v_mfma_f32_16x16x32_bf16 v[16:19], v[180:183], v[204:207], v[16:19]
	v_mfma_f32_16x16x32_bf16 v[4:7], v[172:175], v[212:215], v[4:7]
	v_mfma_f32_16x16x32_bf16 v[0:3], v[180:183], v[212:215], v[0:3]
	s_barrier
	s_setprio 0
	s_cbranch_scc0 .LBB0_662

.LBB0_750:
	s_lshl_b32 s38, s65, 8
	s_ashr_i32 s39, s38, 31
	s_lshl_b64 s[38:39], s[38:39], 11
	s_add_u32 s38, s8, s38
	s_addc_u32 s39, s9, s39
	s_and_b64 s[40:41], s[4:5], exec
	s_cselect_b32 s43, s39, s45
	s_cselect_b32 s67, s38, s44
	s_ashr_i32 s37, s36, 31
	s_lshl_b64 s[40:41], s[36:37], 19
	s_add_u32 s40, s3, s40
	s_addc_u32 s41, s33, s41
	s_and_b64 s[48:49], s[4:5], exec
	s_cselect_b32 s37, s41, s47
	s_cselect_b32 s68, s40, s46
	s_add_u32 s69, s46, 0x100
	s_addc_u32 s71, s47, 0
	s_mov_b32 s72, -2
	s_waitcnt vmcnt(0)
	ds_read_b128 v[144:147], v189
	ds_read_b128 v[148:151], v189 offset:1024
	ds_read_b128 v[152:155], v189 offset:2048
	ds_read_b128 v[156:159], v189 offset:3072
	ds_read_b128 v[160:163], v190
	ds_read_b128 v[164:167], v190 offset:1024
	ds_read_b128 v[168:171], v190 offset:2048
	ds_read_b128 v[172:175], v190 offset:3072
	s_add_u32 s46, s44, 0x100
	s_addc_u32 s47, s45, 0
	s_cmp_eq_u32 s72, 12
	s_cselect_b32 s75, s43, s47
	s_cselect_b32 s74, s67, s46
	s_cselect_b32 s49, s37, s71
	s_cselect_b32 s48, s68, s69
	v_lshl_add_u64 v[184:185], s[44:45], 0, v[136:137]
	s_add_i32 m0, s51, 0xc000
	ds_read_b128 v[176:179], v191
	ds_read_b128 v[180:183], v191 offset:1024
	ds_read_b128 v[194:197], v191 offset:2048
	ds_read_b128 v[198:201], v191 offset:3072
	ds_read_b128 v[202:205], v191 offset:4096
	ds_read_b128 v[206:209], v191 offset:5120
	ds_read_b128 v[210:213], v191 offset:6144
	ds_read_b128 v[214:217], v191 offset:7168
	global_load_lds_dwordx4 v[184:185], off
	s_add_i32 m0, s51, 0xe000
	v_lshl_add_u64 v[184:185], s[44:45], 0, v[138:139]
	global_load_lds_dwordx4 v[184:185], off
	s_setprio 1
	s_waitcnt vmcnt(8) lgkmcnt(0)
	s_barrier
	v_mfma_f32_16x16x32_bf16 v[124:127], v[144:147], v[176:179], 0
	v_mfma_f32_16x16x32_bf16 v[120:123], v[152:155], v[176:179], 0
	v_mfma_f32_16x16x32_bf16 v[108:111], v[144:147], v[194:197], 0
	v_mfma_f32_16x16x32_bf16 v[104:107], v[152:155], v[194:197], 0
	v_mfma_f32_16x16x32_bf16 v[92:95], v[144:147], v[202:205], 0
	v_mfma_f32_16x16x32_bf16 v[88:91], v[152:155], v[202:205], 0
	v_mfma_f32_16x16x32_bf16 v[76:79], v[144:147], v[210:213], 0
	v_mfma_f32_16x16x32_bf16 v[72:75], v[152:155], v[210:213], 0
	v_mfma_f32_16x16x32_bf16 v[124:127], v[148:151], v[180:183], v[124:127]
	v_mfma_f32_16x16x32_bf16 v[120:123], v[156:159], v[180:183], v[120:123]
	v_mfma_f32_16x16x32_bf16 v[108:111], v[148:151], v[198:201], v[108:111]
	v_mfma_f32_16x16x32_bf16 v[104:107], v[156:159], v[198:201], v[104:107]
	v_mfma_f32_16x16x32_bf16 v[92:95], v[148:151], v[206:209], v[92:95]
	v_mfma_f32_16x16x32_bf16 v[88:91], v[156:159], v[206:209], v[88:91]
	v_mfma_f32_16x16x32_bf16 v[76:79], v[148:151], v[214:217], v[76:79]
	v_mfma_f32_16x16x32_bf16 v[72:75], v[156:159], v[214:217], v[72:75]
	v_mfma_f32_16x16x32_bf16 v[116:119], v[160:163], v[176:179], 0
	v_mfma_f32_16x16x32_bf16 v[112:115], v[168:171], v[176:179], 0
	v_mfma_f32_16x16x32_bf16 v[100:103], v[160:163], v[194:197], 0
	v_mfma_f32_16x16x32_bf16 v[96:99], v[168:171], v[194:197], 0
	v_mfma_f32_16x16x32_bf16 v[84:87], v[160:163], v[202:205], 0
	v_mfma_f32_16x16x32_bf16 v[80:83], v[168:171], v[202:205], 0
	v_mfma_f32_16x16x32_bf16 v[68:71], v[160:163], v[210:213], 0
	v_mfma_f32_16x16x32_bf16 v[64:67], v[168:171], v[210:213], 0
	v_mfma_f32_16x16x32_bf16 v[116:119], v[164:167], v[180:183], v[116:119]
	v_mfma_f32_16x16x32_bf16 v[112:115], v[172:175], v[180:183], v[112:115]
	v_mfma_f32_16x16x32_bf16 v[100:103], v[164:167], v[198:201], v[100:103]
	v_mfma_f32_16x16x32_bf16 v[96:99], v[172:175], v[198:201], v[96:99]
	v_mfma_f32_16x16x32_bf16 v[84:87], v[164:167], v[206:209], v[84:87]
	v_mfma_f32_16x16x32_bf16 v[80:83], v[172:175], v[206:209], v[80:83]
	v_mfma_f32_16x16x32_bf16 v[68:71], v[164:167], v[214:217], v[68:71]
	v_mfma_f32_16x16x32_bf16 v[64:67], v[172:175], v[214:217], v[64:67]
	s_barrier
	s_setprio 0
	s_add_i32 s44, s63, s50
	v_lshl_add_u64 v[184:185], s[48:49], 0, v[130:131]
	s_mov_b32 m0, s44
	ds_read_b128 v[176:179], v191 offset:16384
	ds_read_b128 v[180:183], v191 offset:17408
	ds_read_b128 v[194:197], v191 offset:18432
	ds_read_b128 v[198:201], v191 offset:19456
	ds_read_b128 v[202:205], v191 offset:20480
	ds_read_b128 v[206:209], v191 offset:21504
	ds_read_b128 v[210:213], v191 offset:22528
	ds_read_b128 v[214:217], v191 offset:23552
	global_load_lds_dwordx4 v[184:185], off
	s_add_i32 m0, s44, 0x2000
	s_add_u32 s44, s48, 0x40000
	v_lshl_add_u64 v[218:219], s[48:49], 0, v[134:135]
	s_addc_u32 s45, s49, 0
	s_add_i32 s70, s64, s50
	global_load_lds_dwordx4 v[218:219], off
	v_lshl_add_u64 v[220:221], s[44:45], 0, v[130:131]
	s_mov_b32 m0, s70
	v_lshl_add_u64 v[222:223], s[74:75], 0, v[132:133]
	global_load_lds_dwordx4 v[220:221], off
	v_lshl_add_u64 v[220:221], s[44:45], 0, v[134:135]
	s_add_i32 m0, s70, 0x2000
	v_lshl_add_u64 v[224:225], v[222:223], 0, s[12:13]
	global_load_lds_dwordx4 v[220:221], off
	s_mov_b32 m0, s51
	v_lshl_add_u64 v[220:221], s[74:75], 0, v[128:129]
	global_load_lds_dwordx4 v[220:221], off
	s_mov_b32 m0, s52
	s_nop 0
	global_load_lds_dwordx4 v[224:225], off
	s_setprio 1
	s_waitcnt vmcnt(8) lgkmcnt(0)
	s_barrier
	v_mfma_f32_16x16x32_bf16 v[60:63], v[144:147], v[176:179], 0
	v_mfma_f32_16x16x32_bf16 v[56:59], v[152:155], v[176:179], 0
	v_mfma_f32_16x16x32_bf16 v[44:47], v[144:147], v[194:197], 0
	v_mfma_f32_16x16x32_bf16 v[40:43], v[152:155], v[194:197], 0
	v_mfma_f32_16x16x32_bf16 v[28:31], v[144:147], v[202:205], 0
	v_mfma_f32_16x16x32_bf16 v[24:27], v[152:155], v[202:205], 0
	v_mfma_f32_16x16x32_bf16 v[12:15], v[144:147], v[210:213], 0
	v_mfma_f32_16x16x32_bf16 v[8:11], v[152:155], v[210:213], 0
	v_mfma_f32_16x16x32_bf16 v[60:63], v[148:151], v[180:183], v[60:63]
	v_mfma_f32_16x16x32_bf16 v[56:59], v[156:159], v[180:183], v[56:59]
	v_mfma_f32_16x16x32_bf16 v[44:47], v[148:151], v[198:201], v[44:47]
	v_mfma_f32_16x16x32_bf16 v[40:43], v[156:159], v[198:201], v[40:43]
	v_mfma_f32_16x16x32_bf16 v[28:31], v[148:151], v[206:209], v[28:31]
	v_mfma_f32_16x16x32_bf16 v[24:27], v[156:159], v[206:209], v[24:27]
	v_mfma_f32_16x16x32_bf16 v[12:15], v[148:151], v[214:217], v[12:15]
	v_mfma_f32_16x16x32_bf16 v[8:11], v[156:159], v[214:217], v[8:11]
	v_mfma_f32_16x16x32_bf16 v[52:55], v[160:163], v[176:179], 0
	v_mfma_f32_16x16x32_bf16 v[48:51], v[168:171], v[176:179], 0
	v_mfma_f32_16x16x32_bf16 v[36:39], v[160:163], v[194:197], 0
	v_mfma_f32_16x16x32_bf16 v[32:35], v[168:171], v[194:197], 0
	v_mfma_f32_16x16x32_bf16 v[20:23], v[160:163], v[202:205], 0
	v_mfma_f32_16x16x32_bf16 v[16:19], v[168:171], v[202:205], 0
	v_mfma_f32_16x16x32_bf16 v[4:7], v[160:163], v[210:213], 0
	v_mfma_f32_16x16x32_bf16 v[0:3], v[168:171], v[210:213], 0
	v_mfma_f32_16x16x32_bf16 v[52:55], v[164:167], v[180:183], v[52:55]
	v_mfma_f32_16x16x32_bf16 v[48:51], v[172:175], v[180:183], v[48:51]
	v_mfma_f32_16x16x32_bf16 v[36:39], v[164:167], v[198:201], v[36:39]
	v_mfma_f32_16x16x32_bf16 v[32:35], v[172:175], v[198:201], v[32:35]
	v_mfma_f32_16x16x32_bf16 v[20:23], v[164:167], v[206:209], v[20:23]
	v_mfma_f32_16x16x32_bf16 v[16:19], v[172:175], v[206:209], v[16:19]
	v_mfma_f32_16x16x32_bf16 v[4:7], v[164:167], v[214:217], v[4:7]
	v_mfma_f32_16x16x32_bf16 v[0:3], v[172:175], v[214:217], v[0:3]
	s_barrier
	s_setprio 0
	s_add_i32 s44, 0, 0x18000
	s_add_i32 s70, 0, 0x1c000
	v_add_u32_e32 v156, s44, v187
	v_add_u32_e32 v172, s70, v187
	ds_read_b128 v[144:147], v156
	ds_read_b128 v[148:151], v156 offset:1024
	ds_read_b128 v[152:155], v156 offset:2048
	ds_read_b128 v[156:159], v156 offset:3072
	ds_read_b128 v[160:163], v172
	ds_read_b128 v[164:167], v172 offset:1024
	ds_read_b128 v[168:171], v172 offset:2048
	ds_read_b128 v[172:175], v172 offset:3072
	s_mov_b32 m0, s53
	v_lshl_add_u64 v[224:225], v[220:221], 0, s[10:11]
	ds_read_b128 v[176:179], v191 offset:32768
	ds_read_b128 v[180:183], v191 offset:33792
	ds_read_b128 v[194:197], v191 offset:34816
	ds_read_b128 v[198:201], v191 offset:35840
	ds_read_b128 v[202:205], v191 offset:36864
	ds_read_b128 v[206:209], v191 offset:37888
	ds_read_b128 v[210:213], v191 offset:38912
	ds_read_b128 v[214:217], v191 offset:39936
	global_load_lds_dwordx4 v[224:225], off
	s_mov_b32 m0, s54
	v_lshl_add_u64 v[224:225], v[222:223], 0, s[14:15]
	global_load_lds_dwordx4 v[224:225], off
	s_setprio 1
	s_waitcnt vmcnt(8) lgkmcnt(0)
	s_barrier
	v_mfma_f32_16x16x32_bf16 v[124:127], v[144:147], v[176:179], v[124:127]
	v_mfma_f32_16x16x32_bf16 v[120:123], v[152:155], v[176:179], v[120:123]
	v_mfma_f32_16x16x32_bf16 v[108:111], v[144:147], v[194:197], v[108:111]
	v_mfma_f32_16x16x32_bf16 v[104:107], v[152:155], v[194:197], v[104:107]
	v_mfma_f32_16x16x32_bf16 v[92:95], v[144:147], v[202:205], v[92:95]
	v_mfma_f32_16x16x32_bf16 v[88:91], v[152:155], v[202:205], v[88:91]
	v_mfma_f32_16x16x32_bf16 v[76:79], v[144:147], v[210:213], v[76:79]
	v_mfma_f32_16x16x32_bf16 v[72:75], v[152:155], v[210:213], v[72:75]
	v_mfma_f32_16x16x32_bf16 v[124:127], v[148:151], v[180:183], v[124:127]
	v_mfma_f32_16x16x32_bf16 v[120:123], v[156:159], v[180:183], v[120:123]
	v_mfma_f32_16x16x32_bf16 v[108:111], v[148:151], v[198:201], v[108:111]
	v_mfma_f32_16x16x32_bf16 v[104:107], v[156:159], v[198:201], v[104:107]
	v_mfma_f32_16x16x32_bf16 v[92:95], v[148:151], v[206:209], v[92:95]
	v_mfma_f32_16x16x32_bf16 v[88:91], v[156:159], v[206:209], v[88:91]
	v_mfma_f32_16x16x32_bf16 v[76:79], v[148:151], v[214:217], v[76:79]
	v_mfma_f32_16x16x32_bf16 v[72:75], v[156:159], v[214:217], v[72:75]
	v_mfma_f32_16x16x32_bf16 v[116:119], v[160:163], v[176:179], v[116:119]
	v_mfma_f32_16x16x32_bf16 v[112:115], v[168:171], v[176:179], v[112:115]
	v_mfma_f32_16x16x32_bf16 v[100:103], v[160:163], v[194:197], v[100:103]
	v_mfma_f32_16x16x32_bf16 v[96:99], v[168:171], v[194:197], v[96:99]
	v_mfma_f32_16x16x32_bf16 v[84:87], v[160:163], v[202:205], v[84:87]
	v_mfma_f32_16x16x32_bf16 v[80:83], v[168:171], v[202:205], v[80:83]
	v_mfma_f32_16x16x32_bf16 v[68:71], v[160:163], v[210:213], v[68:71]
	v_mfma_f32_16x16x32_bf16 v[64:67], v[168:171], v[210:213], v[64:67]
	v_mfma_f32_16x16x32_bf16 v[116:119], v[164:167], v[180:183], v[116:119]
	v_mfma_f32_16x16x32_bf16 v[112:115], v[172:175], v[180:183], v[112:115]
	v_mfma_f32_16x16x32_bf16 v[100:103], v[164:167], v[198:201], v[100:103]
	v_mfma_f32_16x16x32_bf16 v[96:99], v[172:175], v[198:201], v[96:99]
	v_mfma_f32_16x16x32_bf16 v[84:87], v[164:167], v[206:209], v[84:87]
	v_mfma_f32_16x16x32_bf16 v[80:83], v[172:175], v[206:209], v[80:83]
	v_mfma_f32_16x16x32_bf16 v[68:71], v[164:167], v[214:217], v[68:71]
	v_mfma_f32_16x16x32_bf16 v[64:67], v[172:175], v[214:217], v[64:67]
	s_barrier
	s_setprio 0
	s_add_i32 s44, s44, s50
	v_lshl_add_u64 v[184:185], v[184:185], 0, s[24:25]
	s_mov_b32 m0, s44
	ds_read_b128 v[176:179], v191 offset:49152
	ds_read_b128 v[180:183], v191 offset:50176
	ds_read_b128 v[194:197], v191 offset:51200
	ds_read_b128 v[198:201], v191 offset:52224
	ds_read_b128 v[202:205], v191 offset:53248
	ds_read_b128 v[206:209], v191 offset:54272
	ds_read_b128 v[210:213], v191 offset:55296
	ds_read_b128 v[214:217], v191 offset:56320
	global_load_lds_dwordx4 v[184:185], off
	s_add_i32 m0, s44, 0x2000
	s_add_u32 s44, s48, 0x40080
	v_lshl_add_u64 v[184:185], v[218:219], 0, s[24:25]
	s_addc_u32 s45, s49, 0
	s_add_i32 s48, s70, s50
	global_load_lds_dwordx4 v[184:185], off
	s_mov_b32 m0, s48
	v_lshl_add_u64 v[184:185], s[44:45], 0, v[130:131]
	global_load_lds_dwordx4 v[184:185], off
	s_add_i32 m0, s48, 0x2000
	v_lshl_add_u64 v[184:185], s[44:45], 0, v[134:135]
	global_load_lds_dwordx4 v[184:185], off
	s_mov_b32 m0, s58
	v_lshl_add_u64 v[184:185], v[220:221], 0, s[24:25]
	global_load_lds_dwordx4 v[184:185], off
	s_mov_b32 m0, s59
	v_lshl_add_u64 v[184:185], v[222:223], 0, s[30:31]
	global_load_lds_dwordx4 v[184:185], off
	s_add_i32 s72, s72, 2
	s_add_u32 s69, s69, 0x100
	s_addc_u32 s71, s71, 0
	s_cmp_gt_u32 s72, 13
	s_mov_b64 s[44:45], s[46:47]
	s_setprio 1
	s_waitcnt vmcnt(8) lgkmcnt(0)
	s_barrier
	v_mfma_f32_16x16x32_bf16 v[60:63], v[144:147], v[176:179], v[60:63]
	v_mfma_f32_16x16x32_bf16 v[56:59], v[152:155], v[176:179], v[56:59]
	v_mfma_f32_16x16x32_bf16 v[44:47], v[144:147], v[194:197], v[44:47]
	v_mfma_f32_16x16x32_bf16 v[40:43], v[152:155], v[194:197], v[40:43]
	v_mfma_f32_16x16x32_bf16 v[28:31], v[144:147], v[202:205], v[28:31]
	v_mfma_f32_16x16x32_bf16 v[24:27], v[152:155], v[202:205], v[24:27]
	v_mfma_f32_16x16x32_bf16 v[12:15], v[144:147], v[210:213], v[12:15]
	v_mfma_f32_16x16x32_bf16 v[8:11], v[152:155], v[210:213], v[8:11]
	v_mfma_f32_16x16x32_bf16 v[60:63], v[148:151], v[180:183], v[60:63]
	v_mfma_f32_16x16x32_bf16 v[56:59], v[156:159], v[180:183], v[56:59]
	v_mfma_f32_16x16x32_bf16 v[44:47], v[148:151], v[198:201], v[44:47]
	v_mfma_f32_16x16x32_bf16 v[40:43], v[156:159], v[198:201], v[40:43]
	v_mfma_f32_16x16x32_bf16 v[28:31], v[148:151], v[206:209], v[28:31]
	v_mfma_f32_16x16x32_bf16 v[24:27], v[156:159], v[206:209], v[24:27]
	v_mfma_f32_16x16x32_bf16 v[12:15], v[148:151], v[214:217], v[12:15]
	v_mfma_f32_16x16x32_bf16 v[8:11], v[156:159], v[214:217], v[8:11]
	v_mfma_f32_16x16x32_bf16 v[52:55], v[160:163], v[176:179], v[52:55]
	v_mfma_f32_16x16x32_bf16 v[48:51], v[168:171], v[176:179], v[48:51]
	v_mfma_f32_16x16x32_bf16 v[36:39], v[160:163], v[194:197], v[36:39]
	v_mfma_f32_16x16x32_bf16 v[32:35], v[168:171], v[194:197], v[32:35]
	v_mfma_f32_16x16x32_bf16 v[20:23], v[160:163], v[202:205], v[20:23]
	v_mfma_f32_16x16x32_bf16 v[16:19], v[168:171], v[202:205], v[16:19]
	v_mfma_f32_16x16x32_bf16 v[4:7], v[160:163], v[210:213], v[4:7]
	v_mfma_f32_16x16x32_bf16 v[0:3], v[168:171], v[210:213], v[0:3]
	v_mfma_f32_16x16x32_bf16 v[52:55], v[164:167], v[180:183], v[52:55]
	v_mfma_f32_16x16x32_bf16 v[48:51], v[172:175], v[180:183], v[48:51]
	v_mfma_f32_16x16x32_bf16 v[36:39], v[164:167], v[198:201], v[36:39]
	v_mfma_f32_16x16x32_bf16 v[32:35], v[172:175], v[198:201], v[32:35]
	v_mfma_f32_16x16x32_bf16 v[20:23], v[164:167], v[206:209], v[20:23]
	v_mfma_f32_16x16x32_bf16 v[16:19], v[172:175], v[206:209], v[16:19]
	v_mfma_f32_16x16x32_bf16 v[4:7], v[164:167], v[214:217], v[4:7]
	v_mfma_f32_16x16x32_bf16 v[0:3], v[172:175], v[214:217], v[0:3]
	s_barrier
	s_setprio 0
.LBB0_751:
	ds_read_b128 v[144:147], v189
	ds_read_b128 v[148:151], v189 offset:1024
	ds_read_b128 v[152:155], v189 offset:2048
	ds_read_b128 v[156:159], v189 offset:3072
	ds_read_b128 v[160:163], v190
	ds_read_b128 v[164:167], v190 offset:1024
	ds_read_b128 v[168:171], v190 offset:2048
	ds_read_b128 v[172:175], v190 offset:3072
	s_add_u32 s46, s44, 0x100
	s_addc_u32 s47, s45, 0
	s_cmp_eq_u32 s72, 12
	s_cselect_b32 s75, s43, s47
	s_cselect_b32 s74, s67, s46
	s_cselect_b32 s49, s37, s71
	s_cselect_b32 s48, s68, s69
	v_lshl_add_u64 v[184:185], s[44:45], 0, v[136:137]
	s_add_i32 m0, s51, 0xc000
	ds_read_b128 v[176:179], v191
	ds_read_b128 v[180:183], v191 offset:1024
	ds_read_b128 v[194:197], v191 offset:2048
	ds_read_b128 v[198:201], v191 offset:3072
	ds_read_b128 v[202:205], v191 offset:4096
	ds_read_b128 v[206:209], v191 offset:5120
	ds_read_b128 v[210:213], v191 offset:6144
	ds_read_b128 v[214:217], v191 offset:7168
	global_load_lds_dwordx4 v[184:185], off
	s_add_i32 m0, s51, 0xe000
	v_lshl_add_u64 v[184:185], s[44:45], 0, v[138:139]
	global_load_lds_dwordx4 v[184:185], off
	s_setprio 1
	s_waitcnt vmcnt(8) lgkmcnt(0)
	s_barrier
	v_mfma_f32_16x16x32_bf16 v[124:127], v[144:147], v[176:179], v[124:127]
	v_mfma_f32_16x16x32_bf16 v[120:123], v[152:155], v[176:179], v[120:123]
	v_mfma_f32_16x16x32_bf16 v[108:111], v[144:147], v[194:197], v[108:111]
	v_mfma_f32_16x16x32_bf16 v[104:107], v[152:155], v[194:197], v[104:107]
	v_mfma_f32_16x16x32_bf16 v[92:95], v[144:147], v[202:205], v[92:95]
	v_mfma_f32_16x16x32_bf16 v[88:91], v[152:155], v[202:205], v[88:91]
	v_mfma_f32_16x16x32_bf16 v[76:79], v[144:147], v[210:213], v[76:79]
	v_mfma_f32_16x16x32_bf16 v[72:75], v[152:155], v[210:213], v[72:75]
	v_mfma_f32_16x16x32_bf16 v[124:127], v[148:151], v[180:183], v[124:127]
	v_mfma_f32_16x16x32_bf16 v[120:123], v[156:159], v[180:183], v[120:123]
	v_mfma_f32_16x16x32_bf16 v[108:111], v[148:151], v[198:201], v[108:111]
	v_mfma_f32_16x16x32_bf16 v[104:107], v[156:159], v[198:201], v[104:107]
	v_mfma_f32_16x16x32_bf16 v[92:95], v[148:151], v[206:209], v[92:95]
	v_mfma_f32_16x16x32_bf16 v[88:91], v[156:159], v[206:209], v[88:91]
	v_mfma_f32_16x16x32_bf16 v[76:79], v[148:151], v[214:217], v[76:79]
	v_mfma_f32_16x16x32_bf16 v[72:75], v[156:159], v[214:217], v[72:75]
	v_mfma_f32_16x16x32_bf16 v[116:119], v[160:163], v[176:179], v[116:119]
	v_mfma_f32_16x16x32_bf16 v[112:115], v[168:171], v[176:179], v[112:115]
	v_mfma_f32_16x16x32_bf16 v[100:103], v[160:163], v[194:197], v[100:103]
	v_mfma_f32_16x16x32_bf16 v[96:99], v[168:171], v[194:197], v[96:99]
	v_mfma_f32_16x16x32_bf16 v[84:87], v[160:163], v[202:205], v[84:87]
	v_mfma_f32_16x16x32_bf16 v[80:83], v[168:171], v[202:205], v[80:83]
	v_mfma_f32_16x16x32_bf16 v[68:71], v[160:163], v[210:213], v[68:71]
	v_mfma_f32_16x16x32_bf16 v[64:67], v[168:171], v[210:213], v[64:67]
	v_mfma_f32_16x16x32_bf16 v[116:119], v[164:167], v[180:183], v[116:119]
	v_mfma_f32_16x16x32_bf16 v[112:115], v[172:175], v[180:183], v[112:115]
	v_mfma_f32_16x16x32_bf16 v[100:103], v[164:167], v[198:201], v[100:103]
	v_mfma_f32_16x16x32_bf16 v[96:99], v[172:175], v[198:201], v[96:99]
	v_mfma_f32_16x16x32_bf16 v[84:87], v[164:167], v[206:209], v[84:87]
	v_mfma_f32_16x16x32_bf16 v[80:83], v[172:175], v[206:209], v[80:83]
	v_mfma_f32_16x16x32_bf16 v[68:71], v[164:167], v[214:217], v[68:71]
	v_mfma_f32_16x16x32_bf16 v[64:67], v[172:175], v[214:217], v[64:67]
	s_barrier
	s_setprio 0
	s_add_i32 s44, s63, s50
	v_lshl_add_u64 v[184:185], s[48:49], 0, v[130:131]
	s_mov_b32 m0, s44
	ds_read_b128 v[176:179], v191 offset:16384
	ds_read_b128 v[180:183], v191 offset:17408
	ds_read_b128 v[194:197], v191 offset:18432
	ds_read_b128 v[198:201], v191 offset:19456
	ds_read_b128 v[202:205], v191 offset:20480
	ds_read_b128 v[206:209], v191 offset:21504
	ds_read_b128 v[210:213], v191 offset:22528
	ds_read_b128 v[214:217], v191 offset:23552
	global_load_lds_dwordx4 v[184:185], off
	s_add_i32 m0, s44, 0x2000
	s_add_u32 s44, s48, 0x40000
	v_lshl_add_u64 v[218:219], s[48:49], 0, v[134:135]
	s_addc_u32 s45, s49, 0
	s_add_i32 s70, s64, s50
	global_load_lds_dwordx4 v[218:219], off
	v_lshl_add_u64 v[220:221], s[44:45], 0, v[130:131]
	s_mov_b32 m0, s70
	v_lshl_add_u64 v[222:223], s[74:75], 0, v[132:133]
	global_load_lds_dwordx4 v[220:221], off
	v_lshl_add_u64 v[220:221], s[44:45], 0, v[134:135]
	s_add_i32 m0, s70, 0x2000
	v_lshl_add_u64 v[224:225], v[222:223], 0, s[12:13]
	global_load_lds_dwordx4 v[220:221], off
	s_mov_b32 m0, s51
	v_lshl_add_u64 v[220:221], s[74:75], 0, v[128:129]
	global_load_lds_dwordx4 v[220:221], off
	s_mov_b32 m0, s52
	s_nop 0
	global_load_lds_dwordx4 v[224:225], off
	s_setprio 1
	s_waitcnt vmcnt(8) lgkmcnt(0)
	s_barrier
	v_mfma_f32_16x16x32_bf16 v[60:63], v[144:147], v[176:179], v[60:63]
	v_mfma_f32_16x16x32_bf16 v[56:59], v[152:155], v[176:179], v[56:59]
	v_mfma_f32_16x16x32_bf16 v[44:47], v[144:147], v[194:197], v[44:47]
	v_mfma_f32_16x16x32_bf16 v[40:43], v[152:155], v[194:197], v[40:43]
	v_mfma_f32_16x16x32_bf16 v[28:31], v[144:147], v[202:205], v[28:31]
	v_mfma_f32_16x16x32_bf16 v[24:27], v[152:155], v[202:205], v[24:27]
	v_mfma_f32_16x16x32_bf16 v[12:15], v[144:147], v[210:213], v[12:15]
	v_mfma_f32_16x16x32_bf16 v[8:11], v[152:155], v[210:213], v[8:11]
	v_mfma_f32_16x16x32_bf16 v[60:63], v[148:151], v[180:183], v[60:63]
	v_mfma_f32_16x16x32_bf16 v[56:59], v[156:159], v[180:183], v[56:59]
	v_mfma_f32_16x16x32_bf16 v[44:47], v[148:151], v[198:201], v[44:47]
	v_mfma_f32_16x16x32_bf16 v[40:43], v[156:159], v[198:201], v[40:43]
	v_mfma_f32_16x16x32_bf16 v[28:31], v[148:151], v[206:209], v[28:31]
	v_mfma_f32_16x16x32_bf16 v[24:27], v[156:159], v[206:209], v[24:27]
	v_mfma_f32_16x16x32_bf16 v[12:15], v[148:151], v[214:217], v[12:15]
	v_mfma_f32_16x16x32_bf16 v[8:11], v[156:159], v[214:217], v[8:11]
	v_mfma_f32_16x16x32_bf16 v[52:55], v[160:163], v[176:179], v[52:55]
	v_mfma_f32_16x16x32_bf16 v[48:51], v[168:171], v[176:179], v[48:51]
	v_mfma_f32_16x16x32_bf16 v[36:39], v[160:163], v[194:197], v[36:39]
	v_mfma_f32_16x16x32_bf16 v[32:35], v[168:171], v[194:197], v[32:35]
	v_mfma_f32_16x16x32_bf16 v[20:23], v[160:163], v[202:205], v[20:23]
	v_mfma_f32_16x16x32_bf16 v[16:19], v[168:171], v[202:205], v[16:19]
	v_mfma_f32_16x16x32_bf16 v[4:7], v[160:163], v[210:213], v[4:7]
	v_mfma_f32_16x16x32_bf16 v[0:3], v[168:171], v[210:213], v[0:3]
	v_mfma_f32_16x16x32_bf16 v[52:55], v[164:167], v[180:183], v[52:55]
	v_mfma_f32_16x16x32_bf16 v[48:51], v[172:175], v[180:183], v[48:51]
	v_mfma_f32_16x16x32_bf16 v[36:39], v[164:167], v[198:201], v[36:39]
	v_mfma_f32_16x16x32_bf16 v[32:35], v[172:175], v[198:201], v[32:35]
	v_mfma_f32_16x16x32_bf16 v[20:23], v[164:167], v[206:209], v[20:23]
	v_mfma_f32_16x16x32_bf16 v[16:19], v[172:175], v[206:209], v[16:19]
	v_mfma_f32_16x16x32_bf16 v[4:7], v[164:167], v[214:217], v[4:7]
	v_mfma_f32_16x16x32_bf16 v[0:3], v[172:175], v[214:217], v[0:3]
	s_barrier
	s_setprio 0
	s_add_i32 s44, 0, 0x18000
	s_add_i32 s70, 0, 0x1c000
	v_add_u32_e32 v156, s44, v187
	v_add_u32_e32 v172, s70, v187
	ds_read_b128 v[144:147], v156
	ds_read_b128 v[148:151], v156 offset:1024
	ds_read_b128 v[152:155], v156 offset:2048
	ds_read_b128 v[156:159], v156 offset:3072
	ds_read_b128 v[160:163], v172
	ds_read_b128 v[164:167], v172 offset:1024
	ds_read_b128 v[168:171], v172 offset:2048
	ds_read_b128 v[172:175], v172 offset:3072
	s_mov_b32 m0, s53
	v_lshl_add_u64 v[224:225], v[220:221], 0, s[10:11]
	ds_read_b128 v[176:179], v191 offset:32768
	ds_read_b128 v[180:183], v191 offset:33792
	ds_read_b128 v[194:197], v191 offset:34816
	ds_read_b128 v[198:201], v191 offset:35840
	ds_read_b128 v[202:205], v191 offset:36864
	ds_read_b128 v[206:209], v191 offset:37888
	ds_read_b128 v[210:213], v191 offset:38912
	ds_read_b128 v[214:217], v191 offset:39936
	global_load_lds_dwordx4 v[224:225], off
	s_mov_b32 m0, s54
	v_lshl_add_u64 v[224:225], v[222:223], 0, s[14:15]
	global_load_lds_dwordx4 v[224:225], off
	s_setprio 1
	s_waitcnt vmcnt(8) lgkmcnt(0)
	s_barrier
	v_mfma_f32_16x16x32_bf16 v[124:127], v[144:147], v[176:179], v[124:127]
	v_mfma_f32_16x16x32_bf16 v[120:123], v[152:155], v[176:179], v[120:123]
	v_mfma_f32_16x16x32_bf16 v[108:111], v[144:147], v[194:197], v[108:111]
	v_mfma_f32_16x16x32_bf16 v[104:107], v[152:155], v[194:197], v[104:107]
	v_mfma_f32_16x16x32_bf16 v[92:95], v[144:147], v[202:205], v[92:95]
	v_mfma_f32_16x16x32_bf16 v[88:91], v[152:155], v[202:205], v[88:91]
	v_mfma_f32_16x16x32_bf16 v[76:79], v[144:147], v[210:213], v[76:79]
	v_mfma_f32_16x16x32_bf16 v[72:75], v[152:155], v[210:213], v[72:75]
	v_mfma_f32_16x16x32_bf16 v[124:127], v[148:151], v[180:183], v[124:127]
	v_mfma_f32_16x16x32_bf16 v[120:123], v[156:159], v[180:183], v[120:123]
	v_mfma_f32_16x16x32_bf16 v[108:111], v[148:151], v[198:201], v[108:111]
	v_mfma_f32_16x16x32_bf16 v[104:107], v[156:159], v[198:201], v[104:107]
	v_mfma_f32_16x16x32_bf16 v[92:95], v[148:151], v[206:209], v[92:95]
	v_mfma_f32_16x16x32_bf16 v[88:91], v[156:159], v[206:209], v[88:91]
	v_mfma_f32_16x16x32_bf16 v[76:79], v[148:151], v[214:217], v[76:79]
	v_mfma_f32_16x16x32_bf16 v[72:75], v[156:159], v[214:217], v[72:75]
	v_mfma_f32_16x16x32_bf16 v[116:119], v[160:163], v[176:179], v[116:119]
	v_mfma_f32_16x16x32_bf16 v[112:115], v[168:171], v[176:179], v[112:115]
	v_mfma_f32_16x16x32_bf16 v[100:103], v[160:163], v[194:197], v[100:103]
	v_mfma_f32_16x16x32_bf16 v[96:99], v[168:171], v[194:197], v[96:99]
	v_mfma_f32_16x16x32_bf16 v[84:87], v[160:163], v[202:205], v[84:87]
	v_mfma_f32_16x16x32_bf16 v[80:83], v[168:171], v[202:205], v[80:83]
	v_mfma_f32_16x16x32_bf16 v[68:71], v[160:163], v[210:213], v[68:71]
	v_mfma_f32_16x16x32_bf16 v[64:67], v[168:171], v[210:213], v[64:67]
	v_mfma_f32_16x16x32_bf16 v[116:119], v[164:167], v[180:183], v[116:119]
	v_mfma_f32_16x16x32_bf16 v[112:115], v[172:175], v[180:183], v[112:115]
	v_mfma_f32_16x16x32_bf16 v[100:103], v[164:167], v[198:201], v[100:103]
	v_mfma_f32_16x16x32_bf16 v[96:99], v[172:175], v[198:201], v[96:99]
	v_mfma_f32_16x16x32_bf16 v[84:87], v[164:167], v[206:209], v[84:87]
	v_mfma_f32_16x16x32_bf16 v[80:83], v[172:175], v[206:209], v[80:83]
	v_mfma_f32_16x16x32_bf16 v[68:71], v[164:167], v[214:217], v[68:71]
	v_mfma_f32_16x16x32_bf16 v[64:67], v[172:175], v[214:217], v[64:67]
	s_barrier
	s_setprio 0
	s_add_i32 s44, s44, s50
	v_lshl_add_u64 v[184:185], v[184:185], 0, s[24:25]
	s_mov_b32 m0, s44
	ds_read_b128 v[176:179], v191 offset:49152
	ds_read_b128 v[180:183], v191 offset:50176
	ds_read_b128 v[194:197], v191 offset:51200
	ds_read_b128 v[198:201], v191 offset:52224
	ds_read_b128 v[202:205], v191 offset:53248
	ds_read_b128 v[206:209], v191 offset:54272
	ds_read_b128 v[210:213], v191 offset:55296
	ds_read_b128 v[214:217], v191 offset:56320
	global_load_lds_dwordx4 v[184:185], off
	s_add_i32 m0, s44, 0x2000
	s_add_u32 s44, s48, 0x40080
	v_lshl_add_u64 v[184:185], v[218:219], 0, s[24:25]
	s_addc_u32 s45, s49, 0
	s_add_i32 s48, s70, s50
	global_load_lds_dwordx4 v[184:185], off
	s_mov_b32 m0, s48
	v_lshl_add_u64 v[184:185], s[44:45], 0, v[130:131]
	global_load_lds_dwordx4 v[184:185], off
	s_add_i32 m0, s48, 0x2000
	v_lshl_add_u64 v[184:185], s[44:45], 0, v[134:135]
	global_load_lds_dwordx4 v[184:185], off
	s_mov_b32 m0, s58
	v_lshl_add_u64 v[184:185], v[220:221], 0, s[24:25]
	global_load_lds_dwordx4 v[184:185], off
	s_mov_b32 m0, s59
	v_lshl_add_u64 v[184:185], v[222:223], 0, s[30:31]
	global_load_lds_dwordx4 v[184:185], off
	s_add_i32 s72, s72, 2
	s_add_u32 s69, s69, 0x100
	s_addc_u32 s71, s71, 0
	s_cmp_gt_u32 s72, 13
	s_mov_b64 s[44:45], s[46:47]
	s_setprio 1
	s_waitcnt vmcnt(8) lgkmcnt(0)
	s_barrier
	v_mfma_f32_16x16x32_bf16 v[60:63], v[144:147], v[176:179], v[60:63]
	v_mfma_f32_16x16x32_bf16 v[56:59], v[152:155], v[176:179], v[56:59]
	v_mfma_f32_16x16x32_bf16 v[44:47], v[144:147], v[194:197], v[44:47]
	v_mfma_f32_16x16x32_bf16 v[40:43], v[152:155], v[194:197], v[40:43]
	v_mfma_f32_16x16x32_bf16 v[28:31], v[144:147], v[202:205], v[28:31]
	v_mfma_f32_16x16x32_bf16 v[24:27], v[152:155], v[202:205], v[24:27]
	v_mfma_f32_16x16x32_bf16 v[12:15], v[144:147], v[210:213], v[12:15]
	v_mfma_f32_16x16x32_bf16 v[8:11], v[152:155], v[210:213], v[8:11]
	v_mfma_f32_16x16x32_bf16 v[60:63], v[148:151], v[180:183], v[60:63]
	v_mfma_f32_16x16x32_bf16 v[56:59], v[156:159], v[180:183], v[56:59]
	v_mfma_f32_16x16x32_bf16 v[44:47], v[148:151], v[198:201], v[44:47]
	v_mfma_f32_16x16x32_bf16 v[40:43], v[156:159], v[198:201], v[40:43]
	v_mfma_f32_16x16x32_bf16 v[28:31], v[148:151], v[206:209], v[28:31]
	v_mfma_f32_16x16x32_bf16 v[24:27], v[156:159], v[206:209], v[24:27]
	v_mfma_f32_16x16x32_bf16 v[12:15], v[148:151], v[214:217], v[12:15]
	v_mfma_f32_16x16x32_bf16 v[8:11], v[156:159], v[214:217], v[8:11]
	v_mfma_f32_16x16x32_bf16 v[52:55], v[160:163], v[176:179], v[52:55]
	v_mfma_f32_16x16x32_bf16 v[48:51], v[168:171], v[176:179], v[48:51]
	v_mfma_f32_16x16x32_bf16 v[36:39], v[160:163], v[194:197], v[36:39]
	v_mfma_f32_16x16x32_bf16 v[32:35], v[168:171], v[194:197], v[32:35]
	v_mfma_f32_16x16x32_bf16 v[20:23], v[160:163], v[202:205], v[20:23]
	v_mfma_f32_16x16x32_bf16 v[16:19], v[168:171], v[202:205], v[16:19]
	v_mfma_f32_16x16x32_bf16 v[4:7], v[160:163], v[210:213], v[4:7]
	v_mfma_f32_16x16x32_bf16 v[0:3], v[168:171], v[210:213], v[0:3]
	v_mfma_f32_16x16x32_bf16 v[52:55], v[164:167], v[180:183], v[52:55]
	v_mfma_f32_16x16x32_bf16 v[48:51], v[172:175], v[180:183], v[48:51]
	v_mfma_f32_16x16x32_bf16 v[36:39], v[164:167], v[198:201], v[36:39]
	v_mfma_f32_16x16x32_bf16 v[32:35], v[172:175], v[198:201], v[32:35]
	v_mfma_f32_16x16x32_bf16 v[20:23], v[164:167], v[206:209], v[20:23]
	v_mfma_f32_16x16x32_bf16 v[16:19], v[172:175], v[206:209], v[16:19]
	v_mfma_f32_16x16x32_bf16 v[4:7], v[164:167], v[214:217], v[4:7]
	v_mfma_f32_16x16x32_bf16 v[0:3], v[172:175], v[214:217], v[0:3]
	s_barrier
	s_setprio 0
	s_cbranch_scc0 .LBB0_751
	s_and_b64 vcc, exec, s[34:35]
	s_cbranch_vccz .LBB0_754
	s_barrier
